# B-fragment-ordered k-step pairing plus setprio 0/1 toggles every 4 MFMAs
# speedup vs baseline: 1.0080x; 1.0080x over previous
.LBB0_257:
	s_or_b64 exec, exec, s[50:51]
	s_add_u32 s0, s12, s6
	ds_read_b128 v[146:149], v137
	ds_read_b128 v[150:153], v137 offset:1024
	ds_read_b128 v[154:157], v137 offset:2048
	ds_read_b128 v[158:161], v137 offset:3072
	ds_read_b128 v[162:165], v138
	ds_read_b128 v[166:169], v138 offset:1024
	ds_read_b128 v[170:173], v138 offset:2048
	ds_read_b128 v[174:177], v138 offset:3072
	s_addc_u32 s1, s13, s7
	s_add_u32 s50, s0, 0x20000
	s_addc_u32 s51, s1, 0
	s_add_u32 s52, s93, s6
	s_addc_u32 s53, s94, s7
	s_cmp_eq_u32 s6, 0x60000
	s_cselect_b32 s62, s95, s50
	s_cselect_b32 s63, s31, s51
	s_cselect_b32 s51, s29, s53
	s_cselect_b32 s50, s96, s52
	s_add_u32 s52, s62, 0x8000
	s_addc_u32 s53, s63, 0
	s_add_u32 s54, s50, 0x8000
	s_addc_u32 s55, s51, 0
	ds_read_b128 v[178:181], v139
	ds_read_b128 v[182:185], v139 offset:1024
	ds_read_b128 v[186:189], v139 offset:2048
	ds_read_b128 v[190:193], v139 offset:3072
	ds_read_b128 v[198:201], v139 offset:4096
	ds_read_b128 v[202:205], v139 offset:5120
	ds_read_b128 v[206:209], v139 offset:6144
	ds_read_b128 v[212:215], v139 offset:7168
	s_add_u32 s0, s0, 0x1c000
	s_addc_u32 s1, s1, 0
	s_mov_b32 m0, s78
	s_nop 0
	global_load_lds_dwordx4 v134, s[0:1]
	s_add_u32 m0, s78, 0x2000
	s_nop 0
	global_load_lds_dwordx4 v135, s[0:1]
	s_waitcnt vmcnt(8)
	s_waitcnt lgkmcnt(0)
	s_setprio 1
	s_barrier
	v_mfma_f32_16x16x32_bf16 v[122:125], v[146:149], v[178:181], v[122:125]
	v_mfma_f32_16x16x32_bf16 v[122:125], v[150:153], v[182:185], v[122:125]
	s_waitcnt lgkmcnt(5)
	v_mfma_f32_16x16x32_bf16 v[106:109], v[146:149], v[186:189], v[106:109]
	v_mfma_f32_16x16x32_bf16 v[106:109], v[150:153], v[190:193], v[106:109]
	s_waitcnt lgkmcnt(3)
	s_setprio 0
	s_setprio 1
	v_mfma_f32_16x16x32_bf16 v[90:93], v[146:149], v[198:201], v[90:93]
	v_mfma_f32_16x16x32_bf16 v[90:93], v[150:153], v[202:205], v[90:93]
	s_waitcnt lgkmcnt(1)
	v_mfma_f32_16x16x32_bf16 v[74:77], v[146:149], v[206:209], v[74:77]
	v_mfma_f32_16x16x32_bf16 v[74:77], v[150:153], v[212:215], v[74:77]
	s_setprio 0
	s_setprio 1
	v_mfma_f32_16x16x32_bf16 v[114:117], v[154:157], v[178:181], v[114:117]
	v_mfma_f32_16x16x32_bf16 v[114:117], v[158:161], v[182:185], v[114:117]
	v_mfma_f32_16x16x32_bf16 v[98:101], v[154:157], v[186:189], v[98:101]
	v_mfma_f32_16x16x32_bf16 v[98:101], v[158:161], v[190:193], v[98:101]
	s_setprio 0
	s_setprio 1
	v_mfma_f32_16x16x32_bf16 v[82:85], v[154:157], v[198:201], v[82:85]
	v_mfma_f32_16x16x32_bf16 v[82:85], v[158:161], v[202:205], v[82:85]
	s_waitcnt lgkmcnt(0)
	v_mfma_f32_16x16x32_bf16 v[66:69], v[154:157], v[206:209], v[66:69]
	v_mfma_f32_16x16x32_bf16 v[66:69], v[158:161], v[212:215], v[66:69]
	s_setprio 0
	s_setprio 1
	v_mfma_f32_16x16x32_bf16 v[126:129], v[162:165], v[178:181], v[126:129]
	v_mfma_f32_16x16x32_bf16 v[126:129], v[166:169], v[182:185], v[126:129]
	v_mfma_f32_16x16x32_bf16 v[110:113], v[162:165], v[186:189], v[110:113]
	v_mfma_f32_16x16x32_bf16 v[110:113], v[166:169], v[190:193], v[110:113]
	s_setprio 0
	s_setprio 1
	v_mfma_f32_16x16x32_bf16 v[94:97], v[162:165], v[198:201], v[94:97]
	v_mfma_f32_16x16x32_bf16 v[94:97], v[166:169], v[202:205], v[94:97]
	v_mfma_f32_16x16x32_bf16 v[78:81], v[162:165], v[206:209], v[78:81]
	v_mfma_f32_16x16x32_bf16 v[78:81], v[166:169], v[212:215], v[78:81]
	s_setprio 0
	s_setprio 1
	v_mfma_f32_16x16x32_bf16 v[118:121], v[170:173], v[178:181], v[118:121]
	v_mfma_f32_16x16x32_bf16 v[118:121], v[174:177], v[182:185], v[118:121]
	v_mfma_f32_16x16x32_bf16 v[102:105], v[170:173], v[186:189], v[102:105]
	v_mfma_f32_16x16x32_bf16 v[102:105], v[174:177], v[190:193], v[102:105]
	s_setprio 0
	s_setprio 1
	v_mfma_f32_16x16x32_bf16 v[86:89], v[170:173], v[198:201], v[86:89]
	v_mfma_f32_16x16x32_bf16 v[86:89], v[174:177], v[202:205], v[86:89]
	s_setprio 2
	s_barrier
	v_mfma_f32_16x16x32_bf16 v[70:73], v[170:173], v[206:209], v[70:73]
	v_mfma_f32_16x16x32_bf16 v[70:73], v[174:177], v[212:215], v[70:73]
	s_setprio 0
	s_nop 0
	ds_read_b128 v[178:181], v139 offset:16384
	ds_read_b128 v[182:185], v139 offset:17408
	ds_read_b128 v[186:189], v139 offset:18432
	ds_read_b128 v[190:193], v139 offset:19456
	ds_read_b128 v[198:201], v139 offset:20480
	ds_read_b128 v[202:205], v139 offset:21504
	ds_read_b128 v[206:209], v139 offset:22528
	ds_read_b128 v[212:215], v139 offset:23552
	s_mov_b32 m0, s11
	s_nop 0
	global_load_lds_dwordx4 v134, s[50:51]
	s_add_u32 m0, s11, 0x2000
	s_nop 0
	global_load_lds_dwordx4 v135, s[50:51]
	s_add_u32 s0, s50, 0x4000
	s_addc_u32 s1, s51, 0
	s_mov_b32 m0, s68
	s_nop 0
	global_load_lds_dwordx4 v134, s[0:1]
	s_add_u32 m0, s68, 0x2000
	s_nop 0
	global_load_lds_dwordx4 v135, s[0:1]
	s_nop 0
	s_mov_b32 m0, s65
	s_nop 0
	global_load_lds_dwordx4 v134, s[62:63]
	s_add_u32 m0, s65, 0x2000
	s_nop 0
	global_load_lds_dwordx4 v135, s[62:63]
	s_waitcnt vmcnt(8)
	s_waitcnt lgkmcnt(0)
	s_setprio 1
	s_barrier
	v_mfma_f32_16x16x32_bf16 v[58:61], v[146:149], v[178:181], v[58:61]
	v_mfma_f32_16x16x32_bf16 v[58:61], v[150:153], v[182:185], v[58:61]
	s_waitcnt lgkmcnt(5)
	v_mfma_f32_16x16x32_bf16 v[42:45], v[146:149], v[186:189], v[42:45]
	v_mfma_f32_16x16x32_bf16 v[42:45], v[150:153], v[190:193], v[42:45]
	s_waitcnt lgkmcnt(3)
	s_setprio 0
	s_setprio 1
	v_mfma_f32_16x16x32_bf16 v[26:29], v[146:149], v[198:201], v[26:29]
	v_mfma_f32_16x16x32_bf16 v[26:29], v[150:153], v[202:205], v[26:29]
	s_waitcnt lgkmcnt(1)
	v_mfma_f32_16x16x32_bf16 v[10:13], v[146:149], v[206:209], v[10:13]
	v_mfma_f32_16x16x32_bf16 v[10:13], v[150:153], v[212:215], v[10:13]
	s_setprio 0
	s_setprio 1
	v_mfma_f32_16x16x32_bf16 v[50:53], v[154:157], v[178:181], v[50:53]
	v_mfma_f32_16x16x32_bf16 v[50:53], v[158:161], v[182:185], v[50:53]
	v_mfma_f32_16x16x32_bf16 v[34:37], v[154:157], v[186:189], v[34:37]
	v_mfma_f32_16x16x32_bf16 v[34:37], v[158:161], v[190:193], v[34:37]
	s_setprio 0
	s_setprio 1
	v_mfma_f32_16x16x32_bf16 v[18:21], v[154:157], v[198:201], v[18:21]
	v_mfma_f32_16x16x32_bf16 v[18:21], v[158:161], v[202:205], v[18:21]
	s_waitcnt lgkmcnt(0)
	v_mfma_f32_16x16x32_bf16 v[2:5], v[154:157], v[206:209], v[2:5]
	v_mfma_f32_16x16x32_bf16 v[2:5], v[158:161], v[212:215], v[2:5]
	s_setprio 0
	s_setprio 1
	v_mfma_f32_16x16x32_bf16 v[62:65], v[162:165], v[178:181], v[62:65]
	v_mfma_f32_16x16x32_bf16 v[62:65], v[166:169], v[182:185], v[62:65]
	v_mfma_f32_16x16x32_bf16 v[46:49], v[162:165], v[186:189], v[46:49]
	v_mfma_f32_16x16x32_bf16 v[46:49], v[166:169], v[190:193], v[46:49]
	s_setprio 0
	s_setprio 1
	v_mfma_f32_16x16x32_bf16 v[30:33], v[162:165], v[198:201], v[30:33]
	v_mfma_f32_16x16x32_bf16 v[30:33], v[166:169], v[202:205], v[30:33]
	v_mfma_f32_16x16x32_bf16 v[14:17], v[162:165], v[206:209], v[14:17]
	v_mfma_f32_16x16x32_bf16 v[14:17], v[166:169], v[212:215], v[14:17]
	s_setprio 0
	s_setprio 1
	v_mfma_f32_16x16x32_bf16 v[54:57], v[170:173], v[178:181], v[54:57]
	v_mfma_f32_16x16x32_bf16 v[54:57], v[174:177], v[182:185], v[54:57]
	v_mfma_f32_16x16x32_bf16 v[38:41], v[170:173], v[186:189], v[38:41]
	v_mfma_f32_16x16x32_bf16 v[38:41], v[174:177], v[190:193], v[38:41]
	s_setprio 0
	s_setprio 1
	v_mfma_f32_16x16x32_bf16 v[22:25], v[170:173], v[198:201], v[22:25]
	v_mfma_f32_16x16x32_bf16 v[22:25], v[174:177], v[202:205], v[22:25]
	s_setprio 2
	s_barrier
	v_mfma_f32_16x16x32_bf16 v[6:9], v[170:173], v[206:209], v[6:9]
	v_mfma_f32_16x16x32_bf16 v[6:9], v[174:177], v[212:215], v[6:9]
	s_setprio 0
	s_nop 0
	ds_read_b128 v[146:149], v140
	ds_read_b128 v[150:153], v140 offset:1024
	ds_read_b128 v[154:157], v140 offset:2048
	ds_read_b128 v[158:161], v140 offset:3072
	ds_read_b128 v[162:165], v141
	ds_read_b128 v[166:169], v141 offset:1024
	ds_read_b128 v[170:173], v141 offset:2048
	ds_read_b128 v[174:177], v141 offset:3072
	ds_read_b128 v[178:181], v139 offset:32768
	ds_read_b128 v[182:185], v139 offset:33792
	ds_read_b128 v[186:189], v139 offset:34816
	ds_read_b128 v[190:193], v139 offset:35840
	ds_read_b128 v[198:201], v139 offset:36864
	ds_read_b128 v[202:205], v139 offset:37888
	ds_read_b128 v[206:209], v139 offset:38912
	ds_read_b128 v[212:215], v139 offset:39936
	s_add_u32 s0, s62, 0x4000
	s_addc_u32 s1, s63, 0
	s_mov_b32 m0, s69
	s_nop 0
	global_load_lds_dwordx4 v134, s[0:1]
	s_add_u32 m0, s69, 0x2000
	s_nop 0
	global_load_lds_dwordx4 v135, s[0:1]
	s_waitcnt vmcnt(8)
	s_waitcnt lgkmcnt(0)
	s_setprio 1
	s_barrier
	v_mfma_f32_16x16x32_bf16 v[122:125], v[146:149], v[178:181], v[122:125]
	v_mfma_f32_16x16x32_bf16 v[122:125], v[150:153], v[182:185], v[122:125]
	s_waitcnt lgkmcnt(5)
	v_mfma_f32_16x16x32_bf16 v[106:109], v[146:149], v[186:189], v[106:109]
	v_mfma_f32_16x16x32_bf16 v[106:109], v[150:153], v[190:193], v[106:109]
	s_waitcnt lgkmcnt(3)
	s_setprio 0
	s_setprio 1
	v_mfma_f32_16x16x32_bf16 v[90:93], v[146:149], v[198:201], v[90:93]
	v_mfma_f32_16x16x32_bf16 v[90:93], v[150:153], v[202:205], v[90:93]
	s_waitcnt lgkmcnt(1)
	v_mfma_f32_16x16x32_bf16 v[74:77], v[146:149], v[206:209], v[74:77]
	v_mfma_f32_16x16x32_bf16 v[74:77], v[150:153], v[212:215], v[74:77]
	s_setprio 0
	s_setprio 1
	v_mfma_f32_16x16x32_bf16 v[114:117], v[154:157], v[178:181], v[114:117]
	v_mfma_f32_16x16x32_bf16 v[114:117], v[158:161], v[182:185], v[114:117]
	v_mfma_f32_16x16x32_bf16 v[98:101], v[154:157], v[186:189], v[98:101]
	v_mfma_f32_16x16x32_bf16 v[98:101], v[158:161], v[190:193], v[98:101]
	s_setprio 0
	s_setprio 1
	v_mfma_f32_16x16x32_bf16 v[82:85], v[154:157], v[198:201], v[82:85]
	v_mfma_f32_16x16x32_bf16 v[82:85], v[158:161], v[202:205], v[82:85]
	s_waitcnt lgkmcnt(0)
	v_mfma_f32_16x16x32_bf16 v[66:69], v[154:157], v[206:209], v[66:69]
	v_mfma_f32_16x16x32_bf16 v[66:69], v[158:161], v[212:215], v[66:69]
	s_setprio 0
	s_setprio 1
	v_mfma_f32_16x16x32_bf16 v[126:129], v[162:165], v[178:181], v[126:129]
	v_mfma_f32_16x16x32_bf16 v[126:129], v[166:169], v[182:185], v[126:129]
	v_mfma_f32_16x16x32_bf16 v[110:113], v[162:165], v[186:189], v[110:113]
	v_mfma_f32_16x16x32_bf16 v[110:113], v[166:169], v[190:193], v[110:113]
	s_setprio 0
	s_setprio 1
	v_mfma_f32_16x16x32_bf16 v[94:97], v[162:165], v[198:201], v[94:97]
	v_mfma_f32_16x16x32_bf16 v[94:97], v[166:169], v[202:205], v[94:97]
	v_mfma_f32_16x16x32_bf16 v[78:81], v[162:165], v[206:209], v[78:81]
	v_mfma_f32_16x16x32_bf16 v[78:81], v[166:169], v[212:215], v[78:81]
	s_setprio 0
	s_setprio 1
	v_mfma_f32_16x16x32_bf16 v[118:121], v[170:173], v[178:181], v[118:121]
	v_mfma_f32_16x16x32_bf16 v[118:121], v[174:177], v[182:185], v[118:121]
	v_mfma_f32_16x16x32_bf16 v[102:105], v[170:173], v[186:189], v[102:105]
	v_mfma_f32_16x16x32_bf16 v[102:105], v[174:177], v[190:193], v[102:105]
	s_setprio 0
	s_setprio 1
	v_mfma_f32_16x16x32_bf16 v[86:89], v[170:173], v[198:201], v[86:89]
	v_mfma_f32_16x16x32_bf16 v[86:89], v[174:177], v[202:205], v[86:89]
	s_setprio 2
	s_barrier
	v_mfma_f32_16x16x32_bf16 v[70:73], v[170:173], v[206:209], v[70:73]
	v_mfma_f32_16x16x32_bf16 v[70:73], v[174:177], v[212:215], v[70:73]
	s_setprio 0
	s_nop 0
	ds_read_b128 v[178:181], v139 offset:49152
	ds_read_b128 v[182:185], v139 offset:50176
	ds_read_b128 v[186:189], v139 offset:51200
	ds_read_b128 v[190:193], v139 offset:52224
	ds_read_b128 v[198:201], v139 offset:53248
	ds_read_b128 v[202:205], v139 offset:54272
	ds_read_b128 v[206:209], v139 offset:55296
	ds_read_b128 v[212:215], v139 offset:56320
	s_mov_b32 m0, s74
	s_nop 0
	global_load_lds_dwordx4 v134, s[54:55]
	s_add_u32 m0, s74, 0x2000
	s_nop 0
	global_load_lds_dwordx4 v135, s[54:55]
	s_add_u32 s0, s50, 0xc000
	s_addc_u32 s1, s51, 0
	s_mov_b32 m0, s77
	s_nop 0
	global_load_lds_dwordx4 v134, s[0:1]
	s_add_u32 m0, s77, 0x2000
	s_nop 0
	global_load_lds_dwordx4 v135, s[0:1]
	s_nop 0
	s_mov_b32 m0, s76
	s_nop 0
	global_load_lds_dwordx4 v134, s[52:53]
	s_add_u32 m0, s76, 0x2000
	s_nop 0
	global_load_lds_dwordx4 v135, s[52:53]
	s_waitcnt vmcnt(8)
	s_waitcnt lgkmcnt(0)
	s_setprio 1
	s_barrier
	v_mfma_f32_16x16x32_bf16 v[58:61], v[146:149], v[178:181], v[58:61]
	v_mfma_f32_16x16x32_bf16 v[58:61], v[150:153], v[182:185], v[58:61]
	s_waitcnt lgkmcnt(5)
	v_mfma_f32_16x16x32_bf16 v[42:45], v[146:149], v[186:189], v[42:45]
	v_mfma_f32_16x16x32_bf16 v[42:45], v[150:153], v[190:193], v[42:45]
	s_waitcnt lgkmcnt(3)
	s_setprio 0
	s_setprio 1
	v_mfma_f32_16x16x32_bf16 v[26:29], v[146:149], v[198:201], v[26:29]
	v_mfma_f32_16x16x32_bf16 v[26:29], v[150:153], v[202:205], v[26:29]
	s_waitcnt lgkmcnt(1)
	v_mfma_f32_16x16x32_bf16 v[10:13], v[146:149], v[206:209], v[10:13]
	v_mfma_f32_16x16x32_bf16 v[10:13], v[150:153], v[212:215], v[10:13]
	s_setprio 0
	s_setprio 1
	v_mfma_f32_16x16x32_bf16 v[50:53], v[154:157], v[178:181], v[50:53]
	v_mfma_f32_16x16x32_bf16 v[50:53], v[158:161], v[182:185], v[50:53]
	v_mfma_f32_16x16x32_bf16 v[34:37], v[154:157], v[186:189], v[34:37]
	v_mfma_f32_16x16x32_bf16 v[34:37], v[158:161], v[190:193], v[34:37]
	s_setprio 0
	s_setprio 1
	v_mfma_f32_16x16x32_bf16 v[18:21], v[154:157], v[198:201], v[18:21]
	v_mfma_f32_16x16x32_bf16 v[18:21], v[158:161], v[202:205], v[18:21]
	s_waitcnt lgkmcnt(0)
	v_mfma_f32_16x16x32_bf16 v[2:5], v[154:157], v[206:209], v[2:5]
	v_mfma_f32_16x16x32_bf16 v[2:5], v[158:161], v[212:215], v[2:5]
	s_setprio 0
	s_setprio 1
	v_mfma_f32_16x16x32_bf16 v[62:65], v[162:165], v[178:181], v[62:65]
	v_mfma_f32_16x16x32_bf16 v[62:65], v[166:169], v[182:185], v[62:65]
	v_mfma_f32_16x16x32_bf16 v[46:49], v[162:165], v[186:189], v[46:49]
	v_mfma_f32_16x16x32_bf16 v[46:49], v[166:169], v[190:193], v[46:49]
	s_setprio 0
	s_setprio 1
	v_mfma_f32_16x16x32_bf16 v[30:33], v[162:165], v[198:201], v[30:33]
	v_mfma_f32_16x16x32_bf16 v[30:33], v[166:169], v[202:205], v[30:33]
	v_mfma_f32_16x16x32_bf16 v[14:17], v[162:165], v[206:209], v[14:17]
	v_mfma_f32_16x16x32_bf16 v[14:17], v[166:169], v[212:215], v[14:17]
	s_setprio 0
	s_setprio 1
	v_mfma_f32_16x16x32_bf16 v[54:57], v[170:173], v[178:181], v[54:57]
	v_mfma_f32_16x16x32_bf16 v[54:57], v[174:177], v[182:185], v[54:57]
	v_mfma_f32_16x16x32_bf16 v[38:41], v[170:173], v[186:189], v[38:41]
	v_mfma_f32_16x16x32_bf16 v[38:41], v[174:177], v[190:193], v[38:41]
	s_setprio 0
	s_setprio 1
	v_mfma_f32_16x16x32_bf16 v[22:25], v[170:173], v[198:201], v[22:25]
	v_mfma_f32_16x16x32_bf16 v[22:25], v[174:177], v[202:205], v[22:25]
	s_setprio 2
	s_barrier
	v_mfma_f32_16x16x32_bf16 v[6:9], v[170:173], v[206:209], v[6:9]
	v_mfma_f32_16x16x32_bf16 v[6:9], v[174:177], v[212:215], v[6:9]
	s_setprio 0
	s_nop 0
	s_add_i32 s97, s97, 2
	s_add_u32 s6, s6, 0x10000
	s_addc_u32 s7, s7, 0
	s_cmp_gt_u32 s97, 13
	s_cbranch_scc1 .LBB0_259
	v_mov_b32_e32 v145, v130
	s_branch .LBB0_255

.LBB0_364:
	s_add_i32 s26, s93, 2
	s_lshl_b64 s[62:63], s[26:27], 15
	s_add_u32 s64, s18, s62
	s_addc_u32 s65, s19, s63
	s_and_b64 s[52:53], s[50:51], exec
	s_cselect_b32 s53, s65, s39
	s_cselect_b32 s52, s64, s38
	s_add_u32 s62, s20, s62
	s_waitcnt vmcnt(8)
	s_addc_u32 s63, s21, s63
	s_waitcnt lgkmcnt(0)
	s_and_b64 s[50:51], s[50:51], exec
	s_cselect_b32 s51, s63, s49
	s_cselect_b32 s50, s62, s48
	s_setprio 1
	s_barrier
	v_mfma_f32_16x16x32_bf16 v[126:129], v[146:149], v[186:189], v[126:129]
	v_mfma_f32_16x16x32_bf16 v[126:129], v[150:153], v[190:193], v[126:129]
	s_waitcnt lgkmcnt(5)
	v_mfma_f32_16x16x32_bf16 v[118:121], v[146:149], v[178:181], v[118:121]
	v_mfma_f32_16x16x32_bf16 v[118:121], v[150:153], v[182:185], v[118:121]
	s_waitcnt lgkmcnt(3)
	s_setprio 0
	s_setprio 1
	v_mfma_f32_16x16x32_bf16 v[110:113], v[146:149], v[170:173], v[110:113]
	v_mfma_f32_16x16x32_bf16 v[110:113], v[150:153], v[174:177], v[110:113]
	s_waitcnt lgkmcnt(1)
	v_mfma_f32_16x16x32_bf16 v[102:105], v[146:149], v[162:165], v[102:105]
	v_mfma_f32_16x16x32_bf16 v[102:105], v[150:153], v[166:169], v[102:105]
	s_setprio 0
	s_setprio 1
	v_mfma_f32_16x16x32_bf16 v[122:125], v[154:157], v[186:189], v[122:125]
	v_mfma_f32_16x16x32_bf16 v[122:125], v[158:161], v[190:193], v[122:125]
	v_mfma_f32_16x16x32_bf16 v[114:117], v[154:157], v[178:181], v[114:117]
	v_mfma_f32_16x16x32_bf16 v[114:117], v[158:161], v[182:185], v[114:117]
	s_setprio 0
	s_setprio 1
	v_mfma_f32_16x16x32_bf16 v[106:109], v[154:157], v[170:173], v[106:109]
	v_mfma_f32_16x16x32_bf16 v[106:109], v[158:161], v[174:177], v[106:109]
	s_waitcnt lgkmcnt(0)
	v_mfma_f32_16x16x32_bf16 v[98:101], v[154:157], v[162:165], v[98:101]
	v_mfma_f32_16x16x32_bf16 v[98:101], v[158:161], v[166:169], v[98:101]
	s_setprio 0
	s_setprio 1
	v_mfma_f32_16x16x32_bf16 v[94:97], v[130:133], v[186:189], v[94:97]
	v_mfma_f32_16x16x32_bf16 v[94:97], v[134:137], v[190:193], v[94:97]
	v_mfma_f32_16x16x32_bf16 v[86:89], v[130:133], v[178:181], v[86:89]
	v_mfma_f32_16x16x32_bf16 v[86:89], v[134:137], v[182:185], v[86:89]
	s_setprio 0
	s_setprio 1
	v_mfma_f32_16x16x32_bf16 v[78:81], v[130:133], v[170:173], v[78:81]
	v_mfma_f32_16x16x32_bf16 v[78:81], v[134:137], v[174:177], v[78:81]
	v_mfma_f32_16x16x32_bf16 v[70:73], v[130:133], v[162:165], v[70:73]
	v_mfma_f32_16x16x32_bf16 v[70:73], v[134:137], v[166:169], v[70:73]
	s_setprio 0
	s_setprio 1
	v_mfma_f32_16x16x32_bf16 v[90:93], v[138:141], v[186:189], v[90:93]
	v_mfma_f32_16x16x32_bf16 v[90:93], v[142:145], v[190:193], v[90:93]
	v_mfma_f32_16x16x32_bf16 v[82:85], v[138:141], v[178:181], v[82:85]
	v_mfma_f32_16x16x32_bf16 v[82:85], v[142:145], v[182:185], v[82:85]
	s_setprio 0
	s_setprio 1
	v_mfma_f32_16x16x32_bf16 v[74:77], v[138:141], v[170:173], v[74:77]
	v_mfma_f32_16x16x32_bf16 v[74:77], v[142:145], v[174:177], v[74:77]
	s_setprio 2
	s_barrier
	v_mfma_f32_16x16x32_bf16 v[66:69], v[138:141], v[162:165], v[66:69]
	v_mfma_f32_16x16x32_bf16 v[66:69], v[142:145], v[166:169], v[66:69]
	s_setprio 0
	s_nop 0
	ds_read_b128 v[186:189], v219 offset:16384
	ds_read_b128 v[190:193], v219 offset:17408
	ds_read_b128 v[178:181], v219 offset:18432
	ds_read_b128 v[182:185], v219 offset:19456
	ds_read_b128 v[170:173], v219 offset:20480
	ds_read_b128 v[174:177], v219 offset:21504
	ds_read_b128 v[162:165], v219 offset:22528
	ds_read_b128 v[166:169], v219 offset:23552
	s_mov_b32 m0, s74
	s_nop 0
	global_load_lds_dwordx4 v195, s[50:51]
	s_add_u32 m0, s74, 0x2000
	s_nop 0
	global_load_lds_dwordx4 v212, s[50:51]
	s_add_u32 s62, s50, 0x4000
	s_addc_u32 s63, s51, 0
	s_mov_b32 m0, s75
	s_nop 0
	global_load_lds_dwordx4 v195, s[62:63]
	s_add_u32 m0, s75, 0x2000
	s_nop 0
	global_load_lds_dwordx4 v212, s[62:63]
	s_andn2_b64 vcc, exec, s[54:55]
	s_mov_b32 m0, s73
	s_nop 0
	global_load_lds_dwordx4 v195, s[52:53]
	s_add_u32 m0, s73, 0x2000
	s_nop 0
	global_load_lds_dwordx4 v212, s[52:53]
	s_cbranch_vccnz .LBB0_366
	v_mov_b32_e32 v2, 0
	v_mov_b32_e32 v3, v2
	v_mov_b32_e32 v4, v2
	v_mov_b32_e32 v5, v2
	v_mov_b32_e32 v6, v2
	v_mov_b32_e32 v7, v2
	v_mov_b32_e32 v8, v2
	v_mov_b32_e32 v9, v2
	v_mov_b32_e32 v10, v2
	v_mov_b32_e32 v11, v2
	v_mov_b32_e32 v12, v2
	v_mov_b32_e32 v13, v2
	v_mov_b32_e32 v14, v2
	v_mov_b32_e32 v15, v2
	v_mov_b32_e32 v16, v2
	v_mov_b32_e32 v17, v2
	v_mov_b32_e32 v18, v2
	v_mov_b32_e32 v19, v2
	v_mov_b32_e32 v20, v2
	v_mov_b32_e32 v21, v2
	v_mov_b32_e32 v22, v2
	v_mov_b32_e32 v23, v2
	v_mov_b32_e32 v24, v2
	v_mov_b32_e32 v25, v2
	v_mov_b32_e32 v26, v2
	v_mov_b32_e32 v27, v2
	v_mov_b32_e32 v28, v2
	v_mov_b32_e32 v29, v2
	v_mov_b32_e32 v30, v2
	v_mov_b32_e32 v31, v2
	v_mov_b32_e32 v32, v2
	v_mov_b32_e32 v33, v2
	v_mov_b32_e32 v34, v2
	v_mov_b32_e32 v35, v2
	v_mov_b32_e32 v36, v2
	v_mov_b32_e32 v37, v2
	v_mov_b32_e32 v38, v2
	v_mov_b32_e32 v39, v2
	v_mov_b32_e32 v40, v2
	v_mov_b32_e32 v41, v2
	v_mov_b32_e32 v42, v2
	v_mov_b32_e32 v43, v2
	v_mov_b32_e32 v44, v2
	v_mov_b32_e32 v45, v2
	v_mov_b32_e32 v46, v2
	v_mov_b32_e32 v47, v2
	v_mov_b32_e32 v48, v2
	v_mov_b32_e32 v49, v2
	v_mov_b32_e32 v50, v2
	v_mov_b32_e32 v51, v2
	v_mov_b32_e32 v52, v2
	v_mov_b32_e32 v53, v2
	v_mov_b32_e32 v54, v2
	v_mov_b32_e32 v55, v2
	v_mov_b32_e32 v56, v2
	v_mov_b32_e32 v57, v2
	v_mov_b32_e32 v58, v2
	v_mov_b32_e32 v59, v2
	v_mov_b32_e32 v60, v2
	v_mov_b32_e32 v61, v2
	v_mov_b32_e32 v62, v2
	v_mov_b32_e32 v63, v2
	v_mov_b32_e32 v64, v2
	v_mov_b32_e32 v65, v2
.LBB0_366:
	s_waitcnt vmcnt(8)
	s_add_u32 s54, s52, 0x8000
	s_waitcnt lgkmcnt(0)
	s_addc_u32 s55, s53, 0
	s_add_u32 s62, s50, 0x8000
	s_addc_u32 s63, s51, 0
	s_setprio 1
	s_barrier
	v_mfma_f32_16x16x32_bf16 v[62:65], v[146:149], v[186:189], v[62:65]
	v_mfma_f32_16x16x32_bf16 v[62:65], v[150:153], v[190:193], v[62:65]
	s_waitcnt lgkmcnt(5)
	v_mfma_f32_16x16x32_bf16 v[54:57], v[146:149], v[178:181], v[54:57]
	v_mfma_f32_16x16x32_bf16 v[54:57], v[150:153], v[182:185], v[54:57]
	s_waitcnt lgkmcnt(3)
	s_setprio 0
	s_setprio 1
	v_mfma_f32_16x16x32_bf16 v[46:49], v[146:149], v[170:173], v[46:49]
	v_mfma_f32_16x16x32_bf16 v[46:49], v[150:153], v[174:177], v[46:49]
	s_waitcnt lgkmcnt(1)
	v_mfma_f32_16x16x32_bf16 v[38:41], v[146:149], v[162:165], v[38:41]
	v_mfma_f32_16x16x32_bf16 v[38:41], v[150:153], v[166:169], v[38:41]
	s_setprio 0
	s_setprio 1
	v_mfma_f32_16x16x32_bf16 v[58:61], v[154:157], v[186:189], v[58:61]
	v_mfma_f32_16x16x32_bf16 v[58:61], v[158:161], v[190:193], v[58:61]
	v_mfma_f32_16x16x32_bf16 v[50:53], v[154:157], v[178:181], v[50:53]
	v_mfma_f32_16x16x32_bf16 v[50:53], v[158:161], v[182:185], v[50:53]
	s_setprio 0
	s_setprio 1
	v_mfma_f32_16x16x32_bf16 v[42:45], v[154:157], v[170:173], v[42:45]
	v_mfma_f32_16x16x32_bf16 v[42:45], v[158:161], v[174:177], v[42:45]
	s_waitcnt lgkmcnt(0)
	v_mfma_f32_16x16x32_bf16 v[34:37], v[154:157], v[162:165], v[34:37]
	v_mfma_f32_16x16x32_bf16 v[34:37], v[158:161], v[166:169], v[34:37]
	s_setprio 0
	s_setprio 1
	v_mfma_f32_16x16x32_bf16 v[30:33], v[130:133], v[186:189], v[30:33]
	v_mfma_f32_16x16x32_bf16 v[30:33], v[134:137], v[190:193], v[30:33]
	v_mfma_f32_16x16x32_bf16 v[22:25], v[130:133], v[178:181], v[22:25]
	v_mfma_f32_16x16x32_bf16 v[22:25], v[134:137], v[182:185], v[22:25]
	s_setprio 0
	s_setprio 1
	v_mfma_f32_16x16x32_bf16 v[14:17], v[130:133], v[170:173], v[14:17]
	v_mfma_f32_16x16x32_bf16 v[14:17], v[134:137], v[174:177], v[14:17]
	v_mfma_f32_16x16x32_bf16 v[6:9], v[130:133], v[162:165], v[6:9]
	v_mfma_f32_16x16x32_bf16 v[6:9], v[134:137], v[166:169], v[6:9]
	s_setprio 0
	s_setprio 1
	v_mfma_f32_16x16x32_bf16 v[26:29], v[138:141], v[186:189], v[26:29]
	v_mfma_f32_16x16x32_bf16 v[26:29], v[142:145], v[190:193], v[26:29]
	v_mfma_f32_16x16x32_bf16 v[18:21], v[138:141], v[178:181], v[18:21]
	v_mfma_f32_16x16x32_bf16 v[18:21], v[142:145], v[182:185], v[18:21]
	s_setprio 0
	s_setprio 1
	v_mfma_f32_16x16x32_bf16 v[10:13], v[138:141], v[170:173], v[10:13]
	v_mfma_f32_16x16x32_bf16 v[10:13], v[142:145], v[174:177], v[10:13]
	s_setprio 2
	s_barrier
	v_mfma_f32_16x16x32_bf16 v[2:5], v[138:141], v[162:165], v[2:5]
	v_mfma_f32_16x16x32_bf16 v[2:5], v[142:145], v[166:169], v[2:5]
	s_setprio 0
	s_nop 0
	v_add_u32_e32 v142, 0x18000, v218
	v_add_u32_e32 v158, 0x1c000, v218
	ds_read_b128 v[130:133], v142
	ds_read_b128 v[134:137], v142 offset:1024
	ds_read_b128 v[138:141], v142 offset:2048
	ds_read_b128 v[142:145], v142 offset:3072
	ds_read_b128 v[146:149], v158
	ds_read_b128 v[150:153], v158 offset:1024
	ds_read_b128 v[154:157], v158 offset:2048
	ds_read_b128 v[158:161], v158 offset:3072
	ds_read_b128 v[162:165], v219 offset:32768
	ds_read_b128 v[166:169], v219 offset:33792
	ds_read_b128 v[170:173], v219 offset:34816
	ds_read_b128 v[174:177], v219 offset:35840
	ds_read_b128 v[178:181], v219 offset:36864
	ds_read_b128 v[182:185], v219 offset:37888
	ds_read_b128 v[186:189], v219 offset:38912
	ds_read_b128 v[190:193], v219 offset:39936
	s_add_u32 s52, s52, 0x4000
	s_addc_u32 s53, s53, 0
	s_mov_b32 m0, s76
	s_nop 0
	global_load_lds_dwordx4 v195, s[52:53]
	s_add_u32 m0, s76, 0x2000
	s_nop 0
	global_load_lds_dwordx4 v212, s[52:53]
	s_waitcnt vmcnt(8)
	s_waitcnt lgkmcnt(0)
	s_setprio 1
	s_barrier
	v_mfma_f32_16x16x32_bf16 v[126:129], v[130:133], v[162:165], v[126:129]
	v_mfma_f32_16x16x32_bf16 v[126:129], v[134:137], v[166:169], v[126:129]
	s_waitcnt lgkmcnt(5)
	v_mfma_f32_16x16x32_bf16 v[118:121], v[130:133], v[170:173], v[118:121]
	v_mfma_f32_16x16x32_bf16 v[118:121], v[134:137], v[174:177], v[118:121]
	s_waitcnt lgkmcnt(3)
	s_setprio 0
	s_setprio 1
	v_mfma_f32_16x16x32_bf16 v[110:113], v[130:133], v[178:181], v[110:113]
	v_mfma_f32_16x16x32_bf16 v[110:113], v[134:137], v[182:185], v[110:113]
	s_waitcnt lgkmcnt(1)
	v_mfma_f32_16x16x32_bf16 v[102:105], v[130:133], v[186:189], v[102:105]
	v_mfma_f32_16x16x32_bf16 v[102:105], v[134:137], v[190:193], v[102:105]
	s_setprio 0
	s_setprio 1
	v_mfma_f32_16x16x32_bf16 v[122:125], v[138:141], v[162:165], v[122:125]
	v_mfma_f32_16x16x32_bf16 v[122:125], v[142:145], v[166:169], v[122:125]
	v_mfma_f32_16x16x32_bf16 v[114:117], v[138:141], v[170:173], v[114:117]
	v_mfma_f32_16x16x32_bf16 v[114:117], v[142:145], v[174:177], v[114:117]
	s_setprio 0
	s_setprio 1
	v_mfma_f32_16x16x32_bf16 v[106:109], v[138:141], v[178:181], v[106:109]
	v_mfma_f32_16x16x32_bf16 v[106:109], v[142:145], v[182:185], v[106:109]
	s_waitcnt lgkmcnt(0)
	v_mfma_f32_16x16x32_bf16 v[98:101], v[138:141], v[186:189], v[98:101]
	v_mfma_f32_16x16x32_bf16 v[98:101], v[142:145], v[190:193], v[98:101]
	s_setprio 0
	s_setprio 1
	v_mfma_f32_16x16x32_bf16 v[94:97], v[146:149], v[162:165], v[94:97]
	v_mfma_f32_16x16x32_bf16 v[94:97], v[150:153], v[166:169], v[94:97]
	v_mfma_f32_16x16x32_bf16 v[86:89], v[146:149], v[170:173], v[86:89]
	v_mfma_f32_16x16x32_bf16 v[86:89], v[150:153], v[174:177], v[86:89]
	s_setprio 0
	s_setprio 1
	v_mfma_f32_16x16x32_bf16 v[78:81], v[146:149], v[178:181], v[78:81]
	v_mfma_f32_16x16x32_bf16 v[78:81], v[150:153], v[182:185], v[78:81]
	v_mfma_f32_16x16x32_bf16 v[70:73], v[146:149], v[186:189], v[70:73]
	v_mfma_f32_16x16x32_bf16 v[70:73], v[150:153], v[190:193], v[70:73]
	s_setprio 0
	s_setprio 1
	v_mfma_f32_16x16x32_bf16 v[90:93], v[154:157], v[162:165], v[90:93]
	v_mfma_f32_16x16x32_bf16 v[90:93], v[158:161], v[166:169], v[90:93]
	v_mfma_f32_16x16x32_bf16 v[82:85], v[154:157], v[170:173], v[82:85]
	v_mfma_f32_16x16x32_bf16 v[82:85], v[158:161], v[174:177], v[82:85]
	s_setprio 0
	s_setprio 1
	v_mfma_f32_16x16x32_bf16 v[74:77], v[154:157], v[178:181], v[74:77]
	v_mfma_f32_16x16x32_bf16 v[74:77], v[158:161], v[182:185], v[74:77]
	s_setprio 2
	s_barrier
	v_mfma_f32_16x16x32_bf16 v[66:69], v[154:157], v[186:189], v[66:69]
	v_mfma_f32_16x16x32_bf16 v[66:69], v[158:161], v[190:193], v[66:69]
	s_setprio 0
	s_nop 0
	ds_read_b128 v[162:165], v219 offset:49152
	ds_read_b128 v[166:169], v219 offset:50176
	ds_read_b128 v[170:173], v219 offset:51200
	ds_read_b128 v[174:177], v219 offset:52224
	ds_read_b128 v[178:181], v219 offset:53248
	ds_read_b128 v[182:185], v219 offset:54272
	ds_read_b128 v[186:189], v219 offset:55296
	ds_read_b128 v[190:193], v219 offset:56320
	s_mov_b32 m0, s80
	s_nop 0
	global_load_lds_dwordx4 v195, s[62:63]
	s_add_u32 m0, s80, 0x2000
	s_nop 0
	global_load_lds_dwordx4 v212, s[62:63]
	s_add_u32 s50, s50, 0xc000
	s_addc_u32 s51, s51, 0
	s_mov_b32 m0, s82
	s_nop 0
	global_load_lds_dwordx4 v195, s[50:51]
	s_add_u32 m0, s82, 0x2000
	s_nop 0
	global_load_lds_dwordx4 v212, s[50:51]
	s_nop 0
	s_mov_b32 m0, s81
	s_nop 0
	global_load_lds_dwordx4 v195, s[54:55]
	s_add_u32 m0, s81, 0x2000
	s_nop 0
	global_load_lds_dwordx4 v212, s[54:55]
	s_waitcnt vmcnt(8)
	s_waitcnt lgkmcnt(0)
	s_setprio 1
	s_barrier
	v_mfma_f32_16x16x32_bf16 v[62:65], v[130:133], v[162:165], v[62:65]
	v_mfma_f32_16x16x32_bf16 v[62:65], v[134:137], v[166:169], v[62:65]
	s_waitcnt lgkmcnt(5)
	v_mfma_f32_16x16x32_bf16 v[54:57], v[130:133], v[170:173], v[54:57]
	v_mfma_f32_16x16x32_bf16 v[54:57], v[134:137], v[174:177], v[54:57]
	s_waitcnt lgkmcnt(3)
	s_setprio 0
	s_setprio 1
	v_mfma_f32_16x16x32_bf16 v[46:49], v[130:133], v[178:181], v[46:49]
	v_mfma_f32_16x16x32_bf16 v[46:49], v[134:137], v[182:185], v[46:49]
	s_waitcnt lgkmcnt(1)
	v_mfma_f32_16x16x32_bf16 v[38:41], v[130:133], v[186:189], v[38:41]
	v_mfma_f32_16x16x32_bf16 v[38:41], v[134:137], v[190:193], v[38:41]
	s_setprio 0
	s_setprio 1
	v_mfma_f32_16x16x32_bf16 v[58:61], v[138:141], v[162:165], v[58:61]
	v_mfma_f32_16x16x32_bf16 v[58:61], v[142:145], v[166:169], v[58:61]
	v_mfma_f32_16x16x32_bf16 v[50:53], v[138:141], v[170:173], v[50:53]
	v_mfma_f32_16x16x32_bf16 v[50:53], v[142:145], v[174:177], v[50:53]
	s_setprio 0
	s_setprio 1
	v_mfma_f32_16x16x32_bf16 v[42:45], v[138:141], v[178:181], v[42:45]
	v_mfma_f32_16x16x32_bf16 v[42:45], v[142:145], v[182:185], v[42:45]
	s_waitcnt lgkmcnt(0)
	v_mfma_f32_16x16x32_bf16 v[34:37], v[138:141], v[186:189], v[34:37]
	v_mfma_f32_16x16x32_bf16 v[34:37], v[142:145], v[190:193], v[34:37]
	s_setprio 0
	s_setprio 1
	v_mfma_f32_16x16x32_bf16 v[30:33], v[146:149], v[162:165], v[30:33]
	v_mfma_f32_16x16x32_bf16 v[30:33], v[150:153], v[166:169], v[30:33]
	v_mfma_f32_16x16x32_bf16 v[22:25], v[146:149], v[170:173], v[22:25]
	v_mfma_f32_16x16x32_bf16 v[22:25], v[150:153], v[174:177], v[22:25]
	s_setprio 0
	s_setprio 1
	v_mfma_f32_16x16x32_bf16 v[14:17], v[146:149], v[178:181], v[14:17]
	v_mfma_f32_16x16x32_bf16 v[14:17], v[150:153], v[182:185], v[14:17]
	v_mfma_f32_16x16x32_bf16 v[6:9], v[146:149], v[186:189], v[6:9]
	v_mfma_f32_16x16x32_bf16 v[6:9], v[150:153], v[190:193], v[6:9]
	s_setprio 0
	s_setprio 1
	v_mfma_f32_16x16x32_bf16 v[26:29], v[154:157], v[162:165], v[26:29]
	v_mfma_f32_16x16x32_bf16 v[26:29], v[158:161], v[166:169], v[26:29]
	v_mfma_f32_16x16x32_bf16 v[18:21], v[154:157], v[170:173], v[18:21]
	v_mfma_f32_16x16x32_bf16 v[18:21], v[158:161], v[174:177], v[18:21]
	s_setprio 0
	s_setprio 1
	v_mfma_f32_16x16x32_bf16 v[10:13], v[154:157], v[178:181], v[10:13]
	v_mfma_f32_16x16x32_bf16 v[10:13], v[158:161], v[182:185], v[10:13]
	s_setprio 2
	s_barrier
	v_mfma_f32_16x16x32_bf16 v[2:5], v[154:157], v[186:189], v[2:5]
	v_mfma_f32_16x16x32_bf16 v[2:5], v[158:161], v[190:193], v[2:5]
	s_setprio 0
	s_nop 0
	s_cmp_gt_u32 s93, 41
	s_cbranch_scc1 .LBB0_368
	v_mov_b32_e32 v130, v198
	s_mov_b32 s93, s26
	s_branch .LBB0_343

.LBB0_519:
	ds_read_b128 v[130:133], v141
	ds_read_b128 v[134:137], v141 offset:1024
	ds_read_b128 v[146:149], v141 offset:2048
	ds_read_b128 v[150:153], v141 offset:3072
	ds_read_b128 v[154:157], v142
	ds_read_b128 v[158:161], v142 offset:1024
	ds_read_b128 v[162:165], v142 offset:2048
	ds_read_b128 v[166:169], v142 offset:3072
	s_add_u32 s24, s26, 0x10000
	s_addc_u32 s25, s27, 0
	s_cmp_eq_u32 s77, 12
	s_cselect_b32 s48, s17, s24
	s_cselect_b32 s49, s1, s25
	s_cselect_b32 s30, s23, s75
	s_cselect_b32 s31, s15, s76
	s_add_u32 s28, s48, 0x8000
	s_addc_u32 s29, s49, 0
	ds_read_b128 v[170:173], v143
	ds_read_b128 v[174:177], v143 offset:1024
	ds_read_b128 v[178:181], v143 offset:2048
	ds_read_b128 v[182:185], v143 offset:3072
	ds_read_b128 v[186:189], v143 offset:4096
	ds_read_b128 v[190:193], v143 offset:5120
	ds_read_b128 v[198:201], v143 offset:6144
	ds_read_b128 v[202:205], v143 offset:7168
	s_add_u32 s38, s30, 0x8000
	s_addc_u32 s39, s31, 0
	s_add_u32 s26, s26, 0xc000
	s_addc_u32 s27, s27, 0
	s_mov_b32 m0, s72
	s_nop 0
	global_load_lds_dwordx4 v195, s[26:27]
	s_add_u32 m0, s72, 0x2000
	s_nop 0
	global_load_lds_dwordx4 v212, s[26:27]
	s_waitcnt vmcnt(8)
	s_waitcnt lgkmcnt(0)
	s_setprio 1
	s_barrier
	v_mfma_f32_16x16x32_bf16 v[122:125], v[130:133], v[170:173], v[122:125]
	v_mfma_f32_16x16x32_bf16 v[122:125], v[134:137], v[174:177], v[122:125]
	s_waitcnt lgkmcnt(5)
	v_mfma_f32_16x16x32_bf16 v[110:113], v[130:133], v[178:181], v[110:113]
	v_mfma_f32_16x16x32_bf16 v[110:113], v[134:137], v[182:185], v[110:113]
	s_waitcnt lgkmcnt(3)
	s_setprio 0
	s_setprio 1
	v_mfma_f32_16x16x32_bf16 v[94:97], v[130:133], v[186:189], v[94:97]
	v_mfma_f32_16x16x32_bf16 v[94:97], v[134:137], v[190:193], v[94:97]
	s_waitcnt lgkmcnt(1)
	v_mfma_f32_16x16x32_bf16 v[78:81], v[130:133], v[198:201], v[78:81]
	v_mfma_f32_16x16x32_bf16 v[78:81], v[134:137], v[202:205], v[78:81]
	s_setprio 0
	s_setprio 1
	v_mfma_f32_16x16x32_bf16 v[126:129], v[146:149], v[170:173], v[126:129]
	v_mfma_f32_16x16x32_bf16 v[126:129], v[150:153], v[174:177], v[126:129]
	v_mfma_f32_16x16x32_bf16 v[106:109], v[146:149], v[178:181], v[106:109]
	v_mfma_f32_16x16x32_bf16 v[106:109], v[150:153], v[182:185], v[106:109]
	s_setprio 0
	s_setprio 1
	v_mfma_f32_16x16x32_bf16 v[90:93], v[146:149], v[186:189], v[90:93]
	v_mfma_f32_16x16x32_bf16 v[90:93], v[150:153], v[190:193], v[90:93]
	s_waitcnt lgkmcnt(0)
	v_mfma_f32_16x16x32_bf16 v[74:77], v[146:149], v[198:201], v[74:77]
	v_mfma_f32_16x16x32_bf16 v[74:77], v[150:153], v[202:205], v[74:77]
	s_setprio 0
	s_setprio 1
	v_mfma_f32_16x16x32_bf16 v[114:117], v[154:157], v[170:173], v[114:117]
	v_mfma_f32_16x16x32_bf16 v[114:117], v[158:161], v[174:177], v[114:117]
	v_mfma_f32_16x16x32_bf16 v[98:101], v[154:157], v[178:181], v[98:101]
	v_mfma_f32_16x16x32_bf16 v[98:101], v[158:161], v[182:185], v[98:101]
	s_setprio 0
	s_setprio 1
	v_mfma_f32_16x16x32_bf16 v[82:85], v[154:157], v[186:189], v[82:85]
	v_mfma_f32_16x16x32_bf16 v[82:85], v[158:161], v[190:193], v[82:85]
	v_mfma_f32_16x16x32_bf16 v[66:69], v[154:157], v[198:201], v[66:69]
	v_mfma_f32_16x16x32_bf16 v[66:69], v[158:161], v[202:205], v[66:69]
	s_setprio 0
	s_setprio 1
	v_mfma_f32_16x16x32_bf16 v[118:121], v[162:165], v[170:173], v[118:121]
	v_mfma_f32_16x16x32_bf16 v[118:121], v[166:169], v[174:177], v[118:121]
	v_mfma_f32_16x16x32_bf16 v[102:105], v[162:165], v[178:181], v[102:105]
	v_mfma_f32_16x16x32_bf16 v[102:105], v[166:169], v[182:185], v[102:105]
	s_setprio 0
	s_setprio 1
	v_mfma_f32_16x16x32_bf16 v[86:89], v[162:165], v[186:189], v[86:89]
	v_mfma_f32_16x16x32_bf16 v[86:89], v[166:169], v[190:193], v[86:89]
	s_setprio 2
	s_barrier
	v_mfma_f32_16x16x32_bf16 v[70:73], v[162:165], v[198:201], v[70:73]
	v_mfma_f32_16x16x32_bf16 v[70:73], v[166:169], v[202:205], v[70:73]
	s_setprio 0
	s_nop 0
	ds_read_b128 v[170:173], v143 offset:16384
	ds_read_b128 v[174:177], v143 offset:17408
	ds_read_b128 v[178:181], v143 offset:18432
	ds_read_b128 v[182:185], v143 offset:19456
	ds_read_b128 v[186:189], v143 offset:20480
	ds_read_b128 v[190:193], v143 offset:21504
	ds_read_b128 v[198:201], v143 offset:22528
	ds_read_b128 v[202:205], v143 offset:23552
	s_mov_b32 m0, s55
	s_nop 0
	global_load_lds_dwordx4 v195, s[30:31]
	s_add_u32 m0, s55, 0x2000
	s_nop 0
	global_load_lds_dwordx4 v212, s[30:31]
	s_add_u32 s26, s30, 0x4000
	s_addc_u32 s27, s31, 0
	s_mov_b32 m0, s62
	s_nop 0
	global_load_lds_dwordx4 v195, s[26:27]
	s_add_u32 m0, s62, 0x2000
	s_nop 0
	global_load_lds_dwordx4 v212, s[26:27]
	s_nop 0
	s_mov_b32 m0, s54
	s_nop 0
	global_load_lds_dwordx4 v195, s[48:49]
	s_add_u32 m0, s54, 0x2000
	s_nop 0
	global_load_lds_dwordx4 v212, s[48:49]
	s_waitcnt vmcnt(8)
	s_waitcnt lgkmcnt(0)
	s_setprio 1
	s_barrier
	v_mfma_f32_16x16x32_bf16 v[62:65], v[130:133], v[170:173], v[62:65]
	v_mfma_f32_16x16x32_bf16 v[62:65], v[134:137], v[174:177], v[62:65]
	s_waitcnt lgkmcnt(5)
	v_mfma_f32_16x16x32_bf16 v[46:49], v[130:133], v[178:181], v[46:49]
	v_mfma_f32_16x16x32_bf16 v[46:49], v[134:137], v[182:185], v[46:49]
	s_waitcnt lgkmcnt(3)
	s_setprio 0
	s_setprio 1
	v_mfma_f32_16x16x32_bf16 v[30:33], v[130:133], v[186:189], v[30:33]
	v_mfma_f32_16x16x32_bf16 v[30:33], v[134:137], v[190:193], v[30:33]
	s_waitcnt lgkmcnt(1)
	v_mfma_f32_16x16x32_bf16 v[14:17], v[130:133], v[198:201], v[14:17]
	v_mfma_f32_16x16x32_bf16 v[14:17], v[134:137], v[202:205], v[14:17]
	s_setprio 0
	s_setprio 1
	v_mfma_f32_16x16x32_bf16 v[58:61], v[146:149], v[170:173], v[58:61]
	v_mfma_f32_16x16x32_bf16 v[58:61], v[150:153], v[174:177], v[58:61]
	v_mfma_f32_16x16x32_bf16 v[42:45], v[146:149], v[178:181], v[42:45]
	v_mfma_f32_16x16x32_bf16 v[42:45], v[150:153], v[182:185], v[42:45]
	s_setprio 0
	s_setprio 1
	v_mfma_f32_16x16x32_bf16 v[26:29], v[146:149], v[186:189], v[26:29]
	v_mfma_f32_16x16x32_bf16 v[26:29], v[150:153], v[190:193], v[26:29]
	s_waitcnt lgkmcnt(0)
	v_mfma_f32_16x16x32_bf16 v[10:13], v[146:149], v[198:201], v[10:13]
	v_mfma_f32_16x16x32_bf16 v[10:13], v[150:153], v[202:205], v[10:13]
	s_setprio 0
	s_setprio 1
	v_mfma_f32_16x16x32_bf16 v[50:53], v[154:157], v[170:173], v[50:53]
	v_mfma_f32_16x16x32_bf16 v[50:53], v[158:161], v[174:177], v[50:53]
	v_mfma_f32_16x16x32_bf16 v[34:37], v[154:157], v[178:181], v[34:37]
	v_mfma_f32_16x16x32_bf16 v[34:37], v[158:161], v[182:185], v[34:37]
	s_setprio 0
	s_setprio 1
	v_mfma_f32_16x16x32_bf16 v[18:21], v[154:157], v[186:189], v[18:21]
	v_mfma_f32_16x16x32_bf16 v[18:21], v[158:161], v[190:193], v[18:21]
	v_mfma_f32_16x16x32_bf16 v[2:5], v[154:157], v[198:201], v[2:5]
	v_mfma_f32_16x16x32_bf16 v[2:5], v[158:161], v[202:205], v[2:5]
	s_setprio 0
	s_setprio 1
	v_mfma_f32_16x16x32_bf16 v[54:57], v[162:165], v[170:173], v[54:57]
	v_mfma_f32_16x16x32_bf16 v[54:57], v[166:169], v[174:177], v[54:57]
	v_mfma_f32_16x16x32_bf16 v[38:41], v[162:165], v[178:181], v[38:41]
	v_mfma_f32_16x16x32_bf16 v[38:41], v[166:169], v[182:185], v[38:41]
	s_setprio 0
	s_setprio 1
	v_mfma_f32_16x16x32_bf16 v[22:25], v[162:165], v[186:189], v[22:25]
	v_mfma_f32_16x16x32_bf16 v[22:25], v[166:169], v[190:193], v[22:25]
	s_setprio 2
	s_barrier
	v_mfma_f32_16x16x32_bf16 v[6:9], v[162:165], v[198:201], v[6:9]
	v_mfma_f32_16x16x32_bf16 v[6:9], v[166:169], v[202:205], v[6:9]
	s_setprio 0
	s_nop 0
	ds_read_b128 v[130:133], v144
	ds_read_b128 v[134:137], v144 offset:1024
	ds_read_b128 v[146:149], v144 offset:2048
	ds_read_b128 v[150:153], v144 offset:3072
	ds_read_b128 v[154:157], v145
	ds_read_b128 v[158:161], v145 offset:1024
	ds_read_b128 v[162:165], v145 offset:2048
	ds_read_b128 v[166:169], v145 offset:3072
	ds_read_b128 v[170:173], v143 offset:32768
	ds_read_b128 v[174:177], v143 offset:33792
	ds_read_b128 v[178:181], v143 offset:34816
	ds_read_b128 v[182:185], v143 offset:35840
	ds_read_b128 v[186:189], v143 offset:36864
	ds_read_b128 v[190:193], v143 offset:37888
	ds_read_b128 v[198:201], v143 offset:38912
	ds_read_b128 v[202:205], v143 offset:39936
	s_add_u32 s26, s48, 0x4000
	s_addc_u32 s27, s49, 0
	s_mov_b32 m0, s63
	s_nop 0
	global_load_lds_dwordx4 v195, s[26:27]
	s_add_u32 m0, s63, 0x2000
	s_nop 0
	global_load_lds_dwordx4 v212, s[26:27]
	s_waitcnt vmcnt(8)
	s_waitcnt lgkmcnt(0)
	s_setprio 1
	s_barrier
	v_mfma_f32_16x16x32_bf16 v[122:125], v[130:133], v[170:173], v[122:125]
	v_mfma_f32_16x16x32_bf16 v[122:125], v[134:137], v[174:177], v[122:125]
	s_waitcnt lgkmcnt(5)
	v_mfma_f32_16x16x32_bf16 v[110:113], v[130:133], v[178:181], v[110:113]
	v_mfma_f32_16x16x32_bf16 v[110:113], v[134:137], v[182:185], v[110:113]
	s_waitcnt lgkmcnt(3)
	s_setprio 0
	s_setprio 1
	v_mfma_f32_16x16x32_bf16 v[94:97], v[130:133], v[186:189], v[94:97]
	v_mfma_f32_16x16x32_bf16 v[94:97], v[134:137], v[190:193], v[94:97]
	s_waitcnt lgkmcnt(1)
	v_mfma_f32_16x16x32_bf16 v[78:81], v[130:133], v[198:201], v[78:81]
	v_mfma_f32_16x16x32_bf16 v[78:81], v[134:137], v[202:205], v[78:81]
	s_setprio 0
	s_setprio 1
	v_mfma_f32_16x16x32_bf16 v[126:129], v[146:149], v[170:173], v[126:129]
	v_mfma_f32_16x16x32_bf16 v[126:129], v[150:153], v[174:177], v[126:129]
	v_mfma_f32_16x16x32_bf16 v[106:109], v[146:149], v[178:181], v[106:109]
	v_mfma_f32_16x16x32_bf16 v[106:109], v[150:153], v[182:185], v[106:109]
	s_setprio 0
	s_setprio 1
	v_mfma_f32_16x16x32_bf16 v[90:93], v[146:149], v[186:189], v[90:93]
	v_mfma_f32_16x16x32_bf16 v[90:93], v[150:153], v[190:193], v[90:93]
	s_waitcnt lgkmcnt(0)
	v_mfma_f32_16x16x32_bf16 v[74:77], v[146:149], v[198:201], v[74:77]
	v_mfma_f32_16x16x32_bf16 v[74:77], v[150:153], v[202:205], v[74:77]
	s_setprio 0
	s_setprio 1
	v_mfma_f32_16x16x32_bf16 v[114:117], v[154:157], v[170:173], v[114:117]
	v_mfma_f32_16x16x32_bf16 v[114:117], v[158:161], v[174:177], v[114:117]
	v_mfma_f32_16x16x32_bf16 v[98:101], v[154:157], v[178:181], v[98:101]
	v_mfma_f32_16x16x32_bf16 v[98:101], v[158:161], v[182:185], v[98:101]
	s_setprio 0
	s_setprio 1
	v_mfma_f32_16x16x32_bf16 v[82:85], v[154:157], v[186:189], v[82:85]
	v_mfma_f32_16x16x32_bf16 v[82:85], v[158:161], v[190:193], v[82:85]
	v_mfma_f32_16x16x32_bf16 v[66:69], v[154:157], v[198:201], v[66:69]
	v_mfma_f32_16x16x32_bf16 v[66:69], v[158:161], v[202:205], v[66:69]
	s_setprio 0
	s_setprio 1
	v_mfma_f32_16x16x32_bf16 v[118:121], v[162:165], v[170:173], v[118:121]
	v_mfma_f32_16x16x32_bf16 v[118:121], v[166:169], v[174:177], v[118:121]
	v_mfma_f32_16x16x32_bf16 v[102:105], v[162:165], v[178:181], v[102:105]
	v_mfma_f32_16x16x32_bf16 v[102:105], v[166:169], v[182:185], v[102:105]
	s_setprio 0
	s_setprio 1
	v_mfma_f32_16x16x32_bf16 v[86:89], v[162:165], v[186:189], v[86:89]
	v_mfma_f32_16x16x32_bf16 v[86:89], v[166:169], v[190:193], v[86:89]
	s_setprio 2
	s_barrier
	v_mfma_f32_16x16x32_bf16 v[70:73], v[162:165], v[198:201], v[70:73]
	v_mfma_f32_16x16x32_bf16 v[70:73], v[166:169], v[202:205], v[70:73]
	s_setprio 0
	s_nop 0
	ds_read_b128 v[170:173], v143 offset:49152
	ds_read_b128 v[174:177], v143 offset:50176
	ds_read_b128 v[178:181], v143 offset:51200
	ds_read_b128 v[182:185], v143 offset:52224
	ds_read_b128 v[186:189], v143 offset:53248
	ds_read_b128 v[190:193], v143 offset:54272
	ds_read_b128 v[198:201], v143 offset:55296
	ds_read_b128 v[202:205], v143 offset:56320
	s_mov_b32 m0, s69
	s_nop 0
	global_load_lds_dwordx4 v195, s[38:39]
	s_add_u32 m0, s69, 0x2000
	s_nop 0
	global_load_lds_dwordx4 v212, s[38:39]
	s_add_u32 s26, s30, 0xc000
	s_addc_u32 s27, s31, 0
	s_mov_b32 m0, s71
	s_nop 0
	global_load_lds_dwordx4 v195, s[26:27]
	s_add_u32 m0, s71, 0x2000
	s_nop 0
	global_load_lds_dwordx4 v212, s[26:27]
	s_nop 0
	s_mov_b32 m0, s70
	s_nop 0
	global_load_lds_dwordx4 v195, s[28:29]
	s_add_u32 m0, s70, 0x2000
	s_nop 0
	global_load_lds_dwordx4 v212, s[28:29]
	s_waitcnt vmcnt(8)
	s_waitcnt lgkmcnt(0)
	s_setprio 1
	s_barrier
	v_mfma_f32_16x16x32_bf16 v[62:65], v[130:133], v[170:173], v[62:65]
	v_mfma_f32_16x16x32_bf16 v[62:65], v[134:137], v[174:177], v[62:65]
	s_waitcnt lgkmcnt(5)
	v_mfma_f32_16x16x32_bf16 v[46:49], v[130:133], v[178:181], v[46:49]
	v_mfma_f32_16x16x32_bf16 v[46:49], v[134:137], v[182:185], v[46:49]
	s_waitcnt lgkmcnt(3)
	s_setprio 0
	s_setprio 1
	v_mfma_f32_16x16x32_bf16 v[30:33], v[130:133], v[186:189], v[30:33]
	v_mfma_f32_16x16x32_bf16 v[30:33], v[134:137], v[190:193], v[30:33]
	s_waitcnt lgkmcnt(1)
	v_mfma_f32_16x16x32_bf16 v[14:17], v[130:133], v[198:201], v[14:17]
	v_mfma_f32_16x16x32_bf16 v[14:17], v[134:137], v[202:205], v[14:17]
	s_setprio 0
	s_setprio 1
	v_mfma_f32_16x16x32_bf16 v[58:61], v[146:149], v[170:173], v[58:61]
	v_mfma_f32_16x16x32_bf16 v[58:61], v[150:153], v[174:177], v[58:61]
	v_mfma_f32_16x16x32_bf16 v[42:45], v[146:149], v[178:181], v[42:45]
	v_mfma_f32_16x16x32_bf16 v[42:45], v[150:153], v[182:185], v[42:45]
	s_setprio 0
	s_setprio 1
	v_mfma_f32_16x16x32_bf16 v[26:29], v[146:149], v[186:189], v[26:29]
	v_mfma_f32_16x16x32_bf16 v[26:29], v[150:153], v[190:193], v[26:29]
	s_waitcnt lgkmcnt(0)
	v_mfma_f32_16x16x32_bf16 v[10:13], v[146:149], v[198:201], v[10:13]
	v_mfma_f32_16x16x32_bf16 v[10:13], v[150:153], v[202:205], v[10:13]
	s_setprio 0
	s_setprio 1
	v_mfma_f32_16x16x32_bf16 v[50:53], v[154:157], v[170:173], v[50:53]
	v_mfma_f32_16x16x32_bf16 v[50:53], v[158:161], v[174:177], v[50:53]
	v_mfma_f32_16x16x32_bf16 v[34:37], v[154:157], v[178:181], v[34:37]
	v_mfma_f32_16x16x32_bf16 v[34:37], v[158:161], v[182:185], v[34:37]
	s_setprio 0
	s_setprio 1
	v_mfma_f32_16x16x32_bf16 v[18:21], v[154:157], v[186:189], v[18:21]
	v_mfma_f32_16x16x32_bf16 v[18:21], v[158:161], v[190:193], v[18:21]
	v_mfma_f32_16x16x32_bf16 v[2:5], v[154:157], v[198:201], v[2:5]
	v_mfma_f32_16x16x32_bf16 v[2:5], v[158:161], v[202:205], v[2:5]
	s_setprio 0
	s_setprio 1
	v_mfma_f32_16x16x32_bf16 v[54:57], v[162:165], v[170:173], v[54:57]
	v_mfma_f32_16x16x32_bf16 v[54:57], v[166:169], v[174:177], v[54:57]
	v_mfma_f32_16x16x32_bf16 v[38:41], v[162:165], v[178:181], v[38:41]
	v_mfma_f32_16x16x32_bf16 v[38:41], v[166:169], v[182:185], v[38:41]
	s_setprio 0
	s_setprio 1
	v_mfma_f32_16x16x32_bf16 v[22:25], v[162:165], v[186:189], v[22:25]
	v_mfma_f32_16x16x32_bf16 v[22:25], v[166:169], v[190:193], v[22:25]
	s_setprio 2
	s_barrier
	v_mfma_f32_16x16x32_bf16 v[6:9], v[162:165], v[198:201], v[6:9]
	v_mfma_f32_16x16x32_bf16 v[6:9], v[166:169], v[202:205], v[6:9]
	s_setprio 0
	s_nop 0
	s_add_i32 s77, s77, 2
	s_add_u32 s75, s75, 0x10000
	s_addc_u32 s76, s76, 0
	s_cmp_gt_u32 s77, 13
	s_mov_b64 s[26:27], s[24:25]
	s_cbranch_scc0 .LBB0_519
	s_and_b64 vcc, exec, s[10:11]
	s_cbranch_vccz .LBB0_522
	s_barrier
	s_setprio 1

.LBB0_635:
	s_add_u32 s28, s24, 0x10000
	s_addc_u32 s29, s25, 0
	s_and_b64 s[24:25], s[22:23], exec
	s_cselect_b32 s25, s29, s15
	s_cselect_b32 s24, s28, s33
	s_add_u32 s3, s52, s3
	s_addc_u32 s28, s53, 0
	s_add_u32 s3, s3, 0x10000
	s_waitcnt vmcnt(8)
	s_addc_u32 s28, s28, 0
	s_waitcnt lgkmcnt(0)
	s_and_b64 s[22:23], s[22:23], exec
	s_cselect_b32 s23, s28, s13
	s_cselect_b32 s22, s3, s70
	s_setprio 1
	s_barrier
	v_mfma_f32_16x16x32_bf16 v[126:129], v[146:149], v[186:189], v[126:129]
	v_mfma_f32_16x16x32_bf16 v[126:129], v[150:153], v[190:193], v[126:129]
	s_waitcnt lgkmcnt(5)
	v_mfma_f32_16x16x32_bf16 v[118:121], v[146:149], v[178:181], v[118:121]
	v_mfma_f32_16x16x32_bf16 v[118:121], v[150:153], v[182:185], v[118:121]
	s_waitcnt lgkmcnt(3)
	s_setprio 0
	s_setprio 1
	v_mfma_f32_16x16x32_bf16 v[110:113], v[146:149], v[170:173], v[110:113]
	v_mfma_f32_16x16x32_bf16 v[110:113], v[150:153], v[174:177], v[110:113]
	s_waitcnt lgkmcnt(1)
	v_mfma_f32_16x16x32_bf16 v[102:105], v[146:149], v[162:165], v[102:105]
	v_mfma_f32_16x16x32_bf16 v[102:105], v[150:153], v[166:169], v[102:105]
	s_setprio 0
	s_setprio 1
	v_mfma_f32_16x16x32_bf16 v[122:125], v[154:157], v[186:189], v[122:125]
	v_mfma_f32_16x16x32_bf16 v[122:125], v[158:161], v[190:193], v[122:125]
	v_mfma_f32_16x16x32_bf16 v[114:117], v[154:157], v[178:181], v[114:117]
	v_mfma_f32_16x16x32_bf16 v[114:117], v[158:161], v[182:185], v[114:117]
	s_setprio 0
	s_setprio 1
	v_mfma_f32_16x16x32_bf16 v[106:109], v[154:157], v[170:173], v[106:109]
	v_mfma_f32_16x16x32_bf16 v[106:109], v[158:161], v[174:177], v[106:109]
	s_waitcnt lgkmcnt(0)
	v_mfma_f32_16x16x32_bf16 v[98:101], v[154:157], v[162:165], v[98:101]
	v_mfma_f32_16x16x32_bf16 v[98:101], v[158:161], v[166:169], v[98:101]
	s_setprio 0
	s_setprio 1
	v_mfma_f32_16x16x32_bf16 v[94:97], v[130:133], v[186:189], v[94:97]
	v_mfma_f32_16x16x32_bf16 v[94:97], v[134:137], v[190:193], v[94:97]
	v_mfma_f32_16x16x32_bf16 v[86:89], v[130:133], v[178:181], v[86:89]
	v_mfma_f32_16x16x32_bf16 v[86:89], v[134:137], v[182:185], v[86:89]
	s_setprio 0
	s_setprio 1
	v_mfma_f32_16x16x32_bf16 v[78:81], v[130:133], v[170:173], v[78:81]
	v_mfma_f32_16x16x32_bf16 v[78:81], v[134:137], v[174:177], v[78:81]
	v_mfma_f32_16x16x32_bf16 v[70:73], v[130:133], v[162:165], v[70:73]
	v_mfma_f32_16x16x32_bf16 v[70:73], v[134:137], v[166:169], v[70:73]
	s_setprio 0
	s_setprio 1
	v_mfma_f32_16x16x32_bf16 v[90:93], v[138:141], v[186:189], v[90:93]
	v_mfma_f32_16x16x32_bf16 v[90:93], v[142:145], v[190:193], v[90:93]
	v_mfma_f32_16x16x32_bf16 v[82:85], v[138:141], v[178:181], v[82:85]
	v_mfma_f32_16x16x32_bf16 v[82:85], v[142:145], v[182:185], v[82:85]
	s_setprio 0
	s_setprio 1
	v_mfma_f32_16x16x32_bf16 v[74:77], v[138:141], v[170:173], v[74:77]
	v_mfma_f32_16x16x32_bf16 v[74:77], v[142:145], v[174:177], v[74:77]
	s_setprio 2
	s_barrier
	v_mfma_f32_16x16x32_bf16 v[66:69], v[138:141], v[162:165], v[66:69]
	v_mfma_f32_16x16x32_bf16 v[66:69], v[142:145], v[166:169], v[66:69]
	s_setprio 0
	s_nop 0
	ds_read_b128 v[186:189], v219 offset:16384
	ds_read_b128 v[190:193], v219 offset:17408
	ds_read_b128 v[178:181], v219 offset:18432
	ds_read_b128 v[182:185], v219 offset:19456
	ds_read_b128 v[170:173], v219 offset:20480
	ds_read_b128 v[174:177], v219 offset:21504
	ds_read_b128 v[162:165], v219 offset:22528
	ds_read_b128 v[166:169], v219 offset:23552
	s_mov_b32 m0, s89
	s_nop 0
	global_load_lds_dwordx4 v195, s[22:23]
	s_add_u32 m0, s89, 0x2000
	s_nop 0
	global_load_lds_dwordx4 v213, s[22:23]
	s_add_u32 s28, s22, 0x4000
	s_addc_u32 s29, s23, 0
	s_mov_b32 m0, s54
	s_nop 0
	global_load_lds_dwordx4 v195, s[28:29]
	s_add_u32 m0, s54, 0x2000
	s_nop 0
	global_load_lds_dwordx4 v213, s[28:29]
	s_andn2_b64 vcc, exec, s[26:27]
	s_mov_b32 m0, s39
	s_nop 0
	global_load_lds_dwordx4 v195, s[24:25]
	s_add_u32 m0, s39, 0x2000
	s_nop 0
	global_load_lds_dwordx4 v213, s[24:25]
	s_cbranch_vccnz .LBB0_637
	v_mov_b32_e32 v2, 0
	v_mov_b32_e32 v3, v2
	v_mov_b32_e32 v4, v2
	v_mov_b32_e32 v5, v2
	v_mov_b32_e32 v6, v2
	v_mov_b32_e32 v7, v2
	v_mov_b32_e32 v8, v2
	v_mov_b32_e32 v9, v2
	v_mov_b32_e32 v10, v2
	v_mov_b32_e32 v11, v2
	v_mov_b32_e32 v12, v2
	v_mov_b32_e32 v13, v2
	v_mov_b32_e32 v14, v2
	v_mov_b32_e32 v15, v2
	v_mov_b32_e32 v16, v2
	v_mov_b32_e32 v17, v2
	v_mov_b32_e32 v18, v2
	v_mov_b32_e32 v19, v2
	v_mov_b32_e32 v20, v2
	v_mov_b32_e32 v21, v2
	v_mov_b32_e32 v22, v2
	v_mov_b32_e32 v23, v2
	v_mov_b32_e32 v24, v2
	v_mov_b32_e32 v25, v2
	v_mov_b32_e32 v26, v2
	v_mov_b32_e32 v27, v2
	v_mov_b32_e32 v28, v2
	v_mov_b32_e32 v29, v2
	v_mov_b32_e32 v30, v2
	v_mov_b32_e32 v31, v2
	v_mov_b32_e32 v32, v2
	v_mov_b32_e32 v33, v2
	v_mov_b32_e32 v34, v2
	v_mov_b32_e32 v35, v2
	v_mov_b32_e32 v36, v2
	v_mov_b32_e32 v37, v2
	v_mov_b32_e32 v38, v2
	v_mov_b32_e32 v39, v2
	v_mov_b32_e32 v40, v2
	v_mov_b32_e32 v41, v2
	v_mov_b32_e32 v42, v2
	v_mov_b32_e32 v43, v2
	v_mov_b32_e32 v44, v2
	v_mov_b32_e32 v45, v2
	v_mov_b32_e32 v46, v2
	v_mov_b32_e32 v47, v2
	v_mov_b32_e32 v48, v2
	v_mov_b32_e32 v49, v2
	v_mov_b32_e32 v50, v2
	v_mov_b32_e32 v51, v2
	v_mov_b32_e32 v52, v2
	v_mov_b32_e32 v53, v2
	v_mov_b32_e32 v54, v2
	v_mov_b32_e32 v55, v2
	v_mov_b32_e32 v56, v2
	v_mov_b32_e32 v57, v2
	v_mov_b32_e32 v58, v2
	v_mov_b32_e32 v59, v2
	v_mov_b32_e32 v60, v2
	v_mov_b32_e32 v61, v2
	v_mov_b32_e32 v62, v2
	v_mov_b32_e32 v63, v2
	v_mov_b32_e32 v64, v2
	v_mov_b32_e32 v65, v2
.LBB0_637:
	s_waitcnt vmcnt(8)
	s_add_u32 s26, s24, 0x8000
	s_waitcnt lgkmcnt(0)
	s_addc_u32 s27, s25, 0
	s_add_u32 s28, s22, 0x8000
	s_addc_u32 s29, s23, 0
	s_setprio 1
	s_barrier
	v_mfma_f32_16x16x32_bf16 v[62:65], v[146:149], v[186:189], v[62:65]
	v_mfma_f32_16x16x32_bf16 v[62:65], v[150:153], v[190:193], v[62:65]
	s_waitcnt lgkmcnt(5)
	v_mfma_f32_16x16x32_bf16 v[54:57], v[146:149], v[178:181], v[54:57]
	v_mfma_f32_16x16x32_bf16 v[54:57], v[150:153], v[182:185], v[54:57]
	s_waitcnt lgkmcnt(3)
	s_setprio 0
	s_setprio 1
	v_mfma_f32_16x16x32_bf16 v[46:49], v[146:149], v[170:173], v[46:49]
	v_mfma_f32_16x16x32_bf16 v[46:49], v[150:153], v[174:177], v[46:49]
	s_waitcnt lgkmcnt(1)
	v_mfma_f32_16x16x32_bf16 v[38:41], v[146:149], v[162:165], v[38:41]
	v_mfma_f32_16x16x32_bf16 v[38:41], v[150:153], v[166:169], v[38:41]
	s_setprio 0
	s_setprio 1
	v_mfma_f32_16x16x32_bf16 v[58:61], v[154:157], v[186:189], v[58:61]
	v_mfma_f32_16x16x32_bf16 v[58:61], v[158:161], v[190:193], v[58:61]
	v_mfma_f32_16x16x32_bf16 v[50:53], v[154:157], v[178:181], v[50:53]
	v_mfma_f32_16x16x32_bf16 v[50:53], v[158:161], v[182:185], v[50:53]
	s_setprio 0
	s_setprio 1
	v_mfma_f32_16x16x32_bf16 v[42:45], v[154:157], v[170:173], v[42:45]
	v_mfma_f32_16x16x32_bf16 v[42:45], v[158:161], v[174:177], v[42:45]
	s_waitcnt lgkmcnt(0)
	v_mfma_f32_16x16x32_bf16 v[34:37], v[154:157], v[162:165], v[34:37]
	v_mfma_f32_16x16x32_bf16 v[34:37], v[158:161], v[166:169], v[34:37]
	s_setprio 0
	s_setprio 1
	v_mfma_f32_16x16x32_bf16 v[30:33], v[130:133], v[186:189], v[30:33]
	v_mfma_f32_16x16x32_bf16 v[30:33], v[134:137], v[190:193], v[30:33]
	v_mfma_f32_16x16x32_bf16 v[22:25], v[130:133], v[178:181], v[22:25]
	v_mfma_f32_16x16x32_bf16 v[22:25], v[134:137], v[182:185], v[22:25]
	s_setprio 0
	s_setprio 1
	v_mfma_f32_16x16x32_bf16 v[14:17], v[130:133], v[170:173], v[14:17]
	v_mfma_f32_16x16x32_bf16 v[14:17], v[134:137], v[174:177], v[14:17]
	v_mfma_f32_16x16x32_bf16 v[6:9], v[130:133], v[162:165], v[6:9]
	v_mfma_f32_16x16x32_bf16 v[6:9], v[134:137], v[166:169], v[6:9]
	s_setprio 0
	s_setprio 1
	v_mfma_f32_16x16x32_bf16 v[26:29], v[138:141], v[186:189], v[26:29]
	v_mfma_f32_16x16x32_bf16 v[26:29], v[142:145], v[190:193], v[26:29]
	v_mfma_f32_16x16x32_bf16 v[18:21], v[138:141], v[178:181], v[18:21]
	v_mfma_f32_16x16x32_bf16 v[18:21], v[142:145], v[182:185], v[18:21]
	s_setprio 0
	s_setprio 1
	v_mfma_f32_16x16x32_bf16 v[10:13], v[138:141], v[170:173], v[10:13]
	v_mfma_f32_16x16x32_bf16 v[10:13], v[142:145], v[174:177], v[10:13]
	s_setprio 2
	s_barrier
	v_mfma_f32_16x16x32_bf16 v[2:5], v[138:141], v[162:165], v[2:5]
	v_mfma_f32_16x16x32_bf16 v[2:5], v[142:145], v[166:169], v[2:5]
	s_setprio 0
	s_nop 0
	v_add_u32_e32 v142, 0x18000, v218
	v_add_u32_e32 v158, 0x1c000, v218
	ds_read_b128 v[130:133], v142
	ds_read_b128 v[134:137], v142 offset:1024
	ds_read_b128 v[138:141], v142 offset:2048
	ds_read_b128 v[142:145], v142 offset:3072
	ds_read_b128 v[146:149], v158
	ds_read_b128 v[150:153], v158 offset:1024
	ds_read_b128 v[154:157], v158 offset:2048
	ds_read_b128 v[158:161], v158 offset:3072
	ds_read_b128 v[162:165], v219 offset:32768
	ds_read_b128 v[166:169], v219 offset:33792
	ds_read_b128 v[170:173], v219 offset:34816
	ds_read_b128 v[174:177], v219 offset:35840
	ds_read_b128 v[178:181], v219 offset:36864
	ds_read_b128 v[182:185], v219 offset:37888
	ds_read_b128 v[186:189], v219 offset:38912
	ds_read_b128 v[190:193], v219 offset:39936
	s_add_u32 s24, s24, 0x4000
	s_addc_u32 s25, s25, 0
	s_mov_b32 m0, s55
	s_nop 0
	global_load_lds_dwordx4 v195, s[24:25]
	s_add_u32 m0, s55, 0x2000
	s_nop 0
	global_load_lds_dwordx4 v213, s[24:25]
	s_waitcnt vmcnt(8)
	s_waitcnt lgkmcnt(0)
	s_setprio 1
	s_barrier
	v_mfma_f32_16x16x32_bf16 v[126:129], v[130:133], v[162:165], v[126:129]
	v_mfma_f32_16x16x32_bf16 v[126:129], v[134:137], v[166:169], v[126:129]
	s_waitcnt lgkmcnt(5)
	v_mfma_f32_16x16x32_bf16 v[118:121], v[130:133], v[170:173], v[118:121]
	v_mfma_f32_16x16x32_bf16 v[118:121], v[134:137], v[174:177], v[118:121]
	s_waitcnt lgkmcnt(3)
	s_setprio 0
	s_setprio 1
	v_mfma_f32_16x16x32_bf16 v[110:113], v[130:133], v[178:181], v[110:113]
	v_mfma_f32_16x16x32_bf16 v[110:113], v[134:137], v[182:185], v[110:113]
	s_waitcnt lgkmcnt(1)
	v_mfma_f32_16x16x32_bf16 v[102:105], v[130:133], v[186:189], v[102:105]
	v_mfma_f32_16x16x32_bf16 v[102:105], v[134:137], v[190:193], v[102:105]
	s_setprio 0
	s_setprio 1
	v_mfma_f32_16x16x32_bf16 v[122:125], v[138:141], v[162:165], v[122:125]
	v_mfma_f32_16x16x32_bf16 v[122:125], v[142:145], v[166:169], v[122:125]
	v_mfma_f32_16x16x32_bf16 v[114:117], v[138:141], v[170:173], v[114:117]
	v_mfma_f32_16x16x32_bf16 v[114:117], v[142:145], v[174:177], v[114:117]
	s_setprio 0
	s_setprio 1
	v_mfma_f32_16x16x32_bf16 v[106:109], v[138:141], v[178:181], v[106:109]
	v_mfma_f32_16x16x32_bf16 v[106:109], v[142:145], v[182:185], v[106:109]
	s_waitcnt lgkmcnt(0)
	v_mfma_f32_16x16x32_bf16 v[98:101], v[138:141], v[186:189], v[98:101]
	v_mfma_f32_16x16x32_bf16 v[98:101], v[142:145], v[190:193], v[98:101]
	s_setprio 0
	s_setprio 1
	v_mfma_f32_16x16x32_bf16 v[94:97], v[146:149], v[162:165], v[94:97]
	v_mfma_f32_16x16x32_bf16 v[94:97], v[150:153], v[166:169], v[94:97]
	v_mfma_f32_16x16x32_bf16 v[86:89], v[146:149], v[170:173], v[86:89]
	v_mfma_f32_16x16x32_bf16 v[86:89], v[150:153], v[174:177], v[86:89]
	s_setprio 0
	s_setprio 1
	v_mfma_f32_16x16x32_bf16 v[78:81], v[146:149], v[178:181], v[78:81]
	v_mfma_f32_16x16x32_bf16 v[78:81], v[150:153], v[182:185], v[78:81]
	v_mfma_f32_16x16x32_bf16 v[70:73], v[146:149], v[186:189], v[70:73]
	v_mfma_f32_16x16x32_bf16 v[70:73], v[150:153], v[190:193], v[70:73]
	s_setprio 0
	s_setprio 1
	v_mfma_f32_16x16x32_bf16 v[90:93], v[154:157], v[162:165], v[90:93]
	v_mfma_f32_16x16x32_bf16 v[90:93], v[158:161], v[166:169], v[90:93]
	v_mfma_f32_16x16x32_bf16 v[82:85], v[154:157], v[170:173], v[82:85]
	v_mfma_f32_16x16x32_bf16 v[82:85], v[158:161], v[174:177], v[82:85]
	s_setprio 0
	s_setprio 1
	v_mfma_f32_16x16x32_bf16 v[74:77], v[154:157], v[178:181], v[74:77]
	v_mfma_f32_16x16x32_bf16 v[74:77], v[158:161], v[182:185], v[74:77]
	s_setprio 2
	s_barrier
	v_mfma_f32_16x16x32_bf16 v[66:69], v[154:157], v[186:189], v[66:69]
	v_mfma_f32_16x16x32_bf16 v[66:69], v[158:161], v[190:193], v[66:69]
	s_setprio 0
	s_nop 0
	ds_read_b128 v[162:165], v219 offset:49152
	ds_read_b128 v[166:169], v219 offset:50176
	ds_read_b128 v[170:173], v219 offset:51200
	ds_read_b128 v[174:177], v219 offset:52224
	ds_read_b128 v[178:181], v219 offset:53248
	ds_read_b128 v[182:185], v219 offset:54272
	ds_read_b128 v[186:189], v219 offset:55296
	ds_read_b128 v[190:193], v219 offset:56320
	s_mov_b32 m0, s83
	s_nop 0
	global_load_lds_dwordx4 v195, s[28:29]
	s_add_u32 m0, s83, 0x2000
	s_nop 0
	global_load_lds_dwordx4 v213, s[28:29]
	s_add_u32 s22, s22, 0xc000
	s_addc_u32 s23, s23, 0
	s_mov_b32 m0, s91
	s_nop 0
	global_load_lds_dwordx4 v195, s[22:23]
	s_add_u32 m0, s91, 0x2000
	s_nop 0
	global_load_lds_dwordx4 v213, s[22:23]
	s_nop 0
	s_mov_b32 m0, s90
	s_nop 0
	global_load_lds_dwordx4 v195, s[26:27]
	s_add_u32 m0, s90, 0x2000
	s_nop 0
	global_load_lds_dwordx4 v213, s[26:27]
	s_waitcnt vmcnt(8)
	s_waitcnt lgkmcnt(0)
	s_setprio 1
	s_barrier
	v_mfma_f32_16x16x32_bf16 v[62:65], v[130:133], v[162:165], v[62:65]
	v_mfma_f32_16x16x32_bf16 v[62:65], v[134:137], v[166:169], v[62:65]
	s_waitcnt lgkmcnt(5)
	v_mfma_f32_16x16x32_bf16 v[54:57], v[130:133], v[170:173], v[54:57]
	v_mfma_f32_16x16x32_bf16 v[54:57], v[134:137], v[174:177], v[54:57]
	s_waitcnt lgkmcnt(3)
	s_setprio 0
	s_setprio 1
	v_mfma_f32_16x16x32_bf16 v[46:49], v[130:133], v[178:181], v[46:49]
	v_mfma_f32_16x16x32_bf16 v[46:49], v[134:137], v[182:185], v[46:49]
	s_waitcnt lgkmcnt(1)
	v_mfma_f32_16x16x32_bf16 v[38:41], v[130:133], v[186:189], v[38:41]
	v_mfma_f32_16x16x32_bf16 v[38:41], v[134:137], v[190:193], v[38:41]
	s_setprio 0
	s_setprio 1
	v_mfma_f32_16x16x32_bf16 v[58:61], v[138:141], v[162:165], v[58:61]
	v_mfma_f32_16x16x32_bf16 v[58:61], v[142:145], v[166:169], v[58:61]
	v_mfma_f32_16x16x32_bf16 v[50:53], v[138:141], v[170:173], v[50:53]
	v_mfma_f32_16x16x32_bf16 v[50:53], v[142:145], v[174:177], v[50:53]
	s_setprio 0
	s_setprio 1
	v_mfma_f32_16x16x32_bf16 v[42:45], v[138:141], v[178:181], v[42:45]
	v_mfma_f32_16x16x32_bf16 v[42:45], v[142:145], v[182:185], v[42:45]
	s_waitcnt lgkmcnt(0)
	v_mfma_f32_16x16x32_bf16 v[34:37], v[138:141], v[186:189], v[34:37]
	v_mfma_f32_16x16x32_bf16 v[34:37], v[142:145], v[190:193], v[34:37]
	s_setprio 0
	s_setprio 1
	v_mfma_f32_16x16x32_bf16 v[30:33], v[146:149], v[162:165], v[30:33]
	v_mfma_f32_16x16x32_bf16 v[30:33], v[150:153], v[166:169], v[30:33]
	v_mfma_f32_16x16x32_bf16 v[22:25], v[146:149], v[170:173], v[22:25]
	v_mfma_f32_16x16x32_bf16 v[22:25], v[150:153], v[174:177], v[22:25]
	s_setprio 0
	s_setprio 1
	v_mfma_f32_16x16x32_bf16 v[14:17], v[146:149], v[178:181], v[14:17]
	v_mfma_f32_16x16x32_bf16 v[14:17], v[150:153], v[182:185], v[14:17]
	v_mfma_f32_16x16x32_bf16 v[6:9], v[146:149], v[186:189], v[6:9]
	v_mfma_f32_16x16x32_bf16 v[6:9], v[150:153], v[190:193], v[6:9]
	s_setprio 0
	s_setprio 1
	v_mfma_f32_16x16x32_bf16 v[26:29], v[154:157], v[162:165], v[26:29]
	v_mfma_f32_16x16x32_bf16 v[26:29], v[158:161], v[166:169], v[26:29]
	v_mfma_f32_16x16x32_bf16 v[18:21], v[154:157], v[170:173], v[18:21]
	v_mfma_f32_16x16x32_bf16 v[18:21], v[158:161], v[174:177], v[18:21]
	s_setprio 0
	s_setprio 1
	v_mfma_f32_16x16x32_bf16 v[10:13], v[154:157], v[178:181], v[10:13]
	v_mfma_f32_16x16x32_bf16 v[10:13], v[158:161], v[182:185], v[10:13]
	s_setprio 2
	s_barrier
	v_mfma_f32_16x16x32_bf16 v[2:5], v[154:157], v[186:189], v[2:5]
	v_mfma_f32_16x16x32_bf16 v[2:5], v[158:161], v[190:193], v[2:5]
	s_setprio 0
	s_nop 0
	s_add_i32 s3, s71, 2
	s_cmp_gt_u32 s71, 13
	s_cbranch_scc1 .LBB0_639
	s_mov_b32 s71, s3
	s_branch .LBB0_616

.LBB0_1068:
	s_or_b64 exec, exec, s[62:63]
	s_add_u32 s88, s12, s0
	ds_read_b128 v[132:135], v214
	ds_read_b128 v[136:139], v214 offset:1024
	ds_read_b128 v[140:143], v214 offset:2048
	ds_read_b128 v[144:147], v214 offset:3072
	ds_read_b128 v[154:157], v215
	ds_read_b128 v[158:161], v215 offset:1024
	ds_read_b128 v[162:165], v215 offset:2048
	ds_read_b128 v[166:169], v215 offset:3072
	s_addc_u32 s89, s13, s1
	s_add_u32 s62, s88, 0x20000
	s_addc_u32 s63, s89, 0
	s_add_u32 s64, s94, s0
	s_addc_u32 s65, s96, s1
	s_cmp_eq_u32 s0, 0x60000
	s_cselect_b32 s68, s53, s62
	s_cselect_b32 s69, s33, s63
	s_cselect_b32 s63, s51, s65
	s_cselect_b32 s62, s95, s64
	s_add_u32 s64, s68, 0x8000
	s_addc_u32 s65, s69, 0
	s_add_u32 s66, s62, 0x8000
	s_addc_u32 s67, s63, 0
	ds_read_b128 v[170:173], v216
	ds_read_b128 v[174:177], v216 offset:1024
	ds_read_b128 v[178:181], v216 offset:2048
	ds_read_b128 v[182:185], v216 offset:3072
	ds_read_b128 v[186:189], v216 offset:4096
	ds_read_b128 v[190:193], v216 offset:5120
	ds_read_b128 v[198:201], v216 offset:6144
	ds_read_b128 v[202:205], v216 offset:7168
	s_add_u32 s88, s88, 0x1c000
	s_addc_u32 s89, s89, 0
	s_mov_b32 m0, s79
	s_nop 0
	global_load_lds_dwordx4 v195, s[88:89]
	s_add_u32 m0, s79, 0x2000
	s_nop 0
	global_load_lds_dwordx4 v212, s[88:89]
	s_waitcnt vmcnt(8)
	s_waitcnt lgkmcnt(0)
	s_setprio 1
	s_barrier
	v_mfma_f32_16x16x32_bf16 v[126:129], v[132:135], v[170:173], v[126:129]
	v_mfma_f32_16x16x32_bf16 v[126:129], v[136:139], v[174:177], v[126:129]
	s_waitcnt lgkmcnt(5)
	v_mfma_f32_16x16x32_bf16 v[110:113], v[132:135], v[178:181], v[110:113]
	v_mfma_f32_16x16x32_bf16 v[110:113], v[136:139], v[182:185], v[110:113]
	s_waitcnt lgkmcnt(3)
	s_setprio 0
	s_setprio 1
	v_mfma_f32_16x16x32_bf16 v[94:97], v[132:135], v[186:189], v[94:97]
	v_mfma_f32_16x16x32_bf16 v[94:97], v[136:139], v[190:193], v[94:97]
	s_waitcnt lgkmcnt(1)
	v_mfma_f32_16x16x32_bf16 v[78:81], v[132:135], v[198:201], v[78:81]
	v_mfma_f32_16x16x32_bf16 v[78:81], v[136:139], v[202:205], v[78:81]
	s_setprio 0
	s_setprio 1
	v_mfma_f32_16x16x32_bf16 v[122:125], v[140:143], v[170:173], v[122:125]
	v_mfma_f32_16x16x32_bf16 v[122:125], v[144:147], v[174:177], v[122:125]
	v_mfma_f32_16x16x32_bf16 v[106:109], v[140:143], v[178:181], v[106:109]
	v_mfma_f32_16x16x32_bf16 v[106:109], v[144:147], v[182:185], v[106:109]
	s_setprio 0
	s_setprio 1
	v_mfma_f32_16x16x32_bf16 v[90:93], v[140:143], v[186:189], v[90:93]
	v_mfma_f32_16x16x32_bf16 v[90:93], v[144:147], v[190:193], v[90:93]
	s_waitcnt lgkmcnt(0)
	v_mfma_f32_16x16x32_bf16 v[74:77], v[140:143], v[198:201], v[74:77]
	v_mfma_f32_16x16x32_bf16 v[74:77], v[144:147], v[202:205], v[74:77]
	s_setprio 0
	s_setprio 1
	v_mfma_f32_16x16x32_bf16 v[118:121], v[154:157], v[170:173], v[118:121]
	v_mfma_f32_16x16x32_bf16 v[118:121], v[158:161], v[174:177], v[118:121]
	v_mfma_f32_16x16x32_bf16 v[102:105], v[154:157], v[178:181], v[102:105]
	v_mfma_f32_16x16x32_bf16 v[102:105], v[158:161], v[182:185], v[102:105]
	s_setprio 0
	s_setprio 1
	v_mfma_f32_16x16x32_bf16 v[86:89], v[154:157], v[186:189], v[86:89]
	v_mfma_f32_16x16x32_bf16 v[86:89], v[158:161], v[190:193], v[86:89]
	v_mfma_f32_16x16x32_bf16 v[70:73], v[154:157], v[198:201], v[70:73]
	v_mfma_f32_16x16x32_bf16 v[70:73], v[158:161], v[202:205], v[70:73]
	s_setprio 0
	s_setprio 1
	v_mfma_f32_16x16x32_bf16 v[114:117], v[162:165], v[170:173], v[114:117]
	v_mfma_f32_16x16x32_bf16 v[114:117], v[166:169], v[174:177], v[114:117]
	v_mfma_f32_16x16x32_bf16 v[98:101], v[162:165], v[178:181], v[98:101]
	v_mfma_f32_16x16x32_bf16 v[98:101], v[166:169], v[182:185], v[98:101]
	s_setprio 0
	s_setprio 1
	v_mfma_f32_16x16x32_bf16 v[82:85], v[162:165], v[186:189], v[82:85]
	v_mfma_f32_16x16x32_bf16 v[82:85], v[166:169], v[190:193], v[82:85]
	s_setprio 2
	s_barrier
	v_mfma_f32_16x16x32_bf16 v[66:69], v[162:165], v[198:201], v[66:69]
	v_mfma_f32_16x16x32_bf16 v[66:69], v[166:169], v[202:205], v[66:69]
	s_setprio 0
	s_nop 0
	ds_read_b128 v[170:173], v216 offset:16384
	ds_read_b128 v[174:177], v216 offset:17408
	ds_read_b128 v[178:181], v216 offset:18432
	ds_read_b128 v[182:185], v216 offset:19456
	ds_read_b128 v[186:189], v216 offset:20480
	ds_read_b128 v[190:193], v216 offset:21504
	ds_read_b128 v[198:201], v216 offset:22528
	ds_read_b128 v[202:205], v216 offset:23552
	s_mov_b32 m0, s3
	s_nop 0
	global_load_lds_dwordx4 v195, s[62:63]
	s_add_u32 m0, s3, 0x2000
	s_nop 0
	global_load_lds_dwordx4 v212, s[62:63]
	s_add_u32 s88, s62, 0x4000
	s_addc_u32 s89, s63, 0
	s_mov_b32 m0, s71
	s_nop 0
	global_load_lds_dwordx4 v195, s[88:89]
	s_add_u32 m0, s71, 0x2000
	s_nop 0
	global_load_lds_dwordx4 v212, s[88:89]
	s_nop 0
	s_mov_b32 m0, s70
	s_nop 0
	global_load_lds_dwordx4 v195, s[68:69]
	s_add_u32 m0, s70, 0x2000
	s_nop 0
	global_load_lds_dwordx4 v212, s[68:69]
	s_waitcnt vmcnt(8)
	s_waitcnt lgkmcnt(0)
	s_setprio 1
	s_barrier
	v_mfma_f32_16x16x32_bf16 v[62:65], v[132:135], v[170:173], v[62:65]
	v_mfma_f32_16x16x32_bf16 v[62:65], v[136:139], v[174:177], v[62:65]
	s_waitcnt lgkmcnt(5)
	v_mfma_f32_16x16x32_bf16 v[46:49], v[132:135], v[178:181], v[46:49]
	v_mfma_f32_16x16x32_bf16 v[46:49], v[136:139], v[182:185], v[46:49]
	s_waitcnt lgkmcnt(3)
	s_setprio 0
	s_setprio 1
	v_mfma_f32_16x16x32_bf16 v[30:33], v[132:135], v[186:189], v[30:33]
	v_mfma_f32_16x16x32_bf16 v[30:33], v[136:139], v[190:193], v[30:33]
	s_waitcnt lgkmcnt(1)
	v_mfma_f32_16x16x32_bf16 v[14:17], v[132:135], v[198:201], v[14:17]
	v_mfma_f32_16x16x32_bf16 v[14:17], v[136:139], v[202:205], v[14:17]
	s_setprio 0
	s_setprio 1
	v_mfma_f32_16x16x32_bf16 v[58:61], v[140:143], v[170:173], v[58:61]
	v_mfma_f32_16x16x32_bf16 v[58:61], v[144:147], v[174:177], v[58:61]
	v_mfma_f32_16x16x32_bf16 v[42:45], v[140:143], v[178:181], v[42:45]
	v_mfma_f32_16x16x32_bf16 v[42:45], v[144:147], v[182:185], v[42:45]
	s_setprio 0
	s_setprio 1
	v_mfma_f32_16x16x32_bf16 v[26:29], v[140:143], v[186:189], v[26:29]
	v_mfma_f32_16x16x32_bf16 v[26:29], v[144:147], v[190:193], v[26:29]
	s_waitcnt lgkmcnt(0)
	v_mfma_f32_16x16x32_bf16 v[10:13], v[140:143], v[198:201], v[10:13]
	v_mfma_f32_16x16x32_bf16 v[10:13], v[144:147], v[202:205], v[10:13]
	s_setprio 0
	s_setprio 1
	v_mfma_f32_16x16x32_bf16 v[54:57], v[154:157], v[170:173], v[54:57]
	v_mfma_f32_16x16x32_bf16 v[54:57], v[158:161], v[174:177], v[54:57]
	v_mfma_f32_16x16x32_bf16 v[38:41], v[154:157], v[178:181], v[38:41]
	v_mfma_f32_16x16x32_bf16 v[38:41], v[158:161], v[182:185], v[38:41]
	s_setprio 0
	s_setprio 1
	v_mfma_f32_16x16x32_bf16 v[22:25], v[154:157], v[186:189], v[22:25]
	v_mfma_f32_16x16x32_bf16 v[22:25], v[158:161], v[190:193], v[22:25]
	v_mfma_f32_16x16x32_bf16 v[6:9], v[154:157], v[198:201], v[6:9]
	v_mfma_f32_16x16x32_bf16 v[6:9], v[158:161], v[202:205], v[6:9]
	s_setprio 0
	s_setprio 1
	v_mfma_f32_16x16x32_bf16 v[50:53], v[162:165], v[170:173], v[50:53]
	v_mfma_f32_16x16x32_bf16 v[50:53], v[166:169], v[174:177], v[50:53]
	v_mfma_f32_16x16x32_bf16 v[34:37], v[162:165], v[178:181], v[34:37]
	v_mfma_f32_16x16x32_bf16 v[34:37], v[166:169], v[182:185], v[34:37]
	s_setprio 0
	s_setprio 1
	v_mfma_f32_16x16x32_bf16 v[18:21], v[162:165], v[186:189], v[18:21]
	v_mfma_f32_16x16x32_bf16 v[18:21], v[166:169], v[190:193], v[18:21]
	s_setprio 2
	s_barrier
	v_mfma_f32_16x16x32_bf16 v[2:5], v[162:165], v[198:201], v[2:5]
	v_mfma_f32_16x16x32_bf16 v[2:5], v[166:169], v[202:205], v[2:5]
	s_setprio 0
	s_nop 0
	ds_read_b128 v[132:135], v217
	ds_read_b128 v[136:139], v217 offset:1024
	ds_read_b128 v[140:143], v217 offset:2048
	ds_read_b128 v[144:147], v217 offset:3072
	ds_read_b128 v[154:157], v218
	ds_read_b128 v[158:161], v218 offset:1024
	ds_read_b128 v[162:165], v218 offset:2048
	ds_read_b128 v[166:169], v218 offset:3072
	ds_read_b128 v[170:173], v216 offset:32768
	ds_read_b128 v[174:177], v216 offset:33792
	ds_read_b128 v[178:181], v216 offset:34816
	ds_read_b128 v[182:185], v216 offset:35840
	ds_read_b128 v[186:189], v216 offset:36864
	ds_read_b128 v[190:193], v216 offset:37888
	ds_read_b128 v[198:201], v216 offset:38912
	ds_read_b128 v[202:205], v216 offset:39936
	s_add_u32 s68, s68, 0x4000
	s_addc_u32 s69, s69, 0
	s_mov_b32 m0, s72
	s_nop 0
	global_load_lds_dwordx4 v195, s[68:69]
	s_add_u32 m0, s72, 0x2000
	s_nop 0
	global_load_lds_dwordx4 v212, s[68:69]
	s_waitcnt vmcnt(8)
	s_waitcnt lgkmcnt(0)
	s_setprio 1
	s_barrier
	v_mfma_f32_16x16x32_bf16 v[126:129], v[132:135], v[170:173], v[126:129]
	v_mfma_f32_16x16x32_bf16 v[126:129], v[136:139], v[174:177], v[126:129]
	s_waitcnt lgkmcnt(5)
	v_mfma_f32_16x16x32_bf16 v[110:113], v[132:135], v[178:181], v[110:113]
	v_mfma_f32_16x16x32_bf16 v[110:113], v[136:139], v[182:185], v[110:113]
	s_waitcnt lgkmcnt(3)
	s_setprio 0
	s_setprio 1
	v_mfma_f32_16x16x32_bf16 v[94:97], v[132:135], v[186:189], v[94:97]
	v_mfma_f32_16x16x32_bf16 v[94:97], v[136:139], v[190:193], v[94:97]
	s_waitcnt lgkmcnt(1)
	v_mfma_f32_16x16x32_bf16 v[78:81], v[132:135], v[198:201], v[78:81]
	v_mfma_f32_16x16x32_bf16 v[78:81], v[136:139], v[202:205], v[78:81]
	s_setprio 0
	s_setprio 1
	v_mfma_f32_16x16x32_bf16 v[122:125], v[140:143], v[170:173], v[122:125]
	v_mfma_f32_16x16x32_bf16 v[122:125], v[144:147], v[174:177], v[122:125]
	v_mfma_f32_16x16x32_bf16 v[106:109], v[140:143], v[178:181], v[106:109]
	v_mfma_f32_16x16x32_bf16 v[106:109], v[144:147], v[182:185], v[106:109]
	s_setprio 0
	s_setprio 1
	v_mfma_f32_16x16x32_bf16 v[90:93], v[140:143], v[186:189], v[90:93]
	v_mfma_f32_16x16x32_bf16 v[90:93], v[144:147], v[190:193], v[90:93]
	s_waitcnt lgkmcnt(0)
	v_mfma_f32_16x16x32_bf16 v[74:77], v[140:143], v[198:201], v[74:77]
	v_mfma_f32_16x16x32_bf16 v[74:77], v[144:147], v[202:205], v[74:77]
	s_setprio 0
	s_setprio 1
	v_mfma_f32_16x16x32_bf16 v[118:121], v[154:157], v[170:173], v[118:121]
	v_mfma_f32_16x16x32_bf16 v[118:121], v[158:161], v[174:177], v[118:121]
	v_mfma_f32_16x16x32_bf16 v[102:105], v[154:157], v[178:181], v[102:105]
	v_mfma_f32_16x16x32_bf16 v[102:105], v[158:161], v[182:185], v[102:105]
	s_setprio 0
	s_setprio 1
	v_mfma_f32_16x16x32_bf16 v[86:89], v[154:157], v[186:189], v[86:89]
	v_mfma_f32_16x16x32_bf16 v[86:89], v[158:161], v[190:193], v[86:89]
	v_mfma_f32_16x16x32_bf16 v[70:73], v[154:157], v[198:201], v[70:73]
	v_mfma_f32_16x16x32_bf16 v[70:73], v[158:161], v[202:205], v[70:73]
	s_setprio 0
	s_setprio 1
	v_mfma_f32_16x16x32_bf16 v[114:117], v[162:165], v[170:173], v[114:117]
	v_mfma_f32_16x16x32_bf16 v[114:117], v[166:169], v[174:177], v[114:117]
	v_mfma_f32_16x16x32_bf16 v[98:101], v[162:165], v[178:181], v[98:101]
	v_mfma_f32_16x16x32_bf16 v[98:101], v[166:169], v[182:185], v[98:101]
	s_setprio 0
	s_setprio 1
	v_mfma_f32_16x16x32_bf16 v[82:85], v[162:165], v[186:189], v[82:85]
	v_mfma_f32_16x16x32_bf16 v[82:85], v[166:169], v[190:193], v[82:85]
	s_setprio 2
	s_barrier
	v_mfma_f32_16x16x32_bf16 v[66:69], v[162:165], v[198:201], v[66:69]
	v_mfma_f32_16x16x32_bf16 v[66:69], v[166:169], v[202:205], v[66:69]
	s_setprio 0
	s_nop 0
	ds_read_b128 v[170:173], v216 offset:49152
	ds_read_b128 v[174:177], v216 offset:50176
	ds_read_b128 v[178:181], v216 offset:51200
	ds_read_b128 v[182:185], v216 offset:52224
	ds_read_b128 v[186:189], v216 offset:53248
	ds_read_b128 v[190:193], v216 offset:54272
	ds_read_b128 v[198:201], v216 offset:55296
	ds_read_b128 v[202:205], v216 offset:56320
	s_mov_b32 m0, s76
	s_nop 0
	global_load_lds_dwordx4 v195, s[66:67]
	s_add_u32 m0, s76, 0x2000
	s_nop 0
	global_load_lds_dwordx4 v212, s[66:67]
	s_add_u32 s62, s62, 0xc000
	s_addc_u32 s63, s63, 0
	s_mov_b32 m0, s78
	s_nop 0
	global_load_lds_dwordx4 v195, s[62:63]
	s_add_u32 m0, s78, 0x2000
	s_nop 0
	global_load_lds_dwordx4 v212, s[62:63]
	s_nop 0
	s_mov_b32 m0, s77
	s_nop 0
	global_load_lds_dwordx4 v195, s[64:65]
	s_add_u32 m0, s77, 0x2000
	s_nop 0
	global_load_lds_dwordx4 v212, s[64:65]
	s_waitcnt vmcnt(8)
	s_waitcnt lgkmcnt(0)
	s_setprio 1
	s_barrier
	v_mfma_f32_16x16x32_bf16 v[62:65], v[132:135], v[170:173], v[62:65]
	v_mfma_f32_16x16x32_bf16 v[62:65], v[136:139], v[174:177], v[62:65]
	s_waitcnt lgkmcnt(5)
	v_mfma_f32_16x16x32_bf16 v[46:49], v[132:135], v[178:181], v[46:49]
	v_mfma_f32_16x16x32_bf16 v[46:49], v[136:139], v[182:185], v[46:49]
	s_waitcnt lgkmcnt(3)
	s_setprio 0
	s_setprio 1
	v_mfma_f32_16x16x32_bf16 v[30:33], v[132:135], v[186:189], v[30:33]
	v_mfma_f32_16x16x32_bf16 v[30:33], v[136:139], v[190:193], v[30:33]
	s_waitcnt lgkmcnt(1)
	v_mfma_f32_16x16x32_bf16 v[14:17], v[132:135], v[198:201], v[14:17]
	v_mfma_f32_16x16x32_bf16 v[14:17], v[136:139], v[202:205], v[14:17]
	s_setprio 0
	s_setprio 1
	v_mfma_f32_16x16x32_bf16 v[58:61], v[140:143], v[170:173], v[58:61]
	v_mfma_f32_16x16x32_bf16 v[58:61], v[144:147], v[174:177], v[58:61]
	v_mfma_f32_16x16x32_bf16 v[42:45], v[140:143], v[178:181], v[42:45]
	v_mfma_f32_16x16x32_bf16 v[42:45], v[144:147], v[182:185], v[42:45]
	s_setprio 0
	s_setprio 1
	v_mfma_f32_16x16x32_bf16 v[26:29], v[140:143], v[186:189], v[26:29]
	v_mfma_f32_16x16x32_bf16 v[26:29], v[144:147], v[190:193], v[26:29]
	s_waitcnt lgkmcnt(0)
	v_mfma_f32_16x16x32_bf16 v[10:13], v[140:143], v[198:201], v[10:13]
	v_mfma_f32_16x16x32_bf16 v[10:13], v[144:147], v[202:205], v[10:13]
	s_setprio 0
	s_setprio 1
	v_mfma_f32_16x16x32_bf16 v[54:57], v[154:157], v[170:173], v[54:57]
	v_mfma_f32_16x16x32_bf16 v[54:57], v[158:161], v[174:177], v[54:57]
	v_mfma_f32_16x16x32_bf16 v[38:41], v[154:157], v[178:181], v[38:41]
	v_mfma_f32_16x16x32_bf16 v[38:41], v[158:161], v[182:185], v[38:41]
	s_setprio 0
	s_setprio 1
	v_mfma_f32_16x16x32_bf16 v[22:25], v[154:157], v[186:189], v[22:25]
	v_mfma_f32_16x16x32_bf16 v[22:25], v[158:161], v[190:193], v[22:25]
	v_mfma_f32_16x16x32_bf16 v[6:9], v[154:157], v[198:201], v[6:9]
	v_mfma_f32_16x16x32_bf16 v[6:9], v[158:161], v[202:205], v[6:9]
	s_setprio 0
	s_setprio 1
	v_mfma_f32_16x16x32_bf16 v[50:53], v[162:165], v[170:173], v[50:53]
	v_mfma_f32_16x16x32_bf16 v[50:53], v[166:169], v[174:177], v[50:53]
	v_mfma_f32_16x16x32_bf16 v[34:37], v[162:165], v[178:181], v[34:37]
	v_mfma_f32_16x16x32_bf16 v[34:37], v[166:169], v[182:185], v[34:37]
	s_setprio 0
	s_setprio 1
	v_mfma_f32_16x16x32_bf16 v[18:21], v[162:165], v[186:189], v[18:21]
	v_mfma_f32_16x16x32_bf16 v[18:21], v[166:169], v[190:193], v[18:21]
	s_setprio 2
	s_barrier
	v_mfma_f32_16x16x32_bf16 v[2:5], v[162:165], v[198:201], v[2:5]
	v_mfma_f32_16x16x32_bf16 v[2:5], v[166:169], v[202:205], v[2:5]
	s_setprio 0
	s_nop 0
	s_add_i32 s97, s97, 2
	s_add_u32 s0, s0, 0x10000
	s_addc_u32 s1, s1, 0
	s_cmp_gt_u32 s97, 13
	s_cbranch_scc1 .LBB0_1070
	v_mov_b32_e32 v131, v130
	s_branch .LBB0_1066

.LBB0_1336:
	s_add_u32 s50, s46, 0x10000
	s_addc_u32 s51, s47, 0
	s_and_b64 s[46:47], s[42:43], exec
	s_cselect_b32 s47, s51, s23
	s_cselect_b32 s46, s50, s75
	s_add_u32 s13, s16, s13
	s_addc_u32 s50, s17, 0
	s_add_u32 s13, s13, 0x10000
	s_waitcnt vmcnt(8)
	s_addc_u32 s50, s50, 0
	s_waitcnt lgkmcnt(0)
	s_and_b64 s[42:43], s[42:43], exec
	s_cselect_b32 s43, s50, s25
	s_cselect_b32 s42, s13, s76
	s_setprio 1
	s_barrier
	v_mfma_f32_16x16x32_bf16 v[126:129], v[146:149], v[186:189], v[126:129]
	v_mfma_f32_16x16x32_bf16 v[126:129], v[150:153], v[190:193], v[126:129]
	s_waitcnt lgkmcnt(5)
	v_mfma_f32_16x16x32_bf16 v[118:121], v[146:149], v[178:181], v[118:121]
	v_mfma_f32_16x16x32_bf16 v[118:121], v[150:153], v[182:185], v[118:121]
	s_waitcnt lgkmcnt(3)
	s_setprio 0
	s_setprio 1
	v_mfma_f32_16x16x32_bf16 v[110:113], v[146:149], v[170:173], v[110:113]
	v_mfma_f32_16x16x32_bf16 v[110:113], v[150:153], v[174:177], v[110:113]
	s_waitcnt lgkmcnt(1)
	v_mfma_f32_16x16x32_bf16 v[102:105], v[146:149], v[162:165], v[102:105]
	v_mfma_f32_16x16x32_bf16 v[102:105], v[150:153], v[166:169], v[102:105]
	s_setprio 0
	s_setprio 1
	v_mfma_f32_16x16x32_bf16 v[122:125], v[154:157], v[186:189], v[122:125]
	v_mfma_f32_16x16x32_bf16 v[122:125], v[158:161], v[190:193], v[122:125]
	v_mfma_f32_16x16x32_bf16 v[114:117], v[154:157], v[178:181], v[114:117]
	v_mfma_f32_16x16x32_bf16 v[114:117], v[158:161], v[182:185], v[114:117]
	s_setprio 0
	s_setprio 1
	v_mfma_f32_16x16x32_bf16 v[106:109], v[154:157], v[170:173], v[106:109]
	v_mfma_f32_16x16x32_bf16 v[106:109], v[158:161], v[174:177], v[106:109]
	s_waitcnt lgkmcnt(0)
	v_mfma_f32_16x16x32_bf16 v[98:101], v[154:157], v[162:165], v[98:101]
	v_mfma_f32_16x16x32_bf16 v[98:101], v[158:161], v[166:169], v[98:101]
	s_setprio 0
	s_setprio 1
	v_mfma_f32_16x16x32_bf16 v[94:97], v[130:133], v[186:189], v[94:97]
	v_mfma_f32_16x16x32_bf16 v[94:97], v[134:137], v[190:193], v[94:97]
	v_mfma_f32_16x16x32_bf16 v[86:89], v[130:133], v[178:181], v[86:89]
	v_mfma_f32_16x16x32_bf16 v[86:89], v[134:137], v[182:185], v[86:89]
	s_setprio 0
	s_setprio 1
	v_mfma_f32_16x16x32_bf16 v[78:81], v[130:133], v[170:173], v[78:81]
	v_mfma_f32_16x16x32_bf16 v[78:81], v[134:137], v[174:177], v[78:81]
	v_mfma_f32_16x16x32_bf16 v[70:73], v[130:133], v[162:165], v[70:73]
	v_mfma_f32_16x16x32_bf16 v[70:73], v[134:137], v[166:169], v[70:73]
	s_setprio 0
	s_setprio 1
	v_mfma_f32_16x16x32_bf16 v[90:93], v[138:141], v[186:189], v[90:93]
	v_mfma_f32_16x16x32_bf16 v[90:93], v[142:145], v[190:193], v[90:93]
	v_mfma_f32_16x16x32_bf16 v[82:85], v[138:141], v[178:181], v[82:85]
	v_mfma_f32_16x16x32_bf16 v[82:85], v[142:145], v[182:185], v[82:85]
	s_setprio 0
	s_setprio 1
	v_mfma_f32_16x16x32_bf16 v[74:77], v[138:141], v[170:173], v[74:77]
	v_mfma_f32_16x16x32_bf16 v[74:77], v[142:145], v[174:177], v[74:77]
	s_setprio 2
	s_barrier
	v_mfma_f32_16x16x32_bf16 v[66:69], v[138:141], v[162:165], v[66:69]
	v_mfma_f32_16x16x32_bf16 v[66:69], v[142:145], v[166:169], v[66:69]
	s_setprio 0
	s_nop 0
	ds_read_b128 v[186:189], v208 offset:16384
	ds_read_b128 v[190:193], v208 offset:17408
	ds_read_b128 v[178:181], v208 offset:18432
	ds_read_b128 v[182:185], v208 offset:19456
	ds_read_b128 v[170:173], v208 offset:20480
	ds_read_b128 v[174:177], v208 offset:21504
	ds_read_b128 v[162:165], v208 offset:22528
	ds_read_b128 v[166:169], v208 offset:23552
	s_mov_b32 m0, s58
	s_nop 0
	global_load_lds_dwordx4 v202, s[42:43]
	s_add_u32 m0, s58, 0x2000
	s_nop 0
	global_load_lds_dwordx4 v203, s[42:43]
	s_add_u32 s50, s42, 0x4000
	s_addc_u32 s51, s43, 0
	s_mov_b32 m0, s59
	s_nop 0
	global_load_lds_dwordx4 v202, s[50:51]
	s_add_u32 m0, s59, 0x2000
	s_nop 0
	global_load_lds_dwordx4 v203, s[50:51]
	s_andn2_b64 vcc, exec, s[48:49]
	s_mov_b32 m0, s7
	s_nop 0
	global_load_lds_dwordx4 v202, s[46:47]
	s_add_u32 m0, s7, 0x2000
	s_nop 0
	global_load_lds_dwordx4 v203, s[46:47]
	s_cbranch_vccnz .LBB0_1338
	v_mov_b32_e32 v2, 0
	v_mov_b32_e32 v3, v2
	v_mov_b32_e32 v4, v2
	v_mov_b32_e32 v5, v2
	v_mov_b32_e32 v6, v2
	v_mov_b32_e32 v7, v2
	v_mov_b32_e32 v8, v2
	v_mov_b32_e32 v9, v2
	v_mov_b32_e32 v10, v2
	v_mov_b32_e32 v11, v2
	v_mov_b32_e32 v12, v2
	v_mov_b32_e32 v13, v2
	v_mov_b32_e32 v14, v2
	v_mov_b32_e32 v15, v2
	v_mov_b32_e32 v16, v2
	v_mov_b32_e32 v17, v2
	v_mov_b32_e32 v18, v2
	v_mov_b32_e32 v19, v2
	v_mov_b32_e32 v20, v2
	v_mov_b32_e32 v21, v2
	v_mov_b32_e32 v22, v2
	v_mov_b32_e32 v23, v2
	v_mov_b32_e32 v24, v2
	v_mov_b32_e32 v25, v2
	v_mov_b32_e32 v26, v2
	v_mov_b32_e32 v27, v2
	v_mov_b32_e32 v28, v2
	v_mov_b32_e32 v29, v2
	v_mov_b32_e32 v30, v2
	v_mov_b32_e32 v31, v2
	v_mov_b32_e32 v32, v2
	v_mov_b32_e32 v33, v2
	v_mov_b32_e32 v34, v2
	v_mov_b32_e32 v35, v2
	v_mov_b32_e32 v36, v2
	v_mov_b32_e32 v37, v2
	v_mov_b32_e32 v38, v2
	v_mov_b32_e32 v39, v2
	v_mov_b32_e32 v40, v2
	v_mov_b32_e32 v41, v2
	v_mov_b32_e32 v42, v2
	v_mov_b32_e32 v43, v2
	v_mov_b32_e32 v44, v2
	v_mov_b32_e32 v45, v2
	v_mov_b32_e32 v46, v2
	v_mov_b32_e32 v47, v2
	v_mov_b32_e32 v48, v2
	v_mov_b32_e32 v49, v2
	v_mov_b32_e32 v50, v2
	v_mov_b32_e32 v51, v2
	v_mov_b32_e32 v52, v2
	v_mov_b32_e32 v53, v2
	v_mov_b32_e32 v54, v2
	v_mov_b32_e32 v55, v2
	v_mov_b32_e32 v56, v2
	v_mov_b32_e32 v57, v2
	v_mov_b32_e32 v58, v2
	v_mov_b32_e32 v59, v2
	v_mov_b32_e32 v60, v2
	v_mov_b32_e32 v61, v2
	v_mov_b32_e32 v62, v2
	v_mov_b32_e32 v63, v2
	v_mov_b32_e32 v64, v2
	v_mov_b32_e32 v65, v2
.LBB0_1338:
	s_waitcnt vmcnt(8)
	s_add_u32 s48, s46, 0x8000
	s_waitcnt lgkmcnt(0)
	s_addc_u32 s49, s47, 0
	s_add_u32 s50, s42, 0x8000
	s_addc_u32 s51, s43, 0
	s_setprio 1
	s_barrier
	v_mfma_f32_16x16x32_bf16 v[62:65], v[146:149], v[186:189], v[62:65]
	v_mfma_f32_16x16x32_bf16 v[62:65], v[150:153], v[190:193], v[62:65]
	s_waitcnt lgkmcnt(5)
	v_mfma_f32_16x16x32_bf16 v[54:57], v[146:149], v[178:181], v[54:57]
	v_mfma_f32_16x16x32_bf16 v[54:57], v[150:153], v[182:185], v[54:57]
	s_waitcnt lgkmcnt(3)
	s_setprio 0
	s_setprio 1
	v_mfma_f32_16x16x32_bf16 v[46:49], v[146:149], v[170:173], v[46:49]
	v_mfma_f32_16x16x32_bf16 v[46:49], v[150:153], v[174:177], v[46:49]
	s_waitcnt lgkmcnt(1)
	v_mfma_f32_16x16x32_bf16 v[38:41], v[146:149], v[162:165], v[38:41]
	v_mfma_f32_16x16x32_bf16 v[38:41], v[150:153], v[166:169], v[38:41]
	s_setprio 0
	s_setprio 1
	v_mfma_f32_16x16x32_bf16 v[58:61], v[154:157], v[186:189], v[58:61]
	v_mfma_f32_16x16x32_bf16 v[58:61], v[158:161], v[190:193], v[58:61]
	v_mfma_f32_16x16x32_bf16 v[50:53], v[154:157], v[178:181], v[50:53]
	v_mfma_f32_16x16x32_bf16 v[50:53], v[158:161], v[182:185], v[50:53]
	s_setprio 0
	s_setprio 1
	v_mfma_f32_16x16x32_bf16 v[42:45], v[154:157], v[170:173], v[42:45]
	v_mfma_f32_16x16x32_bf16 v[42:45], v[158:161], v[174:177], v[42:45]
	s_waitcnt lgkmcnt(0)
	v_mfma_f32_16x16x32_bf16 v[34:37], v[154:157], v[162:165], v[34:37]
	v_mfma_f32_16x16x32_bf16 v[34:37], v[158:161], v[166:169], v[34:37]
	s_setprio 0
	s_setprio 1
	v_mfma_f32_16x16x32_bf16 v[30:33], v[130:133], v[186:189], v[30:33]
	v_mfma_f32_16x16x32_bf16 v[30:33], v[134:137], v[190:193], v[30:33]
	v_mfma_f32_16x16x32_bf16 v[22:25], v[130:133], v[178:181], v[22:25]
	v_mfma_f32_16x16x32_bf16 v[22:25], v[134:137], v[182:185], v[22:25]
	s_setprio 0
	s_setprio 1
	v_mfma_f32_16x16x32_bf16 v[14:17], v[130:133], v[170:173], v[14:17]
	v_mfma_f32_16x16x32_bf16 v[14:17], v[134:137], v[174:177], v[14:17]
	v_mfma_f32_16x16x32_bf16 v[6:9], v[130:133], v[162:165], v[6:9]
	v_mfma_f32_16x16x32_bf16 v[6:9], v[134:137], v[166:169], v[6:9]
	s_setprio 0
	s_setprio 1
	v_mfma_f32_16x16x32_bf16 v[26:29], v[138:141], v[186:189], v[26:29]
	v_mfma_f32_16x16x32_bf16 v[26:29], v[142:145], v[190:193], v[26:29]
	v_mfma_f32_16x16x32_bf16 v[18:21], v[138:141], v[178:181], v[18:21]
	v_mfma_f32_16x16x32_bf16 v[18:21], v[142:145], v[182:185], v[18:21]
	s_setprio 0
	s_setprio 1
	v_mfma_f32_16x16x32_bf16 v[10:13], v[138:141], v[170:173], v[10:13]
	v_mfma_f32_16x16x32_bf16 v[10:13], v[142:145], v[174:177], v[10:13]
	s_setprio 2
	s_barrier
	v_mfma_f32_16x16x32_bf16 v[2:5], v[138:141], v[162:165], v[2:5]
	v_mfma_f32_16x16x32_bf16 v[2:5], v[142:145], v[166:169], v[2:5]
	s_setprio 0
	s_nop 0
	v_add_u32_e32 v142, 0x18000, v207
	v_add_u32_e32 v158, 0x1c000, v207
	ds_read_b128 v[130:133], v142
	ds_read_b128 v[134:137], v142 offset:1024
	ds_read_b128 v[138:141], v142 offset:2048
	ds_read_b128 v[142:145], v142 offset:3072
	ds_read_b128 v[146:149], v158
	ds_read_b128 v[150:153], v158 offset:1024
	ds_read_b128 v[154:157], v158 offset:2048
	ds_read_b128 v[158:161], v158 offset:3072
	ds_read_b128 v[162:165], v208 offset:32768
	ds_read_b128 v[166:169], v208 offset:33792
	ds_read_b128 v[170:173], v208 offset:34816
	ds_read_b128 v[174:177], v208 offset:35840
	ds_read_b128 v[178:181], v208 offset:36864
	ds_read_b128 v[182:185], v208 offset:37888
	ds_read_b128 v[186:189], v208 offset:38912
	ds_read_b128 v[190:193], v208 offset:39936
	s_add_u32 s46, s46, 0x4000
	s_addc_u32 s47, s47, 0
	s_mov_b32 m0, s60
	s_nop 0
	global_load_lds_dwordx4 v202, s[46:47]
	s_add_u32 m0, s60, 0x2000
	s_nop 0
	global_load_lds_dwordx4 v203, s[46:47]
	s_waitcnt vmcnt(8)
	s_waitcnt lgkmcnt(0)
	s_setprio 1
	s_barrier
	v_mfma_f32_16x16x32_bf16 v[126:129], v[130:133], v[162:165], v[126:129]
	v_mfma_f32_16x16x32_bf16 v[126:129], v[134:137], v[166:169], v[126:129]
	s_waitcnt lgkmcnt(5)
	v_mfma_f32_16x16x32_bf16 v[118:121], v[130:133], v[170:173], v[118:121]
	v_mfma_f32_16x16x32_bf16 v[118:121], v[134:137], v[174:177], v[118:121]
	s_waitcnt lgkmcnt(3)
	s_setprio 0
	s_setprio 1
	v_mfma_f32_16x16x32_bf16 v[110:113], v[130:133], v[178:181], v[110:113]
	v_mfma_f32_16x16x32_bf16 v[110:113], v[134:137], v[182:185], v[110:113]
	s_waitcnt lgkmcnt(1)
	v_mfma_f32_16x16x32_bf16 v[102:105], v[130:133], v[186:189], v[102:105]
	v_mfma_f32_16x16x32_bf16 v[102:105], v[134:137], v[190:193], v[102:105]
	s_setprio 0
	s_setprio 1
	v_mfma_f32_16x16x32_bf16 v[122:125], v[138:141], v[162:165], v[122:125]
	v_mfma_f32_16x16x32_bf16 v[122:125], v[142:145], v[166:169], v[122:125]
	v_mfma_f32_16x16x32_bf16 v[114:117], v[138:141], v[170:173], v[114:117]
	v_mfma_f32_16x16x32_bf16 v[114:117], v[142:145], v[174:177], v[114:117]
	s_setprio 0
	s_setprio 1
	v_mfma_f32_16x16x32_bf16 v[106:109], v[138:141], v[178:181], v[106:109]
	v_mfma_f32_16x16x32_bf16 v[106:109], v[142:145], v[182:185], v[106:109]
	s_waitcnt lgkmcnt(0)
	v_mfma_f32_16x16x32_bf16 v[98:101], v[138:141], v[186:189], v[98:101]
	v_mfma_f32_16x16x32_bf16 v[98:101], v[142:145], v[190:193], v[98:101]
	s_setprio 0
	s_setprio 1
	v_mfma_f32_16x16x32_bf16 v[94:97], v[146:149], v[162:165], v[94:97]
	v_mfma_f32_16x16x32_bf16 v[94:97], v[150:153], v[166:169], v[94:97]
	v_mfma_f32_16x16x32_bf16 v[86:89], v[146:149], v[170:173], v[86:89]
	v_mfma_f32_16x16x32_bf16 v[86:89], v[150:153], v[174:177], v[86:89]
	s_setprio 0
	s_setprio 1
	v_mfma_f32_16x16x32_bf16 v[78:81], v[146:149], v[178:181], v[78:81]
	v_mfma_f32_16x16x32_bf16 v[78:81], v[150:153], v[182:185], v[78:81]
	v_mfma_f32_16x16x32_bf16 v[70:73], v[146:149], v[186:189], v[70:73]
	v_mfma_f32_16x16x32_bf16 v[70:73], v[150:153], v[190:193], v[70:73]
	s_setprio 0
	s_setprio 1
	v_mfma_f32_16x16x32_bf16 v[90:93], v[154:157], v[162:165], v[90:93]
	v_mfma_f32_16x16x32_bf16 v[90:93], v[158:161], v[166:169], v[90:93]
	v_mfma_f32_16x16x32_bf16 v[82:85], v[154:157], v[170:173], v[82:85]
	v_mfma_f32_16x16x32_bf16 v[82:85], v[158:161], v[174:177], v[82:85]
	s_setprio 0
	s_setprio 1
	v_mfma_f32_16x16x32_bf16 v[74:77], v[154:157], v[178:181], v[74:77]
	v_mfma_f32_16x16x32_bf16 v[74:77], v[158:161], v[182:185], v[74:77]
	s_setprio 2
	s_barrier
	v_mfma_f32_16x16x32_bf16 v[66:69], v[154:157], v[186:189], v[66:69]
	v_mfma_f32_16x16x32_bf16 v[66:69], v[158:161], v[190:193], v[66:69]
	s_setprio 0
	s_nop 0
	ds_read_b128 v[162:165], v208 offset:49152
	ds_read_b128 v[166:169], v208 offset:50176
	ds_read_b128 v[170:173], v208 offset:51200
	ds_read_b128 v[174:177], v208 offset:52224
	ds_read_b128 v[178:181], v208 offset:53248
	ds_read_b128 v[182:185], v208 offset:54272
	ds_read_b128 v[186:189], v208 offset:55296
	ds_read_b128 v[190:193], v208 offset:56320
	s_mov_b32 m0, s64
	s_nop 0
	global_load_lds_dwordx4 v202, s[50:51]
	s_add_u32 m0, s64, 0x2000
	s_nop 0
	global_load_lds_dwordx4 v203, s[50:51]
	s_add_u32 s42, s42, 0xc000
	s_addc_u32 s43, s43, 0
	s_mov_b32 m0, s66
	s_nop 0
	global_load_lds_dwordx4 v202, s[42:43]
	s_add_u32 m0, s66, 0x2000
	s_nop 0
	global_load_lds_dwordx4 v203, s[42:43]
	s_nop 0
	s_mov_b32 m0, s65
	s_nop 0
	global_load_lds_dwordx4 v202, s[48:49]
	s_add_u32 m0, s65, 0x2000
	s_nop 0
	global_load_lds_dwordx4 v203, s[48:49]
	s_waitcnt vmcnt(8)
	s_waitcnt lgkmcnt(0)
	s_setprio 1
	s_barrier
	v_mfma_f32_16x16x32_bf16 v[62:65], v[130:133], v[162:165], v[62:65]
	v_mfma_f32_16x16x32_bf16 v[62:65], v[134:137], v[166:169], v[62:65]
	s_waitcnt lgkmcnt(5)
	v_mfma_f32_16x16x32_bf16 v[54:57], v[130:133], v[170:173], v[54:57]
	v_mfma_f32_16x16x32_bf16 v[54:57], v[134:137], v[174:177], v[54:57]
	s_waitcnt lgkmcnt(3)
	s_setprio 0
	s_setprio 1
	v_mfma_f32_16x16x32_bf16 v[46:49], v[130:133], v[178:181], v[46:49]
	v_mfma_f32_16x16x32_bf16 v[46:49], v[134:137], v[182:185], v[46:49]
	s_waitcnt lgkmcnt(1)
	v_mfma_f32_16x16x32_bf16 v[38:41], v[130:133], v[186:189], v[38:41]
	v_mfma_f32_16x16x32_bf16 v[38:41], v[134:137], v[190:193], v[38:41]
	s_setprio 0
	s_setprio 1
	v_mfma_f32_16x16x32_bf16 v[58:61], v[138:141], v[162:165], v[58:61]
	v_mfma_f32_16x16x32_bf16 v[58:61], v[142:145], v[166:169], v[58:61]
	v_mfma_f32_16x16x32_bf16 v[50:53], v[138:141], v[170:173], v[50:53]
	v_mfma_f32_16x16x32_bf16 v[50:53], v[142:145], v[174:177], v[50:53]
	s_setprio 0
	s_setprio 1
	v_mfma_f32_16x16x32_bf16 v[42:45], v[138:141], v[178:181], v[42:45]
	v_mfma_f32_16x16x32_bf16 v[42:45], v[142:145], v[182:185], v[42:45]
	s_waitcnt lgkmcnt(0)
	v_mfma_f32_16x16x32_bf16 v[34:37], v[138:141], v[186:189], v[34:37]
	v_mfma_f32_16x16x32_bf16 v[34:37], v[142:145], v[190:193], v[34:37]
	s_setprio 0
	s_setprio 1
	v_mfma_f32_16x16x32_bf16 v[30:33], v[146:149], v[162:165], v[30:33]
	v_mfma_f32_16x16x32_bf16 v[30:33], v[150:153], v[166:169], v[30:33]
	v_mfma_f32_16x16x32_bf16 v[22:25], v[146:149], v[170:173], v[22:25]
	v_mfma_f32_16x16x32_bf16 v[22:25], v[150:153], v[174:177], v[22:25]
	s_setprio 0
	s_setprio 1
	v_mfma_f32_16x16x32_bf16 v[14:17], v[146:149], v[178:181], v[14:17]
	v_mfma_f32_16x16x32_bf16 v[14:17], v[150:153], v[182:185], v[14:17]
	v_mfma_f32_16x16x32_bf16 v[6:9], v[146:149], v[186:189], v[6:9]
	v_mfma_f32_16x16x32_bf16 v[6:9], v[150:153], v[190:193], v[6:9]
	s_setprio 0
	s_setprio 1
	v_mfma_f32_16x16x32_bf16 v[26:29], v[154:157], v[162:165], v[26:29]
	v_mfma_f32_16x16x32_bf16 v[26:29], v[158:161], v[166:169], v[26:29]
	v_mfma_f32_16x16x32_bf16 v[18:21], v[154:157], v[170:173], v[18:21]
	v_mfma_f32_16x16x32_bf16 v[18:21], v[158:161], v[174:177], v[18:21]
	s_setprio 0
	s_setprio 1
	v_mfma_f32_16x16x32_bf16 v[10:13], v[154:157], v[178:181], v[10:13]
	v_mfma_f32_16x16x32_bf16 v[10:13], v[158:161], v[182:185], v[10:13]
	s_setprio 2
	s_barrier
	v_mfma_f32_16x16x32_bf16 v[2:5], v[154:157], v[186:189], v[2:5]
	v_mfma_f32_16x16x32_bf16 v[2:5], v[158:161], v[190:193], v[2:5]
	s_setprio 0
	s_nop 0
	s_add_i32 s13, s77, 2
	s_cmp_gt_u32 s77, 5
	s_cbranch_scc1 .LBB0_1340
	s_mov_b32 s77, s13
	s_branch .LBB0_1317

.LBB0_1374:
	s_or_b64 exec, exec, s[40:41]
	s_add_u32 s76, s16, s6
	ds_read_b128 v[132:135], v168
	ds_read_b128 v[136:139], v168 offset:1024
	ds_read_b128 v[140:143], v168 offset:2048
	ds_read_b128 v[144:147], v168 offset:3072
	ds_read_b128 v[148:151], v169
	ds_read_b128 v[158:161], v169 offset:1024
	ds_read_b128 v[162:165], v169 offset:2048
	ds_read_b128 v[174:177], v169 offset:3072
	s_addc_u32 s77, s17, s7
	s_add_u32 s40, s76, 0x20000
	s_addc_u32 s41, s77, 0
	s_add_u32 s42, s71, s6
	s_addc_u32 s43, s72, s7
	s_cmp_eq_u32 s6, 0x20000
	s_cselect_b32 s48, s73, s40
	s_cselect_b32 s49, s27, s41
	s_cselect_b32 s41, s25, s43
	s_cselect_b32 s40, s74, s42
	s_add_u32 s42, s48, 0x8000
	s_addc_u32 s43, s49, 0
	s_add_u32 s46, s40, 0x8000
	s_addc_u32 s47, s41, 0
	ds_read_b128 v[178:181], v170
	ds_read_b128 v[182:185], v170 offset:1024
	ds_read_b128 v[186:189], v170 offset:2048
	ds_read_b128 v[190:193], v170 offset:3072
	ds_read_b128 v[198:201], v170 offset:4096
	ds_read_b128 v[204:207], v170 offset:5120
	ds_read_b128 v[212:215], v170 offset:6144
	ds_read_b128 v[216:219], v170 offset:7168
	s_add_u32 s76, s76, 0x1c000
	s_addc_u32 s77, s77, 0
	s_mov_b32 m0, s63
	s_nop 0
	global_load_lds_dwordx4 v202, s[76:77]
	s_add_u32 m0, s63, 0x2000
	s_nop 0
	global_load_lds_dwordx4 v203, s[76:77]
	s_waitcnt vmcnt(8)
	s_waitcnt lgkmcnt(0)
	s_setprio 1
	s_barrier
	v_mfma_f32_16x16x32_bf16 v[126:129], v[132:135], v[178:181], v[126:129]
	v_mfma_f32_16x16x32_bf16 v[126:129], v[136:139], v[182:185], v[126:129]
	s_waitcnt lgkmcnt(5)
	v_mfma_f32_16x16x32_bf16 v[110:113], v[132:135], v[186:189], v[110:113]
	v_mfma_f32_16x16x32_bf16 v[110:113], v[136:139], v[190:193], v[110:113]
	s_waitcnt lgkmcnt(3)
	s_setprio 0
	s_setprio 1
	v_mfma_f32_16x16x32_bf16 v[94:97], v[132:135], v[198:201], v[94:97]
	v_mfma_f32_16x16x32_bf16 v[94:97], v[136:139], v[204:207], v[94:97]
	s_waitcnt lgkmcnt(1)
	v_mfma_f32_16x16x32_bf16 v[78:81], v[132:135], v[212:215], v[78:81]
	v_mfma_f32_16x16x32_bf16 v[78:81], v[136:139], v[216:219], v[78:81]
	s_setprio 0
	s_setprio 1
	v_mfma_f32_16x16x32_bf16 v[122:125], v[140:143], v[178:181], v[122:125]
	v_mfma_f32_16x16x32_bf16 v[122:125], v[144:147], v[182:185], v[122:125]
	v_mfma_f32_16x16x32_bf16 v[106:109], v[140:143], v[186:189], v[106:109]
	v_mfma_f32_16x16x32_bf16 v[106:109], v[144:147], v[190:193], v[106:109]
	s_setprio 0
	s_setprio 1
	v_mfma_f32_16x16x32_bf16 v[90:93], v[140:143], v[198:201], v[90:93]
	v_mfma_f32_16x16x32_bf16 v[90:93], v[144:147], v[204:207], v[90:93]
	s_waitcnt lgkmcnt(0)
	v_mfma_f32_16x16x32_bf16 v[74:77], v[140:143], v[212:215], v[74:77]
	v_mfma_f32_16x16x32_bf16 v[74:77], v[144:147], v[216:219], v[74:77]
	s_setprio 0
	s_setprio 1
	v_mfma_f32_16x16x32_bf16 v[118:121], v[148:151], v[178:181], v[118:121]
	v_mfma_f32_16x16x32_bf16 v[118:121], v[158:161], v[182:185], v[118:121]
	v_mfma_f32_16x16x32_bf16 v[102:105], v[148:151], v[186:189], v[102:105]
	v_mfma_f32_16x16x32_bf16 v[102:105], v[158:161], v[190:193], v[102:105]
	s_setprio 0
	s_setprio 1
	v_mfma_f32_16x16x32_bf16 v[86:89], v[148:151], v[198:201], v[86:89]
	v_mfma_f32_16x16x32_bf16 v[86:89], v[158:161], v[204:207], v[86:89]
	v_mfma_f32_16x16x32_bf16 v[70:73], v[148:151], v[212:215], v[70:73]
	v_mfma_f32_16x16x32_bf16 v[70:73], v[158:161], v[216:219], v[70:73]
	s_setprio 0
	s_setprio 1
	v_mfma_f32_16x16x32_bf16 v[114:117], v[162:165], v[178:181], v[114:117]
	v_mfma_f32_16x16x32_bf16 v[114:117], v[174:177], v[182:185], v[114:117]
	v_mfma_f32_16x16x32_bf16 v[98:101], v[162:165], v[186:189], v[98:101]
	v_mfma_f32_16x16x32_bf16 v[98:101], v[174:177], v[190:193], v[98:101]
	s_setprio 0
	s_setprio 1
	v_mfma_f32_16x16x32_bf16 v[82:85], v[162:165], v[198:201], v[82:85]
	v_mfma_f32_16x16x32_bf16 v[82:85], v[174:177], v[204:207], v[82:85]
	s_setprio 2
	s_barrier
	v_mfma_f32_16x16x32_bf16 v[66:69], v[162:165], v[212:215], v[66:69]
	v_mfma_f32_16x16x32_bf16 v[66:69], v[174:177], v[216:219], v[66:69]
	s_setprio 0
	s_nop 0
	ds_read_b128 v[178:181], v170 offset:16384
	ds_read_b128 v[182:185], v170 offset:17408
	ds_read_b128 v[186:189], v170 offset:18432
	ds_read_b128 v[190:193], v170 offset:19456
	ds_read_b128 v[198:201], v170 offset:20480
	ds_read_b128 v[204:207], v170 offset:21504
	ds_read_b128 v[212:215], v170 offset:22528
	ds_read_b128 v[216:219], v170 offset:23552
	s_mov_b32 m0, s13
	s_nop 0
	global_load_lds_dwordx4 v202, s[40:41]
	s_add_u32 m0, s13, 0x2000
	s_nop 0
	global_load_lds_dwordx4 v203, s[40:41]
	s_add_u32 s76, s40, 0x4000
	s_addc_u32 s77, s41, 0
	s_mov_b32 m0, s55
	s_nop 0
	global_load_lds_dwordx4 v202, s[76:77]
	s_add_u32 m0, s55, 0x2000
	s_nop 0
	global_load_lds_dwordx4 v203, s[76:77]
	s_nop 0
	s_mov_b32 m0, s54
	s_nop 0
	global_load_lds_dwordx4 v202, s[48:49]
	s_add_u32 m0, s54, 0x2000
	s_nop 0
	global_load_lds_dwordx4 v203, s[48:49]
	s_waitcnt vmcnt(8)
	s_waitcnt lgkmcnt(0)
	s_setprio 1
	s_barrier
	v_mfma_f32_16x16x32_bf16 v[62:65], v[132:135], v[178:181], v[62:65]
	v_mfma_f32_16x16x32_bf16 v[62:65], v[136:139], v[182:185], v[62:65]
	s_waitcnt lgkmcnt(5)
	v_mfma_f32_16x16x32_bf16 v[46:49], v[132:135], v[186:189], v[46:49]
	v_mfma_f32_16x16x32_bf16 v[46:49], v[136:139], v[190:193], v[46:49]
	s_waitcnt lgkmcnt(3)
	s_setprio 0
	s_setprio 1
	v_mfma_f32_16x16x32_bf16 v[30:33], v[132:135], v[198:201], v[30:33]
	v_mfma_f32_16x16x32_bf16 v[30:33], v[136:139], v[204:207], v[30:33]
	s_waitcnt lgkmcnt(1)
	v_mfma_f32_16x16x32_bf16 v[14:17], v[132:135], v[212:215], v[14:17]
	v_mfma_f32_16x16x32_bf16 v[14:17], v[136:139], v[216:219], v[14:17]
	s_setprio 0
	s_setprio 1
	v_mfma_f32_16x16x32_bf16 v[58:61], v[140:143], v[178:181], v[58:61]
	v_mfma_f32_16x16x32_bf16 v[58:61], v[144:147], v[182:185], v[58:61]
	v_mfma_f32_16x16x32_bf16 v[42:45], v[140:143], v[186:189], v[42:45]
	v_mfma_f32_16x16x32_bf16 v[42:45], v[144:147], v[190:193], v[42:45]
	s_setprio 0
	s_setprio 1
	v_mfma_f32_16x16x32_bf16 v[26:29], v[140:143], v[198:201], v[26:29]
	v_mfma_f32_16x16x32_bf16 v[26:29], v[144:147], v[204:207], v[26:29]
	s_waitcnt lgkmcnt(0)
	v_mfma_f32_16x16x32_bf16 v[10:13], v[140:143], v[212:215], v[10:13]
	v_mfma_f32_16x16x32_bf16 v[10:13], v[144:147], v[216:219], v[10:13]
	s_setprio 0
	s_setprio 1
	v_mfma_f32_16x16x32_bf16 v[54:57], v[148:151], v[178:181], v[54:57]
	v_mfma_f32_16x16x32_bf16 v[54:57], v[158:161], v[182:185], v[54:57]
	v_mfma_f32_16x16x32_bf16 v[38:41], v[148:151], v[186:189], v[38:41]
	v_mfma_f32_16x16x32_bf16 v[38:41], v[158:161], v[190:193], v[38:41]
	s_setprio 0
	s_setprio 1
	v_mfma_f32_16x16x32_bf16 v[22:25], v[148:151], v[198:201], v[22:25]
	v_mfma_f32_16x16x32_bf16 v[22:25], v[158:161], v[204:207], v[22:25]
	v_mfma_f32_16x16x32_bf16 v[6:9], v[148:151], v[212:215], v[6:9]
	v_mfma_f32_16x16x32_bf16 v[6:9], v[158:161], v[216:219], v[6:9]
	s_setprio 0
	s_setprio 1
	v_mfma_f32_16x16x32_bf16 v[50:53], v[162:165], v[178:181], v[50:53]
	v_mfma_f32_16x16x32_bf16 v[50:53], v[174:177], v[182:185], v[50:53]
	v_mfma_f32_16x16x32_bf16 v[34:37], v[162:165], v[186:189], v[34:37]
	v_mfma_f32_16x16x32_bf16 v[34:37], v[174:177], v[190:193], v[34:37]
	s_setprio 0
	s_setprio 1
	v_mfma_f32_16x16x32_bf16 v[18:21], v[162:165], v[198:201], v[18:21]
	v_mfma_f32_16x16x32_bf16 v[18:21], v[174:177], v[204:207], v[18:21]
	s_setprio 2
	s_barrier
	v_mfma_f32_16x16x32_bf16 v[2:5], v[162:165], v[212:215], v[2:5]
	v_mfma_f32_16x16x32_bf16 v[2:5], v[174:177], v[216:219], v[2:5]
	s_setprio 0
	s_nop 0
	ds_read_b128 v[132:135], v171
	ds_read_b128 v[136:139], v171 offset:1024
	ds_read_b128 v[140:143], v171 offset:2048
	ds_read_b128 v[144:147], v171 offset:3072
	ds_read_b128 v[148:151], v172
	ds_read_b128 v[158:161], v172 offset:1024
	ds_read_b128 v[162:165], v172 offset:2048
	ds_read_b128 v[174:177], v172 offset:3072
	ds_read_b128 v[178:181], v170 offset:32768
	ds_read_b128 v[182:185], v170 offset:33792
	ds_read_b128 v[186:189], v170 offset:34816
	ds_read_b128 v[190:193], v170 offset:35840
	ds_read_b128 v[198:201], v170 offset:36864
	ds_read_b128 v[204:207], v170 offset:37888
	ds_read_b128 v[212:215], v170 offset:38912
	ds_read_b128 v[216:219], v170 offset:39936
	s_add_u32 s48, s48, 0x4000
	s_addc_u32 s49, s49, 0
	s_mov_b32 m0, s56
	s_nop 0
	global_load_lds_dwordx4 v202, s[48:49]
	s_add_u32 m0, s56, 0x2000
	s_nop 0
	global_load_lds_dwordx4 v203, s[48:49]
	s_waitcnt vmcnt(8)
	s_waitcnt lgkmcnt(0)
	s_setprio 1
	s_barrier
	v_mfma_f32_16x16x32_bf16 v[126:129], v[132:135], v[178:181], v[126:129]
	v_mfma_f32_16x16x32_bf16 v[126:129], v[136:139], v[182:185], v[126:129]
	s_waitcnt lgkmcnt(5)
	v_mfma_f32_16x16x32_bf16 v[110:113], v[132:135], v[186:189], v[110:113]
	v_mfma_f32_16x16x32_bf16 v[110:113], v[136:139], v[190:193], v[110:113]
	s_waitcnt lgkmcnt(3)
	s_setprio 0
	s_setprio 1
	v_mfma_f32_16x16x32_bf16 v[94:97], v[132:135], v[198:201], v[94:97]
	v_mfma_f32_16x16x32_bf16 v[94:97], v[136:139], v[204:207], v[94:97]
	s_waitcnt lgkmcnt(1)
	v_mfma_f32_16x16x32_bf16 v[78:81], v[132:135], v[212:215], v[78:81]
	v_mfma_f32_16x16x32_bf16 v[78:81], v[136:139], v[216:219], v[78:81]
	s_setprio 0
	s_setprio 1
	v_mfma_f32_16x16x32_bf16 v[122:125], v[140:143], v[178:181], v[122:125]
	v_mfma_f32_16x16x32_bf16 v[122:125], v[144:147], v[182:185], v[122:125]
	v_mfma_f32_16x16x32_bf16 v[106:109], v[140:143], v[186:189], v[106:109]
	v_mfma_f32_16x16x32_bf16 v[106:109], v[144:147], v[190:193], v[106:109]
	s_setprio 0
	s_setprio 1
	v_mfma_f32_16x16x32_bf16 v[90:93], v[140:143], v[198:201], v[90:93]
	v_mfma_f32_16x16x32_bf16 v[90:93], v[144:147], v[204:207], v[90:93]
	s_waitcnt lgkmcnt(0)
	v_mfma_f32_16x16x32_bf16 v[74:77], v[140:143], v[212:215], v[74:77]
	v_mfma_f32_16x16x32_bf16 v[74:77], v[144:147], v[216:219], v[74:77]
	s_setprio 0
	s_setprio 1
	v_mfma_f32_16x16x32_bf16 v[118:121], v[148:151], v[178:181], v[118:121]
	v_mfma_f32_16x16x32_bf16 v[118:121], v[158:161], v[182:185], v[118:121]
	v_mfma_f32_16x16x32_bf16 v[102:105], v[148:151], v[186:189], v[102:105]
	v_mfma_f32_16x16x32_bf16 v[102:105], v[158:161], v[190:193], v[102:105]
	s_setprio 0
	s_setprio 1
	v_mfma_f32_16x16x32_bf16 v[86:89], v[148:151], v[198:201], v[86:89]
	v_mfma_f32_16x16x32_bf16 v[86:89], v[158:161], v[204:207], v[86:89]
	v_mfma_f32_16x16x32_bf16 v[70:73], v[148:151], v[212:215], v[70:73]
	v_mfma_f32_16x16x32_bf16 v[70:73], v[158:161], v[216:219], v[70:73]
	s_setprio 0
	s_setprio 1
	v_mfma_f32_16x16x32_bf16 v[114:117], v[162:165], v[178:181], v[114:117]
	v_mfma_f32_16x16x32_bf16 v[114:117], v[174:177], v[182:185], v[114:117]
	v_mfma_f32_16x16x32_bf16 v[98:101], v[162:165], v[186:189], v[98:101]
	v_mfma_f32_16x16x32_bf16 v[98:101], v[174:177], v[190:193], v[98:101]
	s_setprio 0
	s_setprio 1
	v_mfma_f32_16x16x32_bf16 v[82:85], v[162:165], v[198:201], v[82:85]
	v_mfma_f32_16x16x32_bf16 v[82:85], v[174:177], v[204:207], v[82:85]
	s_setprio 2
	s_barrier
	v_mfma_f32_16x16x32_bf16 v[66:69], v[162:165], v[212:215], v[66:69]
	v_mfma_f32_16x16x32_bf16 v[66:69], v[174:177], v[216:219], v[66:69]
	s_setprio 0
	s_nop 0
	ds_read_b128 v[178:181], v170 offset:49152
	ds_read_b128 v[182:185], v170 offset:50176
	ds_read_b128 v[186:189], v170 offset:51200
	ds_read_b128 v[190:193], v170 offset:52224
	ds_read_b128 v[198:201], v170 offset:53248
	ds_read_b128 v[204:207], v170 offset:54272
	ds_read_b128 v[212:215], v170 offset:55296
	ds_read_b128 v[216:219], v170 offset:56320
	s_mov_b32 m0, s59
	s_nop 0
	global_load_lds_dwordx4 v202, s[46:47]
	s_add_u32 m0, s59, 0x2000
	s_nop 0
	global_load_lds_dwordx4 v203, s[46:47]
	s_add_u32 s40, s40, 0xc000
	s_addc_u32 s41, s41, 0
	s_mov_b32 m0, s62
	s_nop 0
	global_load_lds_dwordx4 v202, s[40:41]
	s_add_u32 m0, s62, 0x2000
	s_nop 0
	global_load_lds_dwordx4 v203, s[40:41]
	s_nop 0
	s_mov_b32 m0, s61
	s_nop 0
	global_load_lds_dwordx4 v202, s[42:43]
	s_add_u32 m0, s61, 0x2000
	s_nop 0
	global_load_lds_dwordx4 v203, s[42:43]
	s_waitcnt vmcnt(8)
	s_waitcnt lgkmcnt(0)
	s_setprio 1
	s_barrier
	v_mfma_f32_16x16x32_bf16 v[62:65], v[132:135], v[178:181], v[62:65]
	v_mfma_f32_16x16x32_bf16 v[62:65], v[136:139], v[182:185], v[62:65]
	s_waitcnt lgkmcnt(5)
	v_mfma_f32_16x16x32_bf16 v[46:49], v[132:135], v[186:189], v[46:49]
	v_mfma_f32_16x16x32_bf16 v[46:49], v[136:139], v[190:193], v[46:49]
	s_waitcnt lgkmcnt(3)
	s_setprio 0
	s_setprio 1
	v_mfma_f32_16x16x32_bf16 v[30:33], v[132:135], v[198:201], v[30:33]
	v_mfma_f32_16x16x32_bf16 v[30:33], v[136:139], v[204:207], v[30:33]
	s_waitcnt lgkmcnt(1)
	v_mfma_f32_16x16x32_bf16 v[14:17], v[132:135], v[212:215], v[14:17]
	v_mfma_f32_16x16x32_bf16 v[14:17], v[136:139], v[216:219], v[14:17]
	s_setprio 0
	s_setprio 1
	v_mfma_f32_16x16x32_bf16 v[58:61], v[140:143], v[178:181], v[58:61]
	v_mfma_f32_16x16x32_bf16 v[58:61], v[144:147], v[182:185], v[58:61]
	v_mfma_f32_16x16x32_bf16 v[42:45], v[140:143], v[186:189], v[42:45]
	v_mfma_f32_16x16x32_bf16 v[42:45], v[144:147], v[190:193], v[42:45]
	s_setprio 0
	s_setprio 1
	v_mfma_f32_16x16x32_bf16 v[26:29], v[140:143], v[198:201], v[26:29]
	v_mfma_f32_16x16x32_bf16 v[26:29], v[144:147], v[204:207], v[26:29]
	s_waitcnt lgkmcnt(0)
	v_mfma_f32_16x16x32_bf16 v[10:13], v[140:143], v[212:215], v[10:13]
	v_mfma_f32_16x16x32_bf16 v[10:13], v[144:147], v[216:219], v[10:13]
	s_setprio 0
	s_setprio 1
	v_mfma_f32_16x16x32_bf16 v[54:57], v[148:151], v[178:181], v[54:57]
	v_mfma_f32_16x16x32_bf16 v[54:57], v[158:161], v[182:185], v[54:57]
	v_mfma_f32_16x16x32_bf16 v[38:41], v[148:151], v[186:189], v[38:41]
	v_mfma_f32_16x16x32_bf16 v[38:41], v[158:161], v[190:193], v[38:41]
	s_setprio 0
	s_setprio 1
	v_mfma_f32_16x16x32_bf16 v[22:25], v[148:151], v[198:201], v[22:25]
	v_mfma_f32_16x16x32_bf16 v[22:25], v[158:161], v[204:207], v[22:25]
	v_mfma_f32_16x16x32_bf16 v[6:9], v[148:151], v[212:215], v[6:9]
	v_mfma_f32_16x16x32_bf16 v[6:9], v[158:161], v[216:219], v[6:9]
	s_setprio 0
	s_setprio 1
	v_mfma_f32_16x16x32_bf16 v[50:53], v[162:165], v[178:181], v[50:53]
	v_mfma_f32_16x16x32_bf16 v[50:53], v[174:177], v[182:185], v[50:53]
	v_mfma_f32_16x16x32_bf16 v[34:37], v[162:165], v[186:189], v[34:37]
	v_mfma_f32_16x16x32_bf16 v[34:37], v[174:177], v[190:193], v[34:37]
	s_setprio 0
	s_setprio 1
	v_mfma_f32_16x16x32_bf16 v[18:21], v[162:165], v[198:201], v[18:21]
	v_mfma_f32_16x16x32_bf16 v[18:21], v[174:177], v[204:207], v[18:21]
	s_setprio 2
	s_barrier
	v_mfma_f32_16x16x32_bf16 v[2:5], v[162:165], v[212:215], v[2:5]
	v_mfma_f32_16x16x32_bf16 v[2:5], v[174:177], v[216:219], v[2:5]
	s_setprio 0
	s_nop 0
	s_add_i32 s75, s75, 2
	s_add_u32 s6, s6, 0x10000
	s_addc_u32 s7, s7, 0
	s_cmp_gt_u32 s75, 5
	s_cbranch_scc1 .LBB0_1376
	v_mov_b32_e32 v131, v130
	s_branch .LBB0_1372

.LBB0_1519:
	s_add_i32 s26, s58, 2
	s_lshl_b64 s[54:55], s[26:27], 15
	s_add_u32 s17, s18, s54
	s_addc_u32 s59, s19, s55
	s_and_b64 s[50:51], s[12:13], exec
	s_cselect_b32 s51, s59, s41
	s_cselect_b32 s50, s17, s56
	s_add_u32 s17, s20, s54
	s_waitcnt vmcnt(8)
	s_addc_u32 s54, s21, s55
	s_waitcnt lgkmcnt(0)
	s_and_b64 s[12:13], s[12:13], exec
	s_cselect_b32 s13, s54, s39
	s_cselect_b32 s12, s17, s57
	s_setprio 1
	s_barrier
	v_mfma_f32_16x16x32_bf16 v[126:129], v[146:149], v[186:189], v[126:129]
	v_mfma_f32_16x16x32_bf16 v[126:129], v[150:153], v[190:193], v[126:129]
	s_waitcnt lgkmcnt(5)
	v_mfma_f32_16x16x32_bf16 v[118:121], v[146:149], v[178:181], v[118:121]
	v_mfma_f32_16x16x32_bf16 v[118:121], v[150:153], v[182:185], v[118:121]
	s_waitcnt lgkmcnt(3)
	s_setprio 0
	s_setprio 1
	v_mfma_f32_16x16x32_bf16 v[110:113], v[146:149], v[170:173], v[110:113]
	v_mfma_f32_16x16x32_bf16 v[110:113], v[150:153], v[174:177], v[110:113]
	s_waitcnt lgkmcnt(1)
	v_mfma_f32_16x16x32_bf16 v[102:105], v[146:149], v[162:165], v[102:105]
	v_mfma_f32_16x16x32_bf16 v[102:105], v[150:153], v[166:169], v[102:105]
	s_setprio 0
	s_setprio 1
	v_mfma_f32_16x16x32_bf16 v[122:125], v[154:157], v[186:189], v[122:125]
	v_mfma_f32_16x16x32_bf16 v[122:125], v[158:161], v[190:193], v[122:125]
	v_mfma_f32_16x16x32_bf16 v[114:117], v[154:157], v[178:181], v[114:117]
	v_mfma_f32_16x16x32_bf16 v[114:117], v[158:161], v[182:185], v[114:117]
	s_setprio 0
	s_setprio 1
	v_mfma_f32_16x16x32_bf16 v[106:109], v[154:157], v[170:173], v[106:109]
	v_mfma_f32_16x16x32_bf16 v[106:109], v[158:161], v[174:177], v[106:109]
	s_waitcnt lgkmcnt(0)
	v_mfma_f32_16x16x32_bf16 v[98:101], v[154:157], v[162:165], v[98:101]
	v_mfma_f32_16x16x32_bf16 v[98:101], v[158:161], v[166:169], v[98:101]
	s_setprio 0
	s_setprio 1
	v_mfma_f32_16x16x32_bf16 v[94:97], v[130:133], v[186:189], v[94:97]
	v_mfma_f32_16x16x32_bf16 v[94:97], v[134:137], v[190:193], v[94:97]
	v_mfma_f32_16x16x32_bf16 v[86:89], v[130:133], v[178:181], v[86:89]
	v_mfma_f32_16x16x32_bf16 v[86:89], v[134:137], v[182:185], v[86:89]
	s_setprio 0
	s_setprio 1
	v_mfma_f32_16x16x32_bf16 v[78:81], v[130:133], v[170:173], v[78:81]
	v_mfma_f32_16x16x32_bf16 v[78:81], v[134:137], v[174:177], v[78:81]
	v_mfma_f32_16x16x32_bf16 v[70:73], v[130:133], v[162:165], v[70:73]
	v_mfma_f32_16x16x32_bf16 v[70:73], v[134:137], v[166:169], v[70:73]
	s_setprio 0
	s_setprio 1
	v_mfma_f32_16x16x32_bf16 v[90:93], v[138:141], v[186:189], v[90:93]
	v_mfma_f32_16x16x32_bf16 v[90:93], v[142:145], v[190:193], v[90:93]
	v_mfma_f32_16x16x32_bf16 v[82:85], v[138:141], v[178:181], v[82:85]
	v_mfma_f32_16x16x32_bf16 v[82:85], v[142:145], v[182:185], v[82:85]
	s_setprio 0
	s_setprio 1
	v_mfma_f32_16x16x32_bf16 v[74:77], v[138:141], v[170:173], v[74:77]
	v_mfma_f32_16x16x32_bf16 v[74:77], v[142:145], v[174:177], v[74:77]
	s_setprio 2
	s_barrier
	v_mfma_f32_16x16x32_bf16 v[66:69], v[138:141], v[162:165], v[66:69]
	v_mfma_f32_16x16x32_bf16 v[66:69], v[142:145], v[166:169], v[66:69]
	s_setprio 0
	s_nop 0
	ds_read_b128 v[186:189], v217 offset:16384
	ds_read_b128 v[190:193], v217 offset:17408
	ds_read_b128 v[178:181], v217 offset:18432
	ds_read_b128 v[182:185], v217 offset:19456
	ds_read_b128 v[170:173], v217 offset:20480
	ds_read_b128 v[174:177], v217 offset:21504
	ds_read_b128 v[162:165], v217 offset:22528
	ds_read_b128 v[166:169], v217 offset:23552
	s_mov_b32 m0, s66
	s_nop 0
	global_load_lds_dwordx4 v195, s[12:13]
	s_add_u32 m0, s66, 0x2000
	s_nop 0
	global_load_lds_dwordx4 v212, s[12:13]
	s_add_u32 s54, s12, 0x4000
	s_addc_u32 s55, s13, 0
	s_mov_b32 m0, s67
	s_nop 0
	global_load_lds_dwordx4 v195, s[54:55]
	s_add_u32 m0, s67, 0x2000
	s_nop 0
	global_load_lds_dwordx4 v212, s[54:55]
	s_andn2_b64 vcc, exec, s[52:53]
	s_mov_b32 m0, s15
	s_nop 0
	global_load_lds_dwordx4 v195, s[50:51]
	s_add_u32 m0, s15, 0x2000
	s_nop 0
	global_load_lds_dwordx4 v212, s[50:51]
	s_cbranch_vccnz .LBB0_1521
	v_mov_b32_e32 v2, 0
	v_mov_b32_e32 v3, v2
	v_mov_b32_e32 v4, v2
	v_mov_b32_e32 v5, v2
	v_mov_b32_e32 v6, v2
	v_mov_b32_e32 v7, v2
	v_mov_b32_e32 v8, v2
	v_mov_b32_e32 v9, v2
	v_mov_b32_e32 v10, v2
	v_mov_b32_e32 v11, v2
	v_mov_b32_e32 v12, v2
	v_mov_b32_e32 v13, v2
	v_mov_b32_e32 v14, v2
	v_mov_b32_e32 v15, v2
	v_mov_b32_e32 v16, v2
	v_mov_b32_e32 v17, v2
	v_mov_b32_e32 v18, v2
	v_mov_b32_e32 v19, v2
	v_mov_b32_e32 v20, v2
	v_mov_b32_e32 v21, v2
	v_mov_b32_e32 v22, v2
	v_mov_b32_e32 v23, v2
	v_mov_b32_e32 v24, v2
	v_mov_b32_e32 v25, v2
	v_mov_b32_e32 v26, v2
	v_mov_b32_e32 v27, v2
	v_mov_b32_e32 v28, v2
	v_mov_b32_e32 v29, v2
	v_mov_b32_e32 v30, v2
	v_mov_b32_e32 v31, v2
	v_mov_b32_e32 v32, v2
	v_mov_b32_e32 v33, v2
	v_mov_b32_e32 v34, v2
	v_mov_b32_e32 v35, v2
	v_mov_b32_e32 v36, v2
	v_mov_b32_e32 v37, v2
	v_mov_b32_e32 v38, v2
	v_mov_b32_e32 v39, v2
	v_mov_b32_e32 v40, v2
	v_mov_b32_e32 v41, v2
	v_mov_b32_e32 v42, v2
	v_mov_b32_e32 v43, v2
	v_mov_b32_e32 v44, v2
	v_mov_b32_e32 v45, v2
	v_mov_b32_e32 v46, v2
	v_mov_b32_e32 v47, v2
	v_mov_b32_e32 v48, v2
	v_mov_b32_e32 v49, v2
	v_mov_b32_e32 v50, v2
	v_mov_b32_e32 v51, v2
	v_mov_b32_e32 v52, v2
	v_mov_b32_e32 v53, v2
	v_mov_b32_e32 v54, v2
	v_mov_b32_e32 v55, v2
	v_mov_b32_e32 v56, v2
	v_mov_b32_e32 v57, v2
	v_mov_b32_e32 v58, v2
	v_mov_b32_e32 v59, v2
	v_mov_b32_e32 v60, v2
	v_mov_b32_e32 v61, v2
	v_mov_b32_e32 v62, v2
	v_mov_b32_e32 v63, v2
	v_mov_b32_e32 v64, v2
	v_mov_b32_e32 v65, v2
.LBB0_1521:
	s_waitcnt vmcnt(8)
	s_add_u32 s52, s50, 0x8000
	s_waitcnt lgkmcnt(0)
	s_addc_u32 s53, s51, 0
	s_add_u32 s54, s12, 0x8000
	s_addc_u32 s55, s13, 0
	s_setprio 1
	s_barrier
	v_mfma_f32_16x16x32_bf16 v[62:65], v[146:149], v[186:189], v[62:65]
	v_mfma_f32_16x16x32_bf16 v[62:65], v[150:153], v[190:193], v[62:65]
	s_waitcnt lgkmcnt(5)
	v_mfma_f32_16x16x32_bf16 v[54:57], v[146:149], v[178:181], v[54:57]
	v_mfma_f32_16x16x32_bf16 v[54:57], v[150:153], v[182:185], v[54:57]
	s_waitcnt lgkmcnt(3)
	s_setprio 0
	s_setprio 1
	v_mfma_f32_16x16x32_bf16 v[46:49], v[146:149], v[170:173], v[46:49]
	v_mfma_f32_16x16x32_bf16 v[46:49], v[150:153], v[174:177], v[46:49]
	s_waitcnt lgkmcnt(1)
	v_mfma_f32_16x16x32_bf16 v[38:41], v[146:149], v[162:165], v[38:41]
	v_mfma_f32_16x16x32_bf16 v[38:41], v[150:153], v[166:169], v[38:41]
	s_setprio 0
	s_setprio 1
	v_mfma_f32_16x16x32_bf16 v[58:61], v[154:157], v[186:189], v[58:61]
	v_mfma_f32_16x16x32_bf16 v[58:61], v[158:161], v[190:193], v[58:61]
	v_mfma_f32_16x16x32_bf16 v[50:53], v[154:157], v[178:181], v[50:53]
	v_mfma_f32_16x16x32_bf16 v[50:53], v[158:161], v[182:185], v[50:53]
	s_setprio 0
	s_setprio 1
	v_mfma_f32_16x16x32_bf16 v[42:45], v[154:157], v[170:173], v[42:45]
	v_mfma_f32_16x16x32_bf16 v[42:45], v[158:161], v[174:177], v[42:45]
	s_waitcnt lgkmcnt(0)
	v_mfma_f32_16x16x32_bf16 v[34:37], v[154:157], v[162:165], v[34:37]
	v_mfma_f32_16x16x32_bf16 v[34:37], v[158:161], v[166:169], v[34:37]
	s_setprio 0
	s_setprio 1
	v_mfma_f32_16x16x32_bf16 v[30:33], v[130:133], v[186:189], v[30:33]
	v_mfma_f32_16x16x32_bf16 v[30:33], v[134:137], v[190:193], v[30:33]
	v_mfma_f32_16x16x32_bf16 v[22:25], v[130:133], v[178:181], v[22:25]
	v_mfma_f32_16x16x32_bf16 v[22:25], v[134:137], v[182:185], v[22:25]
	s_setprio 0
	s_setprio 1
	v_mfma_f32_16x16x32_bf16 v[14:17], v[130:133], v[170:173], v[14:17]
	v_mfma_f32_16x16x32_bf16 v[14:17], v[134:137], v[174:177], v[14:17]
	v_mfma_f32_16x16x32_bf16 v[6:9], v[130:133], v[162:165], v[6:9]
	v_mfma_f32_16x16x32_bf16 v[6:9], v[134:137], v[166:169], v[6:9]
	s_setprio 0
	s_setprio 1
	v_mfma_f32_16x16x32_bf16 v[26:29], v[138:141], v[186:189], v[26:29]
	v_mfma_f32_16x16x32_bf16 v[26:29], v[142:145], v[190:193], v[26:29]
	v_mfma_f32_16x16x32_bf16 v[18:21], v[138:141], v[178:181], v[18:21]
	v_mfma_f32_16x16x32_bf16 v[18:21], v[142:145], v[182:185], v[18:21]
	s_setprio 0
	s_setprio 1
	v_mfma_f32_16x16x32_bf16 v[10:13], v[138:141], v[170:173], v[10:13]
	v_mfma_f32_16x16x32_bf16 v[10:13], v[142:145], v[174:177], v[10:13]
	s_setprio 2
	s_barrier
	v_mfma_f32_16x16x32_bf16 v[2:5], v[138:141], v[162:165], v[2:5]
	v_mfma_f32_16x16x32_bf16 v[2:5], v[142:145], v[166:169], v[2:5]
	s_setprio 0
	s_nop 0
	v_add_u32_e32 v142, 0x18000, v216
	v_add_u32_e32 v158, 0x1c000, v216
	ds_read_b128 v[130:133], v142
	ds_read_b128 v[134:137], v142 offset:1024
	ds_read_b128 v[138:141], v142 offset:2048
	ds_read_b128 v[142:145], v142 offset:3072
	ds_read_b128 v[146:149], v158
	ds_read_b128 v[150:153], v158 offset:1024
	ds_read_b128 v[154:157], v158 offset:2048
	ds_read_b128 v[158:161], v158 offset:3072
	ds_read_b128 v[162:165], v217 offset:32768
	ds_read_b128 v[166:169], v217 offset:33792
	ds_read_b128 v[170:173], v217 offset:34816
	ds_read_b128 v[174:177], v217 offset:35840
	ds_read_b128 v[178:181], v217 offset:36864
	ds_read_b128 v[182:185], v217 offset:37888
	ds_read_b128 v[186:189], v217 offset:38912
	ds_read_b128 v[190:193], v217 offset:39936
	s_add_u32 s50, s50, 0x4000
	s_addc_u32 s51, s51, 0
	s_mov_b32 m0, s68
	s_nop 0
	global_load_lds_dwordx4 v195, s[50:51]
	s_add_u32 m0, s68, 0x2000
	s_nop 0
	global_load_lds_dwordx4 v212, s[50:51]
	s_waitcnt vmcnt(8)
	s_waitcnt lgkmcnt(0)
	s_setprio 1
	s_barrier
	v_mfma_f32_16x16x32_bf16 v[126:129], v[130:133], v[162:165], v[126:129]
	v_mfma_f32_16x16x32_bf16 v[126:129], v[134:137], v[166:169], v[126:129]
	s_waitcnt lgkmcnt(5)
	v_mfma_f32_16x16x32_bf16 v[118:121], v[130:133], v[170:173], v[118:121]
	v_mfma_f32_16x16x32_bf16 v[118:121], v[134:137], v[174:177], v[118:121]
	s_waitcnt lgkmcnt(3)
	s_setprio 0
	s_setprio 1
	v_mfma_f32_16x16x32_bf16 v[110:113], v[130:133], v[178:181], v[110:113]
	v_mfma_f32_16x16x32_bf16 v[110:113], v[134:137], v[182:185], v[110:113]
	s_waitcnt lgkmcnt(1)
	v_mfma_f32_16x16x32_bf16 v[102:105], v[130:133], v[186:189], v[102:105]
	v_mfma_f32_16x16x32_bf16 v[102:105], v[134:137], v[190:193], v[102:105]
	s_setprio 0
	s_setprio 1
	v_mfma_f32_16x16x32_bf16 v[122:125], v[138:141], v[162:165], v[122:125]
	v_mfma_f32_16x16x32_bf16 v[122:125], v[142:145], v[166:169], v[122:125]
	v_mfma_f32_16x16x32_bf16 v[114:117], v[138:141], v[170:173], v[114:117]
	v_mfma_f32_16x16x32_bf16 v[114:117], v[142:145], v[174:177], v[114:117]
	s_setprio 0
	s_setprio 1
	v_mfma_f32_16x16x32_bf16 v[106:109], v[138:141], v[178:181], v[106:109]
	v_mfma_f32_16x16x32_bf16 v[106:109], v[142:145], v[182:185], v[106:109]
	s_waitcnt lgkmcnt(0)
	v_mfma_f32_16x16x32_bf16 v[98:101], v[138:141], v[186:189], v[98:101]
	v_mfma_f32_16x16x32_bf16 v[98:101], v[142:145], v[190:193], v[98:101]
	s_setprio 0
	s_setprio 1
	v_mfma_f32_16x16x32_bf16 v[94:97], v[146:149], v[162:165], v[94:97]
	v_mfma_f32_16x16x32_bf16 v[94:97], v[150:153], v[166:169], v[94:97]
	v_mfma_f32_16x16x32_bf16 v[86:89], v[146:149], v[170:173], v[86:89]
	v_mfma_f32_16x16x32_bf16 v[86:89], v[150:153], v[174:177], v[86:89]
	s_setprio 0
	s_setprio 1
	v_mfma_f32_16x16x32_bf16 v[78:81], v[146:149], v[178:181], v[78:81]
	v_mfma_f32_16x16x32_bf16 v[78:81], v[150:153], v[182:185], v[78:81]
	v_mfma_f32_16x16x32_bf16 v[70:73], v[146:149], v[186:189], v[70:73]
	v_mfma_f32_16x16x32_bf16 v[70:73], v[150:153], v[190:193], v[70:73]
	s_setprio 0
	s_setprio 1
	v_mfma_f32_16x16x32_bf16 v[90:93], v[154:157], v[162:165], v[90:93]
	v_mfma_f32_16x16x32_bf16 v[90:93], v[158:161], v[166:169], v[90:93]
	v_mfma_f32_16x16x32_bf16 v[82:85], v[154:157], v[170:173], v[82:85]
	v_mfma_f32_16x16x32_bf16 v[82:85], v[158:161], v[174:177], v[82:85]
	s_setprio 0
	s_setprio 1
	v_mfma_f32_16x16x32_bf16 v[74:77], v[154:157], v[178:181], v[74:77]
	v_mfma_f32_16x16x32_bf16 v[74:77], v[158:161], v[182:185], v[74:77]
	s_setprio 2
	s_barrier
	v_mfma_f32_16x16x32_bf16 v[66:69], v[154:157], v[186:189], v[66:69]
	v_mfma_f32_16x16x32_bf16 v[66:69], v[158:161], v[190:193], v[66:69]
	s_setprio 0
	s_nop 0
	ds_read_b128 v[162:165], v217 offset:49152
	ds_read_b128 v[166:169], v217 offset:50176
	ds_read_b128 v[170:173], v217 offset:51200
	ds_read_b128 v[174:177], v217 offset:52224
	ds_read_b128 v[178:181], v217 offset:53248
	ds_read_b128 v[182:185], v217 offset:54272
	ds_read_b128 v[186:189], v217 offset:55296
	ds_read_b128 v[190:193], v217 offset:56320
	s_mov_b32 m0, s72
	s_nop 0
	global_load_lds_dwordx4 v195, s[54:55]
	s_add_u32 m0, s72, 0x2000
	s_nop 0
	global_load_lds_dwordx4 v212, s[54:55]
	s_add_u32 s12, s12, 0xc000
	s_addc_u32 s13, s13, 0
	s_mov_b32 m0, s74
	s_nop 0
	global_load_lds_dwordx4 v195, s[12:13]
	s_add_u32 m0, s74, 0x2000
	s_nop 0
	global_load_lds_dwordx4 v212, s[12:13]
	s_nop 0
	s_mov_b32 m0, s73
	s_nop 0
	global_load_lds_dwordx4 v195, s[52:53]
	s_add_u32 m0, s73, 0x2000
	s_nop 0
	global_load_lds_dwordx4 v212, s[52:53]
	s_waitcnt vmcnt(8)
	s_waitcnt lgkmcnt(0)
	s_setprio 1
	s_barrier
	v_mfma_f32_16x16x32_bf16 v[62:65], v[130:133], v[162:165], v[62:65]
	v_mfma_f32_16x16x32_bf16 v[62:65], v[134:137], v[166:169], v[62:65]
	s_waitcnt lgkmcnt(5)
	v_mfma_f32_16x16x32_bf16 v[54:57], v[130:133], v[170:173], v[54:57]
	v_mfma_f32_16x16x32_bf16 v[54:57], v[134:137], v[174:177], v[54:57]
	s_waitcnt lgkmcnt(3)
	s_setprio 0
	s_setprio 1
	v_mfma_f32_16x16x32_bf16 v[46:49], v[130:133], v[178:181], v[46:49]
	v_mfma_f32_16x16x32_bf16 v[46:49], v[134:137], v[182:185], v[46:49]
	s_waitcnt lgkmcnt(1)
	v_mfma_f32_16x16x32_bf16 v[38:41], v[130:133], v[186:189], v[38:41]
	v_mfma_f32_16x16x32_bf16 v[38:41], v[134:137], v[190:193], v[38:41]
	s_setprio 0
	s_setprio 1
	v_mfma_f32_16x16x32_bf16 v[58:61], v[138:141], v[162:165], v[58:61]
	v_mfma_f32_16x16x32_bf16 v[58:61], v[142:145], v[166:169], v[58:61]
	v_mfma_f32_16x16x32_bf16 v[50:53], v[138:141], v[170:173], v[50:53]
	v_mfma_f32_16x16x32_bf16 v[50:53], v[142:145], v[174:177], v[50:53]
	s_setprio 0
	s_setprio 1
	v_mfma_f32_16x16x32_bf16 v[42:45], v[138:141], v[178:181], v[42:45]
	v_mfma_f32_16x16x32_bf16 v[42:45], v[142:145], v[182:185], v[42:45]
	s_waitcnt lgkmcnt(0)
	v_mfma_f32_16x16x32_bf16 v[34:37], v[138:141], v[186:189], v[34:37]
	v_mfma_f32_16x16x32_bf16 v[34:37], v[142:145], v[190:193], v[34:37]
	s_setprio 0
	s_setprio 1
	v_mfma_f32_16x16x32_bf16 v[30:33], v[146:149], v[162:165], v[30:33]
	v_mfma_f32_16x16x32_bf16 v[30:33], v[150:153], v[166:169], v[30:33]
	v_mfma_f32_16x16x32_bf16 v[22:25], v[146:149], v[170:173], v[22:25]
	v_mfma_f32_16x16x32_bf16 v[22:25], v[150:153], v[174:177], v[22:25]
	s_setprio 0
	s_setprio 1
	v_mfma_f32_16x16x32_bf16 v[14:17], v[146:149], v[178:181], v[14:17]
	v_mfma_f32_16x16x32_bf16 v[14:17], v[150:153], v[182:185], v[14:17]
	v_mfma_f32_16x16x32_bf16 v[6:9], v[146:149], v[186:189], v[6:9]
	v_mfma_f32_16x16x32_bf16 v[6:9], v[150:153], v[190:193], v[6:9]
	s_setprio 0
	s_setprio 1
	v_mfma_f32_16x16x32_bf16 v[26:29], v[154:157], v[162:165], v[26:29]
	v_mfma_f32_16x16x32_bf16 v[26:29], v[158:161], v[166:169], v[26:29]
	v_mfma_f32_16x16x32_bf16 v[18:21], v[154:157], v[170:173], v[18:21]
	v_mfma_f32_16x16x32_bf16 v[18:21], v[158:161], v[174:177], v[18:21]
	s_setprio 0
	s_setprio 1
	v_mfma_f32_16x16x32_bf16 v[10:13], v[154:157], v[178:181], v[10:13]
	v_mfma_f32_16x16x32_bf16 v[10:13], v[158:161], v[182:185], v[10:13]
	s_setprio 2
	s_barrier
	v_mfma_f32_16x16x32_bf16 v[2:5], v[154:157], v[186:189], v[2:5]
	v_mfma_f32_16x16x32_bf16 v[2:5], v[158:161], v[190:193], v[2:5]
	s_setprio 0
	s_nop 0
	s_cmp_gt_u32 s58, 13
	s_cbranch_scc1 .LBB0_1523
	v_mov_b32_e32 v130, v198
	s_mov_b32 s58, s26
	s_branch .LBB0_1498

.LBB0_1712:
	s_add_u32 s52, s48, 0x10000
	s_addc_u32 s53, s49, 0
	s_and_b64 s[48:49], s[46:47], exec
	s_cselect_b32 s49, s53, s25
	s_cselect_b32 s48, s52, s75
	s_add_u32 s13, s16, s13
	s_addc_u32 s52, s17, 0
	s_add_u32 s13, s13, 0x10000
	s_waitcnt vmcnt(8)
	s_addc_u32 s52, s52, 0
	s_waitcnt lgkmcnt(0)
	s_and_b64 s[46:47], s[46:47], exec
	s_cselect_b32 s47, s52, s27
	s_cselect_b32 s46, s13, s76
	s_setprio 1
	s_barrier
	v_mfma_f32_16x16x32_bf16 v[126:129], v[146:149], v[186:189], v[126:129]
	v_mfma_f32_16x16x32_bf16 v[126:129], v[150:153], v[190:193], v[126:129]
	s_waitcnt lgkmcnt(5)
	v_mfma_f32_16x16x32_bf16 v[118:121], v[146:149], v[178:181], v[118:121]
	v_mfma_f32_16x16x32_bf16 v[118:121], v[150:153], v[182:185], v[118:121]
	s_waitcnt lgkmcnt(3)
	s_setprio 0
	s_setprio 1
	v_mfma_f32_16x16x32_bf16 v[110:113], v[146:149], v[170:173], v[110:113]
	v_mfma_f32_16x16x32_bf16 v[110:113], v[150:153], v[174:177], v[110:113]
	s_waitcnt lgkmcnt(1)
	v_mfma_f32_16x16x32_bf16 v[102:105], v[146:149], v[162:165], v[102:105]
	v_mfma_f32_16x16x32_bf16 v[102:105], v[150:153], v[166:169], v[102:105]
	s_setprio 0
	s_setprio 1
	v_mfma_f32_16x16x32_bf16 v[122:125], v[154:157], v[186:189], v[122:125]
	v_mfma_f32_16x16x32_bf16 v[122:125], v[158:161], v[190:193], v[122:125]
	v_mfma_f32_16x16x32_bf16 v[114:117], v[154:157], v[178:181], v[114:117]
	v_mfma_f32_16x16x32_bf16 v[114:117], v[158:161], v[182:185], v[114:117]
	s_setprio 0
	s_setprio 1
	v_mfma_f32_16x16x32_bf16 v[106:109], v[154:157], v[170:173], v[106:109]
	v_mfma_f32_16x16x32_bf16 v[106:109], v[158:161], v[174:177], v[106:109]
	s_waitcnt lgkmcnt(0)
	v_mfma_f32_16x16x32_bf16 v[98:101], v[154:157], v[162:165], v[98:101]
	v_mfma_f32_16x16x32_bf16 v[98:101], v[158:161], v[166:169], v[98:101]
	s_setprio 0
	s_setprio 1
	v_mfma_f32_16x16x32_bf16 v[94:97], v[130:133], v[186:189], v[94:97]
	v_mfma_f32_16x16x32_bf16 v[94:97], v[134:137], v[190:193], v[94:97]
	v_mfma_f32_16x16x32_bf16 v[86:89], v[130:133], v[178:181], v[86:89]
	v_mfma_f32_16x16x32_bf16 v[86:89], v[134:137], v[182:185], v[86:89]
	s_setprio 0
	s_setprio 1
	v_mfma_f32_16x16x32_bf16 v[78:81], v[130:133], v[170:173], v[78:81]
	v_mfma_f32_16x16x32_bf16 v[78:81], v[134:137], v[174:177], v[78:81]
	v_mfma_f32_16x16x32_bf16 v[70:73], v[130:133], v[162:165], v[70:73]
	v_mfma_f32_16x16x32_bf16 v[70:73], v[134:137], v[166:169], v[70:73]
	s_setprio 0
	s_setprio 1
	v_mfma_f32_16x16x32_bf16 v[90:93], v[138:141], v[186:189], v[90:93]
	v_mfma_f32_16x16x32_bf16 v[90:93], v[142:145], v[190:193], v[90:93]
	v_mfma_f32_16x16x32_bf16 v[82:85], v[138:141], v[178:181], v[82:85]
	v_mfma_f32_16x16x32_bf16 v[82:85], v[142:145], v[182:185], v[82:85]
	s_setprio 0
	s_setprio 1
	v_mfma_f32_16x16x32_bf16 v[74:77], v[138:141], v[170:173], v[74:77]
	v_mfma_f32_16x16x32_bf16 v[74:77], v[142:145], v[174:177], v[74:77]
	s_setprio 2
	s_barrier
	v_mfma_f32_16x16x32_bf16 v[66:69], v[138:141], v[162:165], v[66:69]
	v_mfma_f32_16x16x32_bf16 v[66:69], v[142:145], v[166:169], v[66:69]
	s_setprio 0
	s_nop 0
	ds_read_b128 v[186:189], v209 offset:16384
	ds_read_b128 v[190:193], v209 offset:17408
	ds_read_b128 v[178:181], v209 offset:18432
	ds_read_b128 v[182:185], v209 offset:19456
	ds_read_b128 v[170:173], v209 offset:20480
	ds_read_b128 v[174:177], v209 offset:21504
	ds_read_b128 v[162:165], v209 offset:22528
	ds_read_b128 v[166:169], v209 offset:23552
	s_mov_b32 m0, s58
	s_nop 0
	global_load_lds_dwordx4 v195, s[46:47]
	s_add_u32 m0, s58, 0x2000
	s_nop 0
	global_load_lds_dwordx4 v203, s[46:47]
	s_add_u32 s52, s46, 0x4000
	s_addc_u32 s53, s47, 0
	s_mov_b32 m0, s59
	s_nop 0
	global_load_lds_dwordx4 v195, s[52:53]
	s_add_u32 m0, s59, 0x2000
	s_nop 0
	global_load_lds_dwordx4 v203, s[52:53]
	s_andn2_b64 vcc, exec, s[50:51]
	s_mov_b32 m0, s11
	s_nop 0
	global_load_lds_dwordx4 v195, s[48:49]
	s_add_u32 m0, s11, 0x2000
	s_nop 0
	global_load_lds_dwordx4 v203, s[48:49]
	s_cbranch_vccnz .LBB0_1714
	v_mov_b32_e32 v2, 0
	v_mov_b32_e32 v3, v2
	v_mov_b32_e32 v4, v2
	v_mov_b32_e32 v5, v2
	v_mov_b32_e32 v6, v2
	v_mov_b32_e32 v7, v2
	v_mov_b32_e32 v8, v2
	v_mov_b32_e32 v9, v2
	v_mov_b32_e32 v10, v2
	v_mov_b32_e32 v11, v2
	v_mov_b32_e32 v12, v2
	v_mov_b32_e32 v13, v2
	v_mov_b32_e32 v14, v2
	v_mov_b32_e32 v15, v2
	v_mov_b32_e32 v16, v2
	v_mov_b32_e32 v17, v2
	v_mov_b32_e32 v18, v2
	v_mov_b32_e32 v19, v2
	v_mov_b32_e32 v20, v2
	v_mov_b32_e32 v21, v2
	v_mov_b32_e32 v22, v2
	v_mov_b32_e32 v23, v2
	v_mov_b32_e32 v24, v2
	v_mov_b32_e32 v25, v2
	v_mov_b32_e32 v26, v2
	v_mov_b32_e32 v27, v2
	v_mov_b32_e32 v28, v2
	v_mov_b32_e32 v29, v2
	v_mov_b32_e32 v30, v2
	v_mov_b32_e32 v31, v2
	v_mov_b32_e32 v32, v2
	v_mov_b32_e32 v33, v2
	v_mov_b32_e32 v34, v2
	v_mov_b32_e32 v35, v2
	v_mov_b32_e32 v36, v2
	v_mov_b32_e32 v37, v2
	v_mov_b32_e32 v38, v2
	v_mov_b32_e32 v39, v2
	v_mov_b32_e32 v40, v2
	v_mov_b32_e32 v41, v2
	v_mov_b32_e32 v42, v2
	v_mov_b32_e32 v43, v2
	v_mov_b32_e32 v44, v2
	v_mov_b32_e32 v45, v2
	v_mov_b32_e32 v46, v2
	v_mov_b32_e32 v47, v2
	v_mov_b32_e32 v48, v2
	v_mov_b32_e32 v49, v2
	v_mov_b32_e32 v50, v2
	v_mov_b32_e32 v51, v2
	v_mov_b32_e32 v52, v2
	v_mov_b32_e32 v53, v2
	v_mov_b32_e32 v54, v2
	v_mov_b32_e32 v55, v2
	v_mov_b32_e32 v56, v2
	v_mov_b32_e32 v57, v2
	v_mov_b32_e32 v58, v2
	v_mov_b32_e32 v59, v2
	v_mov_b32_e32 v60, v2
	v_mov_b32_e32 v61, v2
	v_mov_b32_e32 v62, v2
	v_mov_b32_e32 v63, v2
	v_mov_b32_e32 v64, v2
	v_mov_b32_e32 v65, v2
.LBB0_1714:
	s_waitcnt vmcnt(8)
	s_add_u32 s50, s48, 0x8000
	s_waitcnt lgkmcnt(0)
	s_addc_u32 s51, s49, 0
	s_add_u32 s52, s46, 0x8000
	s_addc_u32 s53, s47, 0
	s_setprio 1
	s_barrier
	v_mfma_f32_16x16x32_bf16 v[62:65], v[146:149], v[186:189], v[62:65]
	v_mfma_f32_16x16x32_bf16 v[62:65], v[150:153], v[190:193], v[62:65]
	s_waitcnt lgkmcnt(5)
	v_mfma_f32_16x16x32_bf16 v[54:57], v[146:149], v[178:181], v[54:57]
	v_mfma_f32_16x16x32_bf16 v[54:57], v[150:153], v[182:185], v[54:57]
	s_waitcnt lgkmcnt(3)
	s_setprio 0
	s_setprio 1
	v_mfma_f32_16x16x32_bf16 v[46:49], v[146:149], v[170:173], v[46:49]
	v_mfma_f32_16x16x32_bf16 v[46:49], v[150:153], v[174:177], v[46:49]
	s_waitcnt lgkmcnt(1)
	v_mfma_f32_16x16x32_bf16 v[38:41], v[146:149], v[162:165], v[38:41]
	v_mfma_f32_16x16x32_bf16 v[38:41], v[150:153], v[166:169], v[38:41]
	s_setprio 0
	s_setprio 1
	v_mfma_f32_16x16x32_bf16 v[58:61], v[154:157], v[186:189], v[58:61]
	v_mfma_f32_16x16x32_bf16 v[58:61], v[158:161], v[190:193], v[58:61]
	v_mfma_f32_16x16x32_bf16 v[50:53], v[154:157], v[178:181], v[50:53]
	v_mfma_f32_16x16x32_bf16 v[50:53], v[158:161], v[182:185], v[50:53]
	s_setprio 0
	s_setprio 1
	v_mfma_f32_16x16x32_bf16 v[42:45], v[154:157], v[170:173], v[42:45]
	v_mfma_f32_16x16x32_bf16 v[42:45], v[158:161], v[174:177], v[42:45]
	s_waitcnt lgkmcnt(0)
	v_mfma_f32_16x16x32_bf16 v[34:37], v[154:157], v[162:165], v[34:37]
	v_mfma_f32_16x16x32_bf16 v[34:37], v[158:161], v[166:169], v[34:37]
	s_setprio 0
	s_setprio 1
	v_mfma_f32_16x16x32_bf16 v[30:33], v[130:133], v[186:189], v[30:33]
	v_mfma_f32_16x16x32_bf16 v[30:33], v[134:137], v[190:193], v[30:33]
	v_mfma_f32_16x16x32_bf16 v[22:25], v[130:133], v[178:181], v[22:25]
	v_mfma_f32_16x16x32_bf16 v[22:25], v[134:137], v[182:185], v[22:25]
	s_setprio 0
	s_setprio 1
	v_mfma_f32_16x16x32_bf16 v[14:17], v[130:133], v[170:173], v[14:17]
	v_mfma_f32_16x16x32_bf16 v[14:17], v[134:137], v[174:177], v[14:17]
	v_mfma_f32_16x16x32_bf16 v[6:9], v[130:133], v[162:165], v[6:9]
	v_mfma_f32_16x16x32_bf16 v[6:9], v[134:137], v[166:169], v[6:9]
	s_setprio 0
	s_setprio 1
	v_mfma_f32_16x16x32_bf16 v[26:29], v[138:141], v[186:189], v[26:29]
	v_mfma_f32_16x16x32_bf16 v[26:29], v[142:145], v[190:193], v[26:29]
	v_mfma_f32_16x16x32_bf16 v[18:21], v[138:141], v[178:181], v[18:21]
	v_mfma_f32_16x16x32_bf16 v[18:21], v[142:145], v[182:185], v[18:21]
	s_setprio 0
	s_setprio 1
	v_mfma_f32_16x16x32_bf16 v[10:13], v[138:141], v[170:173], v[10:13]
	v_mfma_f32_16x16x32_bf16 v[10:13], v[142:145], v[174:177], v[10:13]
	s_setprio 2
	s_barrier
	v_mfma_f32_16x16x32_bf16 v[2:5], v[138:141], v[162:165], v[2:5]
	v_mfma_f32_16x16x32_bf16 v[2:5], v[142:145], v[166:169], v[2:5]
	s_setprio 0
	s_nop 0
	v_add_u32_e32 v142, 0x18000, v208
	v_add_u32_e32 v158, 0x1c000, v208
	ds_read_b128 v[130:133], v142
	ds_read_b128 v[134:137], v142 offset:1024
	ds_read_b128 v[138:141], v142 offset:2048
	ds_read_b128 v[142:145], v142 offset:3072
	ds_read_b128 v[146:149], v158
	ds_read_b128 v[150:153], v158 offset:1024
	ds_read_b128 v[154:157], v158 offset:2048
	ds_read_b128 v[158:161], v158 offset:3072
	ds_read_b128 v[162:165], v209 offset:32768
	ds_read_b128 v[166:169], v209 offset:33792
	ds_read_b128 v[170:173], v209 offset:34816
	ds_read_b128 v[174:177], v209 offset:35840
	ds_read_b128 v[178:181], v209 offset:36864
	ds_read_b128 v[182:185], v209 offset:37888
	ds_read_b128 v[186:189], v209 offset:38912
	ds_read_b128 v[190:193], v209 offset:39936
	s_add_u32 s48, s48, 0x4000
	s_addc_u32 s49, s49, 0
	s_mov_b32 m0, s60
	s_nop 0
	global_load_lds_dwordx4 v195, s[48:49]
	s_add_u32 m0, s60, 0x2000
	s_nop 0
	global_load_lds_dwordx4 v203, s[48:49]
	s_waitcnt vmcnt(8)
	s_waitcnt lgkmcnt(0)
	s_setprio 1
	s_barrier
	v_mfma_f32_16x16x32_bf16 v[126:129], v[130:133], v[162:165], v[126:129]
	v_mfma_f32_16x16x32_bf16 v[126:129], v[134:137], v[166:169], v[126:129]
	s_waitcnt lgkmcnt(5)
	v_mfma_f32_16x16x32_bf16 v[118:121], v[130:133], v[170:173], v[118:121]
	v_mfma_f32_16x16x32_bf16 v[118:121], v[134:137], v[174:177], v[118:121]
	s_waitcnt lgkmcnt(3)
	s_setprio 0
	s_setprio 1
	v_mfma_f32_16x16x32_bf16 v[110:113], v[130:133], v[178:181], v[110:113]
	v_mfma_f32_16x16x32_bf16 v[110:113], v[134:137], v[182:185], v[110:113]
	s_waitcnt lgkmcnt(1)
	v_mfma_f32_16x16x32_bf16 v[102:105], v[130:133], v[186:189], v[102:105]
	v_mfma_f32_16x16x32_bf16 v[102:105], v[134:137], v[190:193], v[102:105]
	s_setprio 0
	s_setprio 1
	v_mfma_f32_16x16x32_bf16 v[122:125], v[138:141], v[162:165], v[122:125]
	v_mfma_f32_16x16x32_bf16 v[122:125], v[142:145], v[166:169], v[122:125]
	v_mfma_f32_16x16x32_bf16 v[114:117], v[138:141], v[170:173], v[114:117]
	v_mfma_f32_16x16x32_bf16 v[114:117], v[142:145], v[174:177], v[114:117]
	s_setprio 0
	s_setprio 1
	v_mfma_f32_16x16x32_bf16 v[106:109], v[138:141], v[178:181], v[106:109]
	v_mfma_f32_16x16x32_bf16 v[106:109], v[142:145], v[182:185], v[106:109]
	s_waitcnt lgkmcnt(0)
	v_mfma_f32_16x16x32_bf16 v[98:101], v[138:141], v[186:189], v[98:101]
	v_mfma_f32_16x16x32_bf16 v[98:101], v[142:145], v[190:193], v[98:101]
	s_setprio 0
	s_setprio 1
	v_mfma_f32_16x16x32_bf16 v[94:97], v[146:149], v[162:165], v[94:97]
	v_mfma_f32_16x16x32_bf16 v[94:97], v[150:153], v[166:169], v[94:97]
	v_mfma_f32_16x16x32_bf16 v[86:89], v[146:149], v[170:173], v[86:89]
	v_mfma_f32_16x16x32_bf16 v[86:89], v[150:153], v[174:177], v[86:89]
	s_setprio 0
	s_setprio 1
	v_mfma_f32_16x16x32_bf16 v[78:81], v[146:149], v[178:181], v[78:81]
	v_mfma_f32_16x16x32_bf16 v[78:81], v[150:153], v[182:185], v[78:81]
	v_mfma_f32_16x16x32_bf16 v[70:73], v[146:149], v[186:189], v[70:73]
	v_mfma_f32_16x16x32_bf16 v[70:73], v[150:153], v[190:193], v[70:73]
	s_setprio 0
	s_setprio 1
	v_mfma_f32_16x16x32_bf16 v[90:93], v[154:157], v[162:165], v[90:93]
	v_mfma_f32_16x16x32_bf16 v[90:93], v[158:161], v[166:169], v[90:93]
	v_mfma_f32_16x16x32_bf16 v[82:85], v[154:157], v[170:173], v[82:85]
	v_mfma_f32_16x16x32_bf16 v[82:85], v[158:161], v[174:177], v[82:85]
	s_setprio 0
	s_setprio 1
	v_mfma_f32_16x16x32_bf16 v[74:77], v[154:157], v[178:181], v[74:77]
	v_mfma_f32_16x16x32_bf16 v[74:77], v[158:161], v[182:185], v[74:77]
	s_setprio 2
	s_barrier
	v_mfma_f32_16x16x32_bf16 v[66:69], v[154:157], v[186:189], v[66:69]
	v_mfma_f32_16x16x32_bf16 v[66:69], v[158:161], v[190:193], v[66:69]
	s_setprio 0
	s_nop 0
	ds_read_b128 v[162:165], v209 offset:49152
	ds_read_b128 v[166:169], v209 offset:50176
	ds_read_b128 v[170:173], v209 offset:51200
	ds_read_b128 v[174:177], v209 offset:52224
	ds_read_b128 v[178:181], v209 offset:53248
	ds_read_b128 v[182:185], v209 offset:54272
	ds_read_b128 v[186:189], v209 offset:55296
	ds_read_b128 v[190:193], v209 offset:56320
	s_mov_b32 m0, s64
	s_nop 0
	global_load_lds_dwordx4 v195, s[52:53]
	s_add_u32 m0, s64, 0x2000
	s_nop 0
	global_load_lds_dwordx4 v203, s[52:53]
	s_add_u32 s46, s46, 0xc000
	s_addc_u32 s47, s47, 0
	s_mov_b32 m0, s66
	s_nop 0
	global_load_lds_dwordx4 v195, s[46:47]
	s_add_u32 m0, s66, 0x2000
	s_nop 0
	global_load_lds_dwordx4 v203, s[46:47]
	s_nop 0
	s_mov_b32 m0, s65
	s_nop 0
	global_load_lds_dwordx4 v195, s[50:51]
	s_add_u32 m0, s65, 0x2000
	s_nop 0
	global_load_lds_dwordx4 v203, s[50:51]
	s_waitcnt vmcnt(8)
	s_waitcnt lgkmcnt(0)
	s_setprio 1
	s_barrier
	v_mfma_f32_16x16x32_bf16 v[62:65], v[130:133], v[162:165], v[62:65]
	v_mfma_f32_16x16x32_bf16 v[62:65], v[134:137], v[166:169], v[62:65]
	s_waitcnt lgkmcnt(5)
	v_mfma_f32_16x16x32_bf16 v[54:57], v[130:133], v[170:173], v[54:57]
	v_mfma_f32_16x16x32_bf16 v[54:57], v[134:137], v[174:177], v[54:57]
	s_waitcnt lgkmcnt(3)
	s_setprio 0
	s_setprio 1
	v_mfma_f32_16x16x32_bf16 v[46:49], v[130:133], v[178:181], v[46:49]
	v_mfma_f32_16x16x32_bf16 v[46:49], v[134:137], v[182:185], v[46:49]
	s_waitcnt lgkmcnt(1)
	v_mfma_f32_16x16x32_bf16 v[38:41], v[130:133], v[186:189], v[38:41]
	v_mfma_f32_16x16x32_bf16 v[38:41], v[134:137], v[190:193], v[38:41]
	s_setprio 0
	s_setprio 1
	v_mfma_f32_16x16x32_bf16 v[58:61], v[138:141], v[162:165], v[58:61]
	v_mfma_f32_16x16x32_bf16 v[58:61], v[142:145], v[166:169], v[58:61]
	v_mfma_f32_16x16x32_bf16 v[50:53], v[138:141], v[170:173], v[50:53]
	v_mfma_f32_16x16x32_bf16 v[50:53], v[142:145], v[174:177], v[50:53]
	s_setprio 0
	s_setprio 1
	v_mfma_f32_16x16x32_bf16 v[42:45], v[138:141], v[178:181], v[42:45]
	v_mfma_f32_16x16x32_bf16 v[42:45], v[142:145], v[182:185], v[42:45]
	s_waitcnt lgkmcnt(0)
	v_mfma_f32_16x16x32_bf16 v[34:37], v[138:141], v[186:189], v[34:37]
	v_mfma_f32_16x16x32_bf16 v[34:37], v[142:145], v[190:193], v[34:37]
	s_setprio 0
	s_setprio 1
	v_mfma_f32_16x16x32_bf16 v[30:33], v[146:149], v[162:165], v[30:33]
	v_mfma_f32_16x16x32_bf16 v[30:33], v[150:153], v[166:169], v[30:33]
	v_mfma_f32_16x16x32_bf16 v[22:25], v[146:149], v[170:173], v[22:25]
	v_mfma_f32_16x16x32_bf16 v[22:25], v[150:153], v[174:177], v[22:25]
	s_setprio 0
	s_setprio 1
	v_mfma_f32_16x16x32_bf16 v[14:17], v[146:149], v[178:181], v[14:17]
	v_mfma_f32_16x16x32_bf16 v[14:17], v[150:153], v[182:185], v[14:17]
	v_mfma_f32_16x16x32_bf16 v[6:9], v[146:149], v[186:189], v[6:9]
	v_mfma_f32_16x16x32_bf16 v[6:9], v[150:153], v[190:193], v[6:9]
	s_setprio 0
	s_setprio 1
	v_mfma_f32_16x16x32_bf16 v[26:29], v[154:157], v[162:165], v[26:29]
	v_mfma_f32_16x16x32_bf16 v[26:29], v[158:161], v[166:169], v[26:29]
	v_mfma_f32_16x16x32_bf16 v[18:21], v[154:157], v[170:173], v[18:21]
	v_mfma_f32_16x16x32_bf16 v[18:21], v[158:161], v[174:177], v[18:21]
	s_setprio 0
	s_setprio 1
	v_mfma_f32_16x16x32_bf16 v[10:13], v[154:157], v[178:181], v[10:13]
	v_mfma_f32_16x16x32_bf16 v[10:13], v[158:161], v[182:185], v[10:13]
	s_setprio 2
	s_barrier
	v_mfma_f32_16x16x32_bf16 v[2:5], v[154:157], v[186:189], v[2:5]
	v_mfma_f32_16x16x32_bf16 v[2:5], v[158:161], v[190:193], v[2:5]
	s_setprio 0
	s_nop 0
	s_add_i32 s13, s77, 2
	s_cmp_gt_u32 s77, 13
	s_cbranch_scc1 .LBB0_1716
	s_mov_b32 s77, s13
	s_branch .LBB0_1693

.LBB0_1919:
	s_or_b64 exec, exec, s[10:11]
	s_add_u32 s50, s16, s6
	ds_read_b128 v[134:137], v201
	ds_read_b128 v[138:141], v201 offset:1024
	ds_read_b128 v[142:145], v201 offset:2048
	ds_read_b128 v[146:149], v201 offset:3072
	ds_read_b128 v[150:153], v202
	ds_read_b128 v[154:157], v202 offset:1024
	ds_read_b128 v[162:165], v202 offset:2048
	ds_read_b128 v[166:169], v202 offset:3072
	s_addc_u32 s51, s17, s7
	s_add_u32 s10, s50, 0x20000
	s_addc_u32 s11, s51, 0
	s_add_u32 s42, s75, s6
	s_addc_u32 s43, s76, s7
	s_cmp_eq_u32 s6, 0x60000
	s_cselect_b32 s46, s29, s10
	s_cselect_b32 s47, s20, s11
	s_cselect_b32 s11, s27, s43
	s_cselect_b32 s10, s48, s42
	s_add_u32 s42, s46, 0x8000
	s_addc_u32 s43, s47, 0
	s_add_u32 s44, s10, 0x8000
	s_addc_u32 s45, s11, 0
	ds_read_b128 v[170:173], v203
	ds_read_b128 v[174:177], v203 offset:1024
	ds_read_b128 v[178:181], v203 offset:2048
	ds_read_b128 v[182:185], v203 offset:3072
	ds_read_b128 v[186:189], v203 offset:4096
	ds_read_b128 v[190:193], v203 offset:5120
	ds_read_b128 v[212:215], v203 offset:6144
	ds_read_b128 v[216:219], v203 offset:7168
	s_add_u32 s50, s50, 0x1c000
	s_addc_u32 s51, s51, 0
	s_mov_b32 m0, s65
	s_nop 0
	global_load_lds_dwordx4 v195, s[50:51]
	s_add_u32 m0, s65, 0x2000
	s_nop 0
	global_load_lds_dwordx4 v197, s[50:51]
	s_waitcnt vmcnt(8)
	s_waitcnt lgkmcnt(0)
	s_setprio 1
	s_barrier
	v_mfma_f32_16x16x32_bf16 v[130:133], v[134:137], v[170:173], v[130:133]
	v_mfma_f32_16x16x32_bf16 v[126:129], v[142:145], v[170:173], v[126:129]
	s_waitcnt lgkmcnt(5)
	v_mfma_f32_16x16x32_bf16 v[110:113], v[134:137], v[178:181], v[110:113]
	v_mfma_f32_16x16x32_bf16 v[106:109], v[142:145], v[178:181], v[106:109]
	s_waitcnt lgkmcnt(3)
	v_mfma_f32_16x16x32_bf16 v[94:97], v[134:137], v[186:189], v[94:97]
	v_mfma_f32_16x16x32_bf16 v[90:93], v[142:145], v[186:189], v[90:93]
	s_waitcnt lgkmcnt(1)
	v_mfma_f32_16x16x32_bf16 v[78:81], v[134:137], v[212:215], v[78:81]
	v_mfma_f32_16x16x32_bf16 v[74:77], v[142:145], v[212:215], v[74:77]
	v_mfma_f32_16x16x32_bf16 v[130:133], v[138:141], v[174:177], v[130:133]
	v_mfma_f32_16x16x32_bf16 v[126:129], v[146:149], v[174:177], v[126:129]
	v_mfma_f32_16x16x32_bf16 v[110:113], v[138:141], v[182:185], v[110:113]
	v_mfma_f32_16x16x32_bf16 v[106:109], v[146:149], v[182:185], v[106:109]
	v_mfma_f32_16x16x32_bf16 v[94:97], v[138:141], v[190:193], v[94:97]
	v_mfma_f32_16x16x32_bf16 v[90:93], v[146:149], v[190:193], v[90:93]
	s_waitcnt lgkmcnt(0)
	v_mfma_f32_16x16x32_bf16 v[78:81], v[138:141], v[216:219], v[78:81]
	v_mfma_f32_16x16x32_bf16 v[74:77], v[146:149], v[216:219], v[74:77]
	s_setprio 0
	s_setprio 1
	v_mfma_f32_16x16x32_bf16 v[122:125], v[150:153], v[170:173], v[122:125]
	v_mfma_f32_16x16x32_bf16 v[116:119], v[162:165], v[170:173], v[118:121]
	v_mfma_f32_16x16x32_bf16 v[102:105], v[150:153], v[178:181], v[102:105]
	v_mfma_f32_16x16x32_bf16 v[98:101], v[162:165], v[178:181], v[98:101]
	v_mfma_f32_16x16x32_bf16 v[86:89], v[150:153], v[186:189], v[86:89]
	v_mfma_f32_16x16x32_bf16 v[82:85], v[162:165], v[186:189], v[82:85]
	v_mfma_f32_16x16x32_bf16 v[70:73], v[150:153], v[212:215], v[70:73]
	v_mfma_f32_16x16x32_bf16 v[66:69], v[162:165], v[212:215], v[66:69]
	v_mfma_f32_16x16x32_bf16 v[122:125], v[154:157], v[174:177], v[122:125]
	v_mfma_f32_16x16x32_bf16 v[116:119], v[166:169], v[174:177], v[116:119]
	v_mfma_f32_16x16x32_bf16 v[102:105], v[154:157], v[182:185], v[102:105]
	v_mfma_f32_16x16x32_bf16 v[98:101], v[166:169], v[182:185], v[98:101]
	v_mfma_f32_16x16x32_bf16 v[86:89], v[154:157], v[190:193], v[86:89]
	v_mfma_f32_16x16x32_bf16 v[82:85], v[166:169], v[190:193], v[82:85]
	s_setprio 2
	s_barrier
	v_mfma_f32_16x16x32_bf16 v[70:73], v[154:157], v[216:219], v[70:73]
	v_mfma_f32_16x16x32_bf16 v[66:69], v[166:169], v[216:219], v[66:69]
	s_setprio 0
	s_nop 0
	ds_read_b128 v[170:173], v203 offset:16384
	ds_read_b128 v[174:177], v203 offset:17408
	ds_read_b128 v[178:181], v203 offset:18432
	ds_read_b128 v[182:185], v203 offset:19456
	ds_read_b128 v[186:189], v203 offset:20480
	ds_read_b128 v[190:193], v203 offset:21504
	ds_read_b128 v[212:215], v203 offset:22528
	ds_read_b128 v[216:219], v203 offset:23552
	s_mov_b32 m0, s13
	s_nop 0
	global_load_lds_dwordx4 v195, s[10:11]
	s_add_u32 m0, s13, 0x2000
	s_nop 0
	global_load_lds_dwordx4 v197, s[10:11]
	s_add_u32 s50, s10, 0x4000
	s_addc_u32 s51, s11, 0
	s_mov_b32 m0, s57
	s_nop 0
	global_load_lds_dwordx4 v195, s[50:51]
	s_add_u32 m0, s57, 0x2000
	s_nop 0
	global_load_lds_dwordx4 v197, s[50:51]
	s_nop 0
	s_mov_b32 m0, s56
	s_nop 0
	global_load_lds_dwordx4 v195, s[46:47]
	s_add_u32 m0, s56, 0x2000
	s_nop 0
	global_load_lds_dwordx4 v197, s[46:47]
	s_waitcnt vmcnt(8)
	s_waitcnt lgkmcnt(0)
	s_setprio 1
	s_barrier
	v_mfma_f32_16x16x32_bf16 v[62:65], v[134:137], v[170:173], v[62:65]
	v_mfma_f32_16x16x32_bf16 v[62:65], v[138:141], v[174:177], v[62:65]
	s_waitcnt lgkmcnt(5)
	v_mfma_f32_16x16x32_bf16 v[46:49], v[134:137], v[178:181], v[46:49]
	v_mfma_f32_16x16x32_bf16 v[46:49], v[138:141], v[182:185], v[46:49]
	s_waitcnt lgkmcnt(3)
	s_setprio 0
	s_setprio 1
	v_mfma_f32_16x16x32_bf16 v[30:33], v[134:137], v[186:189], v[30:33]
	v_mfma_f32_16x16x32_bf16 v[30:33], v[138:141], v[190:193], v[30:33]
	s_waitcnt lgkmcnt(1)
	v_mfma_f32_16x16x32_bf16 v[14:17], v[134:137], v[212:215], v[14:17]
	v_mfma_f32_16x16x32_bf16 v[14:17], v[138:141], v[216:219], v[14:17]
	s_setprio 0
	s_setprio 1
	v_mfma_f32_16x16x32_bf16 v[58:61], v[142:145], v[170:173], v[58:61]
	v_mfma_f32_16x16x32_bf16 v[58:61], v[146:149], v[174:177], v[58:61]
	v_mfma_f32_16x16x32_bf16 v[42:45], v[142:145], v[178:181], v[42:45]
	v_mfma_f32_16x16x32_bf16 v[42:45], v[146:149], v[182:185], v[42:45]
	s_setprio 0
	s_setprio 1
	v_mfma_f32_16x16x32_bf16 v[26:29], v[142:145], v[186:189], v[26:29]
	v_mfma_f32_16x16x32_bf16 v[26:29], v[146:149], v[190:193], v[26:29]
	s_waitcnt lgkmcnt(0)
	v_mfma_f32_16x16x32_bf16 v[10:13], v[142:145], v[212:215], v[10:13]
	v_mfma_f32_16x16x32_bf16 v[10:13], v[146:149], v[216:219], v[10:13]
	s_setprio 0
	s_setprio 1
	v_mfma_f32_16x16x32_bf16 v[54:57], v[150:153], v[170:173], v[54:57]
	v_mfma_f32_16x16x32_bf16 v[54:57], v[154:157], v[174:177], v[54:57]
	v_mfma_f32_16x16x32_bf16 v[38:41], v[150:153], v[178:181], v[38:41]
	v_mfma_f32_16x16x32_bf16 v[38:41], v[154:157], v[182:185], v[38:41]
	s_setprio 0
	s_setprio 1
	v_mfma_f32_16x16x32_bf16 v[22:25], v[150:153], v[186:189], v[22:25]
	v_mfma_f32_16x16x32_bf16 v[22:25], v[154:157], v[190:193], v[22:25]
	v_mfma_f32_16x16x32_bf16 v[6:9], v[150:153], v[212:215], v[6:9]
	v_mfma_f32_16x16x32_bf16 v[6:9], v[154:157], v[216:219], v[6:9]
	s_setprio 0
	s_setprio 1
	v_mfma_f32_16x16x32_bf16 v[50:53], v[162:165], v[170:173], v[50:53]
	v_mfma_f32_16x16x32_bf16 v[50:53], v[166:169], v[174:177], v[50:53]
	v_mfma_f32_16x16x32_bf16 v[34:37], v[162:165], v[178:181], v[34:37]
	v_mfma_f32_16x16x32_bf16 v[34:37], v[166:169], v[182:185], v[34:37]
	s_setprio 0
	s_setprio 1
	v_mfma_f32_16x16x32_bf16 v[18:21], v[162:165], v[186:189], v[18:21]
	v_mfma_f32_16x16x32_bf16 v[18:21], v[166:169], v[190:193], v[18:21]
	s_setprio 2
	s_barrier
	v_mfma_f32_16x16x32_bf16 v[2:5], v[162:165], v[212:215], v[2:5]
	v_mfma_f32_16x16x32_bf16 v[2:5], v[166:169], v[216:219], v[2:5]
	s_setprio 0
	s_nop 0
	ds_read_b128 v[134:137], v204
	ds_read_b128 v[138:141], v204 offset:1024
	ds_read_b128 v[142:145], v204 offset:2048
	ds_read_b128 v[146:149], v204 offset:3072
	ds_read_b128 v[150:153], v205
	ds_read_b128 v[154:157], v205 offset:1024
	ds_read_b128 v[162:165], v205 offset:2048
	ds_read_b128 v[166:169], v205 offset:3072
	ds_read_b128 v[170:173], v203 offset:32768
	ds_read_b128 v[174:177], v203 offset:33792
	ds_read_b128 v[178:181], v203 offset:34816
	ds_read_b128 v[182:185], v203 offset:35840
	ds_read_b128 v[186:189], v203 offset:36864
	ds_read_b128 v[190:193], v203 offset:37888
	ds_read_b128 v[212:215], v203 offset:38912
	ds_read_b128 v[216:219], v203 offset:39936
	s_add_u32 s46, s46, 0x4000
	s_addc_u32 s47, s47, 0
	s_mov_b32 m0, s58
	s_nop 0
	global_load_lds_dwordx4 v195, s[46:47]
	s_add_u32 m0, s58, 0x2000
	s_nop 0
	global_load_lds_dwordx4 v197, s[46:47]
	s_waitcnt vmcnt(8)
	s_waitcnt lgkmcnt(0)
	s_setprio 1
	s_barrier
	v_mfma_f32_16x16x32_bf16 v[130:133], v[134:137], v[170:173], v[130:133]
	v_mfma_f32_16x16x32_bf16 v[126:129], v[142:145], v[170:173], v[126:129]
	s_waitcnt lgkmcnt(5)
	v_mfma_f32_16x16x32_bf16 v[110:113], v[134:137], v[178:181], v[110:113]
	v_mfma_f32_16x16x32_bf16 v[106:109], v[142:145], v[178:181], v[106:109]
	s_waitcnt lgkmcnt(3)
	v_mfma_f32_16x16x32_bf16 v[94:97], v[134:137], v[186:189], v[94:97]
	v_mfma_f32_16x16x32_bf16 v[90:93], v[142:145], v[186:189], v[90:93]
	s_waitcnt lgkmcnt(1)
	v_mfma_f32_16x16x32_bf16 v[78:81], v[134:137], v[212:215], v[78:81]
	v_mfma_f32_16x16x32_bf16 v[74:77], v[142:145], v[212:215], v[74:77]
	v_mfma_f32_16x16x32_bf16 v[130:133], v[138:141], v[174:177], v[130:133]
	v_mfma_f32_16x16x32_bf16 v[126:129], v[146:149], v[174:177], v[126:129]
	v_mfma_f32_16x16x32_bf16 v[110:113], v[138:141], v[182:185], v[110:113]
	v_mfma_f32_16x16x32_bf16 v[106:109], v[146:149], v[182:185], v[106:109]
	v_mfma_f32_16x16x32_bf16 v[94:97], v[138:141], v[190:193], v[94:97]
	v_mfma_f32_16x16x32_bf16 v[90:93], v[146:149], v[190:193], v[90:93]
	s_waitcnt lgkmcnt(0)
	v_mfma_f32_16x16x32_bf16 v[78:81], v[138:141], v[216:219], v[78:81]
	v_mfma_f32_16x16x32_bf16 v[74:77], v[146:149], v[216:219], v[74:77]
	s_setprio 0
	s_setprio 1
	v_mfma_f32_16x16x32_bf16 v[120:123], v[150:153], v[170:173], v[122:125]
	v_mfma_f32_16x16x32_bf16 v[116:119], v[162:165], v[170:173], v[116:119]
	v_mfma_f32_16x16x32_bf16 v[102:105], v[150:153], v[178:181], v[102:105]
	v_mfma_f32_16x16x32_bf16 v[98:101], v[162:165], v[178:181], v[98:101]
	v_mfma_f32_16x16x32_bf16 v[86:89], v[150:153], v[186:189], v[86:89]
	v_mfma_f32_16x16x32_bf16 v[82:85], v[162:165], v[186:189], v[82:85]
	v_mfma_f32_16x16x32_bf16 v[70:73], v[150:153], v[212:215], v[70:73]
	v_mfma_f32_16x16x32_bf16 v[66:69], v[162:165], v[212:215], v[66:69]
	v_mfma_f32_16x16x32_bf16 v[122:125], v[154:157], v[174:177], v[120:123]
	v_mfma_f32_16x16x32_bf16 v[118:121], v[166:169], v[174:177], v[116:119]
	v_mfma_f32_16x16x32_bf16 v[102:105], v[154:157], v[182:185], v[102:105]
	v_mfma_f32_16x16x32_bf16 v[98:101], v[166:169], v[182:185], v[98:101]
	v_mfma_f32_16x16x32_bf16 v[86:89], v[154:157], v[190:193], v[86:89]
	v_mfma_f32_16x16x32_bf16 v[82:85], v[166:169], v[190:193], v[82:85]
	s_setprio 2
	s_barrier
	v_mfma_f32_16x16x32_bf16 v[70:73], v[154:157], v[216:219], v[70:73]
	v_mfma_f32_16x16x32_bf16 v[66:69], v[166:169], v[216:219], v[66:69]
	s_setprio 0
	s_nop 0
	ds_read_b128 v[170:173], v203 offset:49152
	ds_read_b128 v[174:177], v203 offset:50176
	ds_read_b128 v[178:181], v203 offset:51200
	ds_read_b128 v[182:185], v203 offset:52224
	ds_read_b128 v[186:189], v203 offset:53248
	ds_read_b128 v[190:193], v203 offset:54272
	ds_read_b128 v[212:215], v203 offset:55296
	ds_read_b128 v[216:219], v203 offset:56320
	s_mov_b32 m0, s62
	s_nop 0
	global_load_lds_dwordx4 v195, s[44:45]
	s_add_u32 m0, s62, 0x2000
	s_nop 0
	global_load_lds_dwordx4 v197, s[44:45]
	s_add_u32 s10, s10, 0xc000
	s_addc_u32 s11, s11, 0
	s_mov_b32 m0, s64
	s_nop 0
	global_load_lds_dwordx4 v195, s[10:11]
	s_add_u32 m0, s64, 0x2000
	s_nop 0
	global_load_lds_dwordx4 v197, s[10:11]
	s_nop 0
	s_mov_b32 m0, s63
	s_nop 0
	global_load_lds_dwordx4 v195, s[42:43]
	s_add_u32 m0, s63, 0x2000
	s_nop 0
	global_load_lds_dwordx4 v197, s[42:43]
	s_waitcnt vmcnt(8)
	s_waitcnt lgkmcnt(0)
	s_setprio 1
	s_barrier
	v_mfma_f32_16x16x32_bf16 v[62:65], v[134:137], v[170:173], v[62:65]
	v_mfma_f32_16x16x32_bf16 v[62:65], v[138:141], v[174:177], v[62:65]
	s_waitcnt lgkmcnt(5)
	v_mfma_f32_16x16x32_bf16 v[46:49], v[134:137], v[178:181], v[46:49]
	v_mfma_f32_16x16x32_bf16 v[46:49], v[138:141], v[182:185], v[46:49]
	s_waitcnt lgkmcnt(3)
	s_setprio 0
	s_setprio 1
	v_mfma_f32_16x16x32_bf16 v[30:33], v[134:137], v[186:189], v[30:33]
	v_mfma_f32_16x16x32_bf16 v[30:33], v[138:141], v[190:193], v[30:33]
	s_waitcnt lgkmcnt(1)
	v_mfma_f32_16x16x32_bf16 v[14:17], v[134:137], v[212:215], v[14:17]
	v_mfma_f32_16x16x32_bf16 v[14:17], v[138:141], v[216:219], v[14:17]
	s_setprio 0
	s_setprio 1
	v_mfma_f32_16x16x32_bf16 v[58:61], v[142:145], v[170:173], v[58:61]
	v_mfma_f32_16x16x32_bf16 v[58:61], v[146:149], v[174:177], v[58:61]
	v_mfma_f32_16x16x32_bf16 v[42:45], v[142:145], v[178:181], v[42:45]
	v_mfma_f32_16x16x32_bf16 v[42:45], v[146:149], v[182:185], v[42:45]
	s_setprio 0
	s_setprio 1
	v_mfma_f32_16x16x32_bf16 v[26:29], v[142:145], v[186:189], v[26:29]
	v_mfma_f32_16x16x32_bf16 v[26:29], v[146:149], v[190:193], v[26:29]
	s_waitcnt lgkmcnt(0)
	v_mfma_f32_16x16x32_bf16 v[10:13], v[142:145], v[212:215], v[10:13]
	v_mfma_f32_16x16x32_bf16 v[10:13], v[146:149], v[216:219], v[10:13]
	s_setprio 0
	s_setprio 1
	v_mfma_f32_16x16x32_bf16 v[54:57], v[150:153], v[170:173], v[54:57]
	v_mfma_f32_16x16x32_bf16 v[54:57], v[154:157], v[174:177], v[54:57]
	v_mfma_f32_16x16x32_bf16 v[38:41], v[150:153], v[178:181], v[38:41]
	v_mfma_f32_16x16x32_bf16 v[38:41], v[154:157], v[182:185], v[38:41]
	s_setprio 0
	s_setprio 1
	v_mfma_f32_16x16x32_bf16 v[22:25], v[150:153], v[186:189], v[22:25]
	v_mfma_f32_16x16x32_bf16 v[22:25], v[154:157], v[190:193], v[22:25]
	v_mfma_f32_16x16x32_bf16 v[6:9], v[150:153], v[212:215], v[6:9]
	v_mfma_f32_16x16x32_bf16 v[6:9], v[154:157], v[216:219], v[6:9]
	s_setprio 0
	s_setprio 1
	v_mfma_f32_16x16x32_bf16 v[50:53], v[162:165], v[170:173], v[50:53]
	v_mfma_f32_16x16x32_bf16 v[50:53], v[166:169], v[174:177], v[50:53]
	v_mfma_f32_16x16x32_bf16 v[34:37], v[162:165], v[178:181], v[34:37]
	v_mfma_f32_16x16x32_bf16 v[34:37], v[166:169], v[182:185], v[34:37]
	s_setprio 0
	s_setprio 1
	v_mfma_f32_16x16x32_bf16 v[18:21], v[162:165], v[186:189], v[18:21]
	v_mfma_f32_16x16x32_bf16 v[18:21], v[166:169], v[190:193], v[18:21]
	s_setprio 2
	s_barrier
	v_mfma_f32_16x16x32_bf16 v[2:5], v[162:165], v[212:215], v[2:5]
	v_mfma_f32_16x16x32_bf16 v[2:5], v[166:169], v[216:219], v[2:5]
	s_setprio 0
	s_nop 0
	s_add_i32 s49, s49, 2
	s_add_u32 s6, s6, 0x10000
	s_addc_u32 s7, s7, 0
	s_cmp_gt_u32 s49, 13
	v_mov_b32_e32 v115, v114
	s_cbranch_scc1 .LBB0_1922

.LBB0_2120:
	s_add_u32 s56, s52, 0x10000
	s_addc_u32 s57, s53, 0
	s_and_b64 s[52:53], s[50:51], exec
	s_cselect_b32 s53, s57, s43
	s_cselect_b32 s52, s56, s88
	s_add_u32 s15, s18, s15
	s_addc_u32 s56, s19, 0
	s_add_u32 s15, s15, 0x10000
	s_waitcnt vmcnt(8)
	s_addc_u32 s56, s56, 0
	s_waitcnt lgkmcnt(0)
	s_and_b64 s[50:51], s[50:51], exec
	s_cselect_b32 s51, s56, s41
	s_cselect_b32 s50, s15, s89
	s_setprio 1
	s_barrier
	v_mfma_f32_16x16x32_bf16 v[126:129], v[146:149], v[186:189], v[126:129]
	v_mfma_f32_16x16x32_bf16 v[126:129], v[150:153], v[190:193], v[126:129]
	s_waitcnt lgkmcnt(5)
	v_mfma_f32_16x16x32_bf16 v[118:121], v[146:149], v[178:181], v[118:121]
	v_mfma_f32_16x16x32_bf16 v[118:121], v[150:153], v[182:185], v[118:121]
	s_waitcnt lgkmcnt(3)
	s_setprio 0
	s_setprio 1
	v_mfma_f32_16x16x32_bf16 v[110:113], v[146:149], v[170:173], v[110:113]
	v_mfma_f32_16x16x32_bf16 v[110:113], v[150:153], v[174:177], v[110:113]
	s_waitcnt lgkmcnt(1)
	v_mfma_f32_16x16x32_bf16 v[102:105], v[146:149], v[162:165], v[102:105]
	v_mfma_f32_16x16x32_bf16 v[102:105], v[150:153], v[166:169], v[102:105]
	s_setprio 0
	s_setprio 1
	v_mfma_f32_16x16x32_bf16 v[122:125], v[154:157], v[186:189], v[122:125]
	v_mfma_f32_16x16x32_bf16 v[122:125], v[158:161], v[190:193], v[122:125]
	v_mfma_f32_16x16x32_bf16 v[114:117], v[154:157], v[178:181], v[114:117]
	v_mfma_f32_16x16x32_bf16 v[114:117], v[158:161], v[182:185], v[114:117]
	s_setprio 0
	s_setprio 1
	v_mfma_f32_16x16x32_bf16 v[106:109], v[154:157], v[170:173], v[106:109]
	v_mfma_f32_16x16x32_bf16 v[106:109], v[158:161], v[174:177], v[106:109]
	s_waitcnt lgkmcnt(0)
	v_mfma_f32_16x16x32_bf16 v[98:101], v[154:157], v[162:165], v[98:101]
	v_mfma_f32_16x16x32_bf16 v[98:101], v[158:161], v[166:169], v[98:101]
	s_setprio 0
	s_setprio 1
	v_mfma_f32_16x16x32_bf16 v[94:97], v[130:133], v[186:189], v[94:97]
	v_mfma_f32_16x16x32_bf16 v[94:97], v[134:137], v[190:193], v[94:97]
	v_mfma_f32_16x16x32_bf16 v[86:89], v[130:133], v[178:181], v[86:89]
	v_mfma_f32_16x16x32_bf16 v[86:89], v[134:137], v[182:185], v[86:89]
	s_setprio 0
	s_setprio 1
	v_mfma_f32_16x16x32_bf16 v[78:81], v[130:133], v[170:173], v[78:81]
	v_mfma_f32_16x16x32_bf16 v[78:81], v[134:137], v[174:177], v[78:81]
	v_mfma_f32_16x16x32_bf16 v[70:73], v[130:133], v[162:165], v[70:73]
	v_mfma_f32_16x16x32_bf16 v[70:73], v[134:137], v[166:169], v[70:73]
	s_setprio 0
	s_setprio 1
	v_mfma_f32_16x16x32_bf16 v[90:93], v[138:141], v[186:189], v[90:93]
	v_mfma_f32_16x16x32_bf16 v[90:93], v[142:145], v[190:193], v[90:93]
	v_mfma_f32_16x16x32_bf16 v[82:85], v[138:141], v[178:181], v[82:85]
	v_mfma_f32_16x16x32_bf16 v[82:85], v[142:145], v[182:185], v[82:85]
	s_setprio 0
	s_setprio 1
	v_mfma_f32_16x16x32_bf16 v[74:77], v[138:141], v[170:173], v[74:77]
	v_mfma_f32_16x16x32_bf16 v[74:77], v[142:145], v[174:177], v[74:77]
	s_setprio 2
	s_barrier
	v_mfma_f32_16x16x32_bf16 v[66:69], v[138:141], v[162:165], v[66:69]
	v_mfma_f32_16x16x32_bf16 v[66:69], v[142:145], v[166:169], v[66:69]
	s_setprio 0
	s_nop 0
	ds_read_b128 v[186:189], v207 offset:16384
	ds_read_b128 v[190:193], v207 offset:17408
	ds_read_b128 v[178:181], v207 offset:18432
	ds_read_b128 v[182:185], v207 offset:19456
	ds_read_b128 v[170:173], v207 offset:20480
	ds_read_b128 v[174:177], v207 offset:21504
	ds_read_b128 v[162:165], v207 offset:22528
	ds_read_b128 v[166:169], v207 offset:23552
	s_mov_b32 m0, s62
	s_nop 0
	global_load_lds_dwordx4 v195, s[50:51]
	s_add_u32 m0, s62, 0x2000
	s_nop 0
	global_load_lds_dwordx4 v197, s[50:51]
	s_add_u32 s56, s50, 0x4000
	s_addc_u32 s57, s51, 0
	s_mov_b32 m0, s63
	s_nop 0
	global_load_lds_dwordx4 v195, s[56:57]
	s_add_u32 m0, s63, 0x2000
	s_nop 0
	global_load_lds_dwordx4 v197, s[56:57]
	s_andn2_b64 vcc, exec, s[54:55]
	s_mov_b32 m0, s61
	s_nop 0
	global_load_lds_dwordx4 v195, s[52:53]
	s_add_u32 m0, s61, 0x2000
	s_nop 0
	global_load_lds_dwordx4 v197, s[52:53]
	s_cbranch_vccnz .LBB0_2122
	v_mov_b32_e32 v2, 0
	v_mov_b32_e32 v3, v2
	v_mov_b32_e32 v4, v2
	v_mov_b32_e32 v5, v2
	v_mov_b32_e32 v6, v2
	v_mov_b32_e32 v7, v2
	v_mov_b32_e32 v8, v2
	v_mov_b32_e32 v9, v2
	v_mov_b32_e32 v10, v2
	v_mov_b32_e32 v11, v2
	v_mov_b32_e32 v12, v2
	v_mov_b32_e32 v13, v2
	v_mov_b32_e32 v14, v2
	v_mov_b32_e32 v15, v2
	v_mov_b32_e32 v16, v2
	v_mov_b32_e32 v17, v2
	v_mov_b32_e32 v18, v2
	v_mov_b32_e32 v19, v2
	v_mov_b32_e32 v20, v2
	v_mov_b32_e32 v21, v2
	v_mov_b32_e32 v22, v2
	v_mov_b32_e32 v23, v2
	v_mov_b32_e32 v24, v2
	v_mov_b32_e32 v25, v2
	v_mov_b32_e32 v26, v2
	v_mov_b32_e32 v27, v2
	v_mov_b32_e32 v28, v2
	v_mov_b32_e32 v29, v2
	v_mov_b32_e32 v30, v2
	v_mov_b32_e32 v31, v2
	v_mov_b32_e32 v32, v2
	v_mov_b32_e32 v33, v2
	v_mov_b32_e32 v34, v2
	v_mov_b32_e32 v35, v2
	v_mov_b32_e32 v36, v2
	v_mov_b32_e32 v37, v2
	v_mov_b32_e32 v38, v2
	v_mov_b32_e32 v39, v2
	v_mov_b32_e32 v40, v2
	v_mov_b32_e32 v41, v2
	v_mov_b32_e32 v42, v2
	v_mov_b32_e32 v43, v2
	v_mov_b32_e32 v44, v2
	v_mov_b32_e32 v45, v2
	v_mov_b32_e32 v46, v2
	v_mov_b32_e32 v47, v2
	v_mov_b32_e32 v48, v2
	v_mov_b32_e32 v49, v2
	v_mov_b32_e32 v50, v2
	v_mov_b32_e32 v51, v2
	v_mov_b32_e32 v52, v2
	v_mov_b32_e32 v53, v2
	v_mov_b32_e32 v54, v2
	v_mov_b32_e32 v55, v2
	v_mov_b32_e32 v56, v2
	v_mov_b32_e32 v57, v2
	v_mov_b32_e32 v58, v2
	v_mov_b32_e32 v59, v2
	v_mov_b32_e32 v60, v2
	v_mov_b32_e32 v61, v2
	v_mov_b32_e32 v62, v2
	v_mov_b32_e32 v63, v2
	v_mov_b32_e32 v64, v2
	v_mov_b32_e32 v65, v2
.LBB0_2122:
	s_waitcnt vmcnt(8)
	s_add_u32 s54, s52, 0x8000
	s_waitcnt lgkmcnt(0)
	s_addc_u32 s55, s53, 0
	s_add_u32 s56, s50, 0x8000
	s_addc_u32 s57, s51, 0
	s_setprio 1
	s_barrier
	v_mfma_f32_16x16x32_bf16 v[62:65], v[146:149], v[186:189], v[62:65]
	v_mfma_f32_16x16x32_bf16 v[62:65], v[150:153], v[190:193], v[62:65]
	s_waitcnt lgkmcnt(5)
	v_mfma_f32_16x16x32_bf16 v[54:57], v[146:149], v[178:181], v[54:57]
	v_mfma_f32_16x16x32_bf16 v[54:57], v[150:153], v[182:185], v[54:57]
	s_waitcnt lgkmcnt(3)
	s_setprio 0
	s_setprio 1
	v_mfma_f32_16x16x32_bf16 v[46:49], v[146:149], v[170:173], v[46:49]
	v_mfma_f32_16x16x32_bf16 v[46:49], v[150:153], v[174:177], v[46:49]
	s_waitcnt lgkmcnt(1)
	v_mfma_f32_16x16x32_bf16 v[38:41], v[146:149], v[162:165], v[38:41]
	v_mfma_f32_16x16x32_bf16 v[38:41], v[150:153], v[166:169], v[38:41]
	s_setprio 0
	s_setprio 1
	v_mfma_f32_16x16x32_bf16 v[58:61], v[154:157], v[186:189], v[58:61]
	v_mfma_f32_16x16x32_bf16 v[58:61], v[158:161], v[190:193], v[58:61]
	v_mfma_f32_16x16x32_bf16 v[50:53], v[154:157], v[178:181], v[50:53]
	v_mfma_f32_16x16x32_bf16 v[50:53], v[158:161], v[182:185], v[50:53]
	s_setprio 0
	s_setprio 1
	v_mfma_f32_16x16x32_bf16 v[42:45], v[154:157], v[170:173], v[42:45]
	v_mfma_f32_16x16x32_bf16 v[42:45], v[158:161], v[174:177], v[42:45]
	s_waitcnt lgkmcnt(0)
	v_mfma_f32_16x16x32_bf16 v[34:37], v[154:157], v[162:165], v[34:37]
	v_mfma_f32_16x16x32_bf16 v[34:37], v[158:161], v[166:169], v[34:37]
	s_setprio 0
	s_setprio 1
	v_mfma_f32_16x16x32_bf16 v[30:33], v[130:133], v[186:189], v[30:33]
	v_mfma_f32_16x16x32_bf16 v[30:33], v[134:137], v[190:193], v[30:33]
	v_mfma_f32_16x16x32_bf16 v[22:25], v[130:133], v[178:181], v[22:25]
	v_mfma_f32_16x16x32_bf16 v[22:25], v[134:137], v[182:185], v[22:25]
	s_setprio 0
	s_setprio 1
	v_mfma_f32_16x16x32_bf16 v[14:17], v[130:133], v[170:173], v[14:17]
	v_mfma_f32_16x16x32_bf16 v[14:17], v[134:137], v[174:177], v[14:17]
	v_mfma_f32_16x16x32_bf16 v[6:9], v[130:133], v[162:165], v[6:9]
	v_mfma_f32_16x16x32_bf16 v[6:9], v[134:137], v[166:169], v[6:9]
	s_setprio 0
	s_setprio 1
	v_mfma_f32_16x16x32_bf16 v[26:29], v[138:141], v[186:189], v[26:29]
	v_mfma_f32_16x16x32_bf16 v[26:29], v[142:145], v[190:193], v[26:29]
	v_mfma_f32_16x16x32_bf16 v[18:21], v[138:141], v[178:181], v[18:21]
	v_mfma_f32_16x16x32_bf16 v[18:21], v[142:145], v[182:185], v[18:21]
	s_setprio 0
	s_setprio 1
	v_mfma_f32_16x16x32_bf16 v[10:13], v[138:141], v[170:173], v[10:13]
	v_mfma_f32_16x16x32_bf16 v[10:13], v[142:145], v[174:177], v[10:13]
	s_setprio 2
	s_barrier
	v_mfma_f32_16x16x32_bf16 v[2:5], v[138:141], v[162:165], v[2:5]
	v_mfma_f32_16x16x32_bf16 v[2:5], v[142:145], v[166:169], v[2:5]
	s_setprio 0
	s_nop 0
	v_add_u32_e32 v142, 0x18000, v206
	v_add_u32_e32 v158, 0x1c000, v206
	ds_read_b128 v[130:133], v142
	ds_read_b128 v[134:137], v142 offset:1024
	ds_read_b128 v[138:141], v142 offset:2048
	ds_read_b128 v[142:145], v142 offset:3072
	ds_read_b128 v[146:149], v158
	ds_read_b128 v[150:153], v158 offset:1024
	ds_read_b128 v[154:157], v158 offset:2048
	ds_read_b128 v[158:161], v158 offset:3072
	ds_read_b128 v[162:165], v207 offset:32768
	ds_read_b128 v[166:169], v207 offset:33792
	ds_read_b128 v[170:173], v207 offset:34816
	ds_read_b128 v[174:177], v207 offset:35840
	ds_read_b128 v[178:181], v207 offset:36864
	ds_read_b128 v[182:185], v207 offset:37888
	ds_read_b128 v[186:189], v207 offset:38912
	ds_read_b128 v[190:193], v207 offset:39936
	s_add_u32 s52, s52, 0x4000
	s_addc_u32 s53, s53, 0
	s_mov_b32 m0, s64
	s_nop 0
	global_load_lds_dwordx4 v195, s[52:53]
	s_add_u32 m0, s64, 0x2000
	s_nop 0
	global_load_lds_dwordx4 v197, s[52:53]
	s_waitcnt vmcnt(8)
	s_waitcnt lgkmcnt(0)
	s_setprio 1
	s_barrier
	v_mfma_f32_16x16x32_bf16 v[126:129], v[130:133], v[162:165], v[126:129]
	v_mfma_f32_16x16x32_bf16 v[126:129], v[134:137], v[166:169], v[126:129]
	s_waitcnt lgkmcnt(5)
	v_mfma_f32_16x16x32_bf16 v[118:121], v[130:133], v[170:173], v[118:121]
	v_mfma_f32_16x16x32_bf16 v[118:121], v[134:137], v[174:177], v[118:121]
	s_waitcnt lgkmcnt(3)
	s_setprio 0
	s_setprio 1
	v_mfma_f32_16x16x32_bf16 v[110:113], v[130:133], v[178:181], v[110:113]
	v_mfma_f32_16x16x32_bf16 v[110:113], v[134:137], v[182:185], v[110:113]
	s_waitcnt lgkmcnt(1)
	v_mfma_f32_16x16x32_bf16 v[102:105], v[130:133], v[186:189], v[102:105]
	v_mfma_f32_16x16x32_bf16 v[102:105], v[134:137], v[190:193], v[102:105]
	s_setprio 0
	s_setprio 1
	v_mfma_f32_16x16x32_bf16 v[122:125], v[138:141], v[162:165], v[122:125]
	v_mfma_f32_16x16x32_bf16 v[122:125], v[142:145], v[166:169], v[122:125]
	v_mfma_f32_16x16x32_bf16 v[114:117], v[138:141], v[170:173], v[114:117]
	v_mfma_f32_16x16x32_bf16 v[114:117], v[142:145], v[174:177], v[114:117]
	s_setprio 0
	s_setprio 1
	v_mfma_f32_16x16x32_bf16 v[106:109], v[138:141], v[178:181], v[106:109]
	v_mfma_f32_16x16x32_bf16 v[106:109], v[142:145], v[182:185], v[106:109]
	s_waitcnt lgkmcnt(0)
	v_mfma_f32_16x16x32_bf16 v[98:101], v[138:141], v[186:189], v[98:101]
	v_mfma_f32_16x16x32_bf16 v[98:101], v[142:145], v[190:193], v[98:101]
	s_setprio 0
	s_setprio 1
	v_mfma_f32_16x16x32_bf16 v[94:97], v[146:149], v[162:165], v[94:97]
	v_mfma_f32_16x16x32_bf16 v[94:97], v[150:153], v[166:169], v[94:97]
	v_mfma_f32_16x16x32_bf16 v[86:89], v[146:149], v[170:173], v[86:89]
	v_mfma_f32_16x16x32_bf16 v[86:89], v[150:153], v[174:177], v[86:89]
	s_setprio 0
	s_setprio 1
	v_mfma_f32_16x16x32_bf16 v[78:81], v[146:149], v[178:181], v[78:81]
	v_mfma_f32_16x16x32_bf16 v[78:81], v[150:153], v[182:185], v[78:81]
	v_mfma_f32_16x16x32_bf16 v[70:73], v[146:149], v[186:189], v[70:73]
	v_mfma_f32_16x16x32_bf16 v[70:73], v[150:153], v[190:193], v[70:73]
	s_setprio 0
	s_setprio 1
	v_mfma_f32_16x16x32_bf16 v[90:93], v[154:157], v[162:165], v[90:93]
	v_mfma_f32_16x16x32_bf16 v[90:93], v[158:161], v[166:169], v[90:93]
	v_mfma_f32_16x16x32_bf16 v[82:85], v[154:157], v[170:173], v[82:85]
	v_mfma_f32_16x16x32_bf16 v[82:85], v[158:161], v[174:177], v[82:85]
	s_setprio 0
	s_setprio 1
	v_mfma_f32_16x16x32_bf16 v[74:77], v[154:157], v[178:181], v[74:77]
	v_mfma_f32_16x16x32_bf16 v[74:77], v[158:161], v[182:185], v[74:77]
	s_setprio 2
	s_barrier
	v_mfma_f32_16x16x32_bf16 v[66:69], v[154:157], v[186:189], v[66:69]
	v_mfma_f32_16x16x32_bf16 v[66:69], v[158:161], v[190:193], v[66:69]
	s_setprio 0
	s_nop 0
	ds_read_b128 v[162:165], v207 offset:49152
	ds_read_b128 v[166:169], v207 offset:50176
	ds_read_b128 v[170:173], v207 offset:51200
	ds_read_b128 v[174:177], v207 offset:52224
	ds_read_b128 v[178:181], v207 offset:53248
	ds_read_b128 v[182:185], v207 offset:54272
	ds_read_b128 v[186:189], v207 offset:55296
	ds_read_b128 v[190:193], v207 offset:56320
	s_mov_b32 m0, s70
	s_nop 0
	global_load_lds_dwordx4 v195, s[56:57]
	s_add_u32 m0, s70, 0x2000
	s_nop 0
	global_load_lds_dwordx4 v197, s[56:57]
	s_add_u32 s50, s50, 0xc000
	s_addc_u32 s51, s51, 0
	s_mov_b32 m0, s72
	s_nop 0
	global_load_lds_dwordx4 v195, s[50:51]
	s_add_u32 m0, s72, 0x2000
	s_nop 0
	global_load_lds_dwordx4 v197, s[50:51]
	s_nop 0
	s_mov_b32 m0, s71
	s_nop 0
	global_load_lds_dwordx4 v195, s[54:55]
	s_add_u32 m0, s71, 0x2000
	s_nop 0
	global_load_lds_dwordx4 v197, s[54:55]
	s_waitcnt vmcnt(8)
	s_waitcnt lgkmcnt(0)
	s_setprio 1
	s_barrier
	v_mfma_f32_16x16x32_bf16 v[62:65], v[130:133], v[162:165], v[62:65]
	v_mfma_f32_16x16x32_bf16 v[62:65], v[134:137], v[166:169], v[62:65]
	s_waitcnt lgkmcnt(5)
	v_mfma_f32_16x16x32_bf16 v[54:57], v[130:133], v[170:173], v[54:57]
	v_mfma_f32_16x16x32_bf16 v[54:57], v[134:137], v[174:177], v[54:57]
	s_waitcnt lgkmcnt(3)
	s_setprio 0
	s_setprio 1
	v_mfma_f32_16x16x32_bf16 v[46:49], v[130:133], v[178:181], v[46:49]
	v_mfma_f32_16x16x32_bf16 v[46:49], v[134:137], v[182:185], v[46:49]
	s_waitcnt lgkmcnt(1)
	v_mfma_f32_16x16x32_bf16 v[38:41], v[130:133], v[186:189], v[38:41]
	v_mfma_f32_16x16x32_bf16 v[38:41], v[134:137], v[190:193], v[38:41]
	s_setprio 0
	s_setprio 1
	v_mfma_f32_16x16x32_bf16 v[58:61], v[138:141], v[162:165], v[58:61]
	v_mfma_f32_16x16x32_bf16 v[58:61], v[142:145], v[166:169], v[58:61]
	v_mfma_f32_16x16x32_bf16 v[50:53], v[138:141], v[170:173], v[50:53]
	v_mfma_f32_16x16x32_bf16 v[50:53], v[142:145], v[174:177], v[50:53]
	s_setprio 0
	s_setprio 1
	v_mfma_f32_16x16x32_bf16 v[42:45], v[138:141], v[178:181], v[42:45]
	v_mfma_f32_16x16x32_bf16 v[42:45], v[142:145], v[182:185], v[42:45]
	s_waitcnt lgkmcnt(0)
	v_mfma_f32_16x16x32_bf16 v[34:37], v[138:141], v[186:189], v[34:37]
	v_mfma_f32_16x16x32_bf16 v[34:37], v[142:145], v[190:193], v[34:37]
	s_setprio 0
	s_setprio 1
	v_mfma_f32_16x16x32_bf16 v[30:33], v[146:149], v[162:165], v[30:33]
	v_mfma_f32_16x16x32_bf16 v[30:33], v[150:153], v[166:169], v[30:33]
	v_mfma_f32_16x16x32_bf16 v[22:25], v[146:149], v[170:173], v[22:25]
	v_mfma_f32_16x16x32_bf16 v[22:25], v[150:153], v[174:177], v[22:25]
	s_setprio 0
	s_setprio 1
	v_mfma_f32_16x16x32_bf16 v[14:17], v[146:149], v[178:181], v[14:17]
	v_mfma_f32_16x16x32_bf16 v[14:17], v[150:153], v[182:185], v[14:17]
	v_mfma_f32_16x16x32_bf16 v[6:9], v[146:149], v[186:189], v[6:9]
	v_mfma_f32_16x16x32_bf16 v[6:9], v[150:153], v[190:193], v[6:9]
	s_setprio 0
	s_setprio 1
	v_mfma_f32_16x16x32_bf16 v[26:29], v[154:157], v[162:165], v[26:29]
	v_mfma_f32_16x16x32_bf16 v[26:29], v[158:161], v[166:169], v[26:29]
	v_mfma_f32_16x16x32_bf16 v[18:21], v[154:157], v[170:173], v[18:21]
	v_mfma_f32_16x16x32_bf16 v[18:21], v[158:161], v[174:177], v[18:21]
	s_setprio 0
	s_setprio 1
	v_mfma_f32_16x16x32_bf16 v[10:13], v[154:157], v[178:181], v[10:13]
	v_mfma_f32_16x16x32_bf16 v[10:13], v[158:161], v[182:185], v[10:13]
	s_setprio 2
	s_barrier
	v_mfma_f32_16x16x32_bf16 v[2:5], v[154:157], v[186:189], v[2:5]
	v_mfma_f32_16x16x32_bf16 v[2:5], v[158:161], v[190:193], v[2:5]
	s_setprio 0
	s_nop 0
	s_add_i32 s15, s90, 2
	s_cmp_gt_u32 s90, 13
	s_cbranch_scc1 .LBB0_2124
	v_mov_b32_e32 v130, v198
	s_mov_b32 s90, s15
	s_branch .LBB0_2099

.LBB0_2229:
	s_add_i32 s22, s46, 2
	s_lshl_b64 s[42:43], s[22:23], 15
	s_add_u32 s44, s2, s42
	s_addc_u32 s45, s3, s43
	s_and_b64 s[38:39], s[14:15], exec
	s_cselect_b32 s39, s45, s29
	s_cselect_b32 s38, s44, s28
	s_add_u32 s42, s16, s42
	s_waitcnt vmcnt(8)
	s_addc_u32 s43, s17, s43
	s_waitcnt lgkmcnt(0)
	s_and_b64 s[14:15], s[14:15], exec
	s_cselect_b32 s15, s43, s31
	s_cselect_b32 s14, s42, s30
	s_setprio 1
	s_barrier
	v_mfma_f32_16x16x32_bf16 v[126:129], v[146:149], v[186:189], v[126:129]
	v_mfma_f32_16x16x32_bf16 v[126:129], v[150:153], v[190:193], v[126:129]
	s_waitcnt lgkmcnt(5)
	v_mfma_f32_16x16x32_bf16 v[118:121], v[146:149], v[178:181], v[118:121]
	v_mfma_f32_16x16x32_bf16 v[118:121], v[150:153], v[182:185], v[118:121]
	s_waitcnt lgkmcnt(3)
	s_setprio 0
	s_setprio 1
	v_mfma_f32_16x16x32_bf16 v[110:113], v[146:149], v[170:173], v[110:113]
	v_mfma_f32_16x16x32_bf16 v[110:113], v[150:153], v[174:177], v[110:113]
	s_waitcnt lgkmcnt(1)
	v_mfma_f32_16x16x32_bf16 v[102:105], v[146:149], v[162:165], v[102:105]
	v_mfma_f32_16x16x32_bf16 v[102:105], v[150:153], v[166:169], v[102:105]
	s_setprio 0
	s_setprio 1
	v_mfma_f32_16x16x32_bf16 v[122:125], v[154:157], v[186:189], v[122:125]
	v_mfma_f32_16x16x32_bf16 v[122:125], v[158:161], v[190:193], v[122:125]
	v_mfma_f32_16x16x32_bf16 v[114:117], v[154:157], v[178:181], v[114:117]
	v_mfma_f32_16x16x32_bf16 v[114:117], v[158:161], v[182:185], v[114:117]
	s_setprio 0
	s_setprio 1
	v_mfma_f32_16x16x32_bf16 v[106:109], v[154:157], v[170:173], v[106:109]
	v_mfma_f32_16x16x32_bf16 v[106:109], v[158:161], v[174:177], v[106:109]
	s_waitcnt lgkmcnt(0)
	v_mfma_f32_16x16x32_bf16 v[98:101], v[154:157], v[162:165], v[98:101]
	v_mfma_f32_16x16x32_bf16 v[98:101], v[158:161], v[166:169], v[98:101]
	s_setprio 0
	s_setprio 1
	v_mfma_f32_16x16x32_bf16 v[94:97], v[130:133], v[186:189], v[94:97]
	v_mfma_f32_16x16x32_bf16 v[94:97], v[134:137], v[190:193], v[94:97]
	v_mfma_f32_16x16x32_bf16 v[86:89], v[130:133], v[178:181], v[86:89]
	v_mfma_f32_16x16x32_bf16 v[86:89], v[134:137], v[182:185], v[86:89]
	s_setprio 0
	s_setprio 1
	v_mfma_f32_16x16x32_bf16 v[78:81], v[130:133], v[170:173], v[78:81]
	v_mfma_f32_16x16x32_bf16 v[78:81], v[134:137], v[174:177], v[78:81]
	v_mfma_f32_16x16x32_bf16 v[70:73], v[130:133], v[162:165], v[70:73]
	v_mfma_f32_16x16x32_bf16 v[70:73], v[134:137], v[166:169], v[70:73]
	s_setprio 0
	s_setprio 1
	v_mfma_f32_16x16x32_bf16 v[90:93], v[138:141], v[186:189], v[90:93]
	v_mfma_f32_16x16x32_bf16 v[90:93], v[142:145], v[190:193], v[90:93]
	v_mfma_f32_16x16x32_bf16 v[82:85], v[138:141], v[178:181], v[82:85]
	v_mfma_f32_16x16x32_bf16 v[82:85], v[142:145], v[182:185], v[82:85]
	s_setprio 0
	s_setprio 1
	v_mfma_f32_16x16x32_bf16 v[74:77], v[138:141], v[170:173], v[74:77]
	v_mfma_f32_16x16x32_bf16 v[74:77], v[142:145], v[174:177], v[74:77]
	s_setprio 2
	s_barrier
	v_mfma_f32_16x16x32_bf16 v[66:69], v[138:141], v[162:165], v[66:69]
	v_mfma_f32_16x16x32_bf16 v[66:69], v[142:145], v[166:169], v[66:69]
	s_setprio 0
	s_nop 0
	ds_read_b128 v[186:189], v215 offset:16384
	ds_read_b128 v[190:193], v215 offset:17408
	ds_read_b128 v[178:181], v215 offset:18432
	ds_read_b128 v[182:185], v215 offset:19456
	ds_read_b128 v[170:173], v215 offset:20480
	ds_read_b128 v[174:177], v215 offset:21504
	ds_read_b128 v[162:165], v215 offset:22528
	ds_read_b128 v[166:169], v215 offset:23552
	s_mov_b32 m0, s57
	s_nop 0
	global_load_lds_dwordx4 v195, s[14:15]
	s_add_u32 m0, s57, 0x2000
	s_nop 0
	global_load_lds_dwordx4 v208, s[14:15]
	s_add_u32 s42, s14, 0x4000
	s_addc_u32 s43, s15, 0
	s_mov_b32 m0, s58
	s_nop 0
	global_load_lds_dwordx4 v195, s[42:43]
	s_add_u32 m0, s58, 0x2000
	s_nop 0
	global_load_lds_dwordx4 v208, s[42:43]
	s_andn2_b64 vcc, exec, s[40:41]
	s_mov_b32 m0, s56
	s_nop 0
	global_load_lds_dwordx4 v195, s[38:39]
	s_add_u32 m0, s56, 0x2000
	s_nop 0
	global_load_lds_dwordx4 v208, s[38:39]
	s_cbranch_vccnz .LBB0_2231
	v_mov_b32_e32 v2, 0
	v_mov_b32_e32 v3, v2
	v_mov_b32_e32 v4, v2
	v_mov_b32_e32 v5, v2
	v_mov_b32_e32 v6, v2
	v_mov_b32_e32 v7, v2
	v_mov_b32_e32 v8, v2
	v_mov_b32_e32 v9, v2
	v_mov_b32_e32 v10, v2
	v_mov_b32_e32 v11, v2
	v_mov_b32_e32 v12, v2
	v_mov_b32_e32 v13, v2
	v_mov_b32_e32 v14, v2
	v_mov_b32_e32 v15, v2
	v_mov_b32_e32 v16, v2
	v_mov_b32_e32 v17, v2
	v_mov_b32_e32 v18, v2
	v_mov_b32_e32 v19, v2
	v_mov_b32_e32 v20, v2
	v_mov_b32_e32 v21, v2
	v_mov_b32_e32 v22, v2
	v_mov_b32_e32 v23, v2
	v_mov_b32_e32 v24, v2
	v_mov_b32_e32 v25, v2
	v_mov_b32_e32 v26, v2
	v_mov_b32_e32 v27, v2
	v_mov_b32_e32 v28, v2
	v_mov_b32_e32 v29, v2
	v_mov_b32_e32 v30, v2
	v_mov_b32_e32 v31, v2
	v_mov_b32_e32 v32, v2
	v_mov_b32_e32 v33, v2
	v_mov_b32_e32 v34, v2
	v_mov_b32_e32 v35, v2
	v_mov_b32_e32 v36, v2
	v_mov_b32_e32 v37, v2
	v_mov_b32_e32 v38, v2
	v_mov_b32_e32 v39, v2
	v_mov_b32_e32 v40, v2
	v_mov_b32_e32 v41, v2
	v_mov_b32_e32 v42, v2
	v_mov_b32_e32 v43, v2
	v_mov_b32_e32 v44, v2
	v_mov_b32_e32 v45, v2
	v_mov_b32_e32 v46, v2
	v_mov_b32_e32 v47, v2
	v_mov_b32_e32 v48, v2
	v_mov_b32_e32 v49, v2
	v_mov_b32_e32 v50, v2
	v_mov_b32_e32 v51, v2
	v_mov_b32_e32 v52, v2
	v_mov_b32_e32 v53, v2
	v_mov_b32_e32 v54, v2
	v_mov_b32_e32 v55, v2
	v_mov_b32_e32 v56, v2
	v_mov_b32_e32 v57, v2
	v_mov_b32_e32 v58, v2
	v_mov_b32_e32 v59, v2
	v_mov_b32_e32 v60, v2
	v_mov_b32_e32 v61, v2
	v_mov_b32_e32 v62, v2
	v_mov_b32_e32 v63, v2
	v_mov_b32_e32 v64, v2
	v_mov_b32_e32 v65, v2
.LBB0_2231:
	s_waitcnt vmcnt(8)
	s_add_u32 s40, s38, 0x8000
	s_waitcnt lgkmcnt(0)
	s_addc_u32 s41, s39, 0
	s_add_u32 s42, s14, 0x8000
	s_addc_u32 s43, s15, 0
	s_setprio 1
	s_barrier
	v_mfma_f32_16x16x32_bf16 v[62:65], v[146:149], v[186:189], v[62:65]
	v_mfma_f32_16x16x32_bf16 v[62:65], v[150:153], v[190:193], v[62:65]
	s_waitcnt lgkmcnt(5)
	v_mfma_f32_16x16x32_bf16 v[54:57], v[146:149], v[178:181], v[54:57]
	v_mfma_f32_16x16x32_bf16 v[54:57], v[150:153], v[182:185], v[54:57]
	s_waitcnt lgkmcnt(3)
	s_setprio 0
	s_setprio 1
	v_mfma_f32_16x16x32_bf16 v[46:49], v[146:149], v[170:173], v[46:49]
	v_mfma_f32_16x16x32_bf16 v[46:49], v[150:153], v[174:177], v[46:49]
	s_waitcnt lgkmcnt(1)
	v_mfma_f32_16x16x32_bf16 v[38:41], v[146:149], v[162:165], v[38:41]
	v_mfma_f32_16x16x32_bf16 v[38:41], v[150:153], v[166:169], v[38:41]
	s_setprio 0
	s_setprio 1
	v_mfma_f32_16x16x32_bf16 v[58:61], v[154:157], v[186:189], v[58:61]
	v_mfma_f32_16x16x32_bf16 v[58:61], v[158:161], v[190:193], v[58:61]
	v_mfma_f32_16x16x32_bf16 v[50:53], v[154:157], v[178:181], v[50:53]
	v_mfma_f32_16x16x32_bf16 v[50:53], v[158:161], v[182:185], v[50:53]
	s_setprio 0
	s_setprio 1
	v_mfma_f32_16x16x32_bf16 v[42:45], v[154:157], v[170:173], v[42:45]
	v_mfma_f32_16x16x32_bf16 v[42:45], v[158:161], v[174:177], v[42:45]
	s_waitcnt lgkmcnt(0)
	v_mfma_f32_16x16x32_bf16 v[34:37], v[154:157], v[162:165], v[34:37]
	v_mfma_f32_16x16x32_bf16 v[34:37], v[158:161], v[166:169], v[34:37]
	s_setprio 0
	s_setprio 1
	v_mfma_f32_16x16x32_bf16 v[30:33], v[130:133], v[186:189], v[30:33]
	v_mfma_f32_16x16x32_bf16 v[30:33], v[134:137], v[190:193], v[30:33]
	v_mfma_f32_16x16x32_bf16 v[22:25], v[130:133], v[178:181], v[22:25]
	v_mfma_f32_16x16x32_bf16 v[22:25], v[134:137], v[182:185], v[22:25]
	s_setprio 0
	s_setprio 1
	v_mfma_f32_16x16x32_bf16 v[14:17], v[130:133], v[170:173], v[14:17]
	v_mfma_f32_16x16x32_bf16 v[14:17], v[134:137], v[174:177], v[14:17]
	v_mfma_f32_16x16x32_bf16 v[6:9], v[130:133], v[162:165], v[6:9]
	v_mfma_f32_16x16x32_bf16 v[6:9], v[134:137], v[166:169], v[6:9]
	s_setprio 0
	s_setprio 1
	v_mfma_f32_16x16x32_bf16 v[26:29], v[138:141], v[186:189], v[26:29]
	v_mfma_f32_16x16x32_bf16 v[26:29], v[142:145], v[190:193], v[26:29]
	v_mfma_f32_16x16x32_bf16 v[18:21], v[138:141], v[178:181], v[18:21]
	v_mfma_f32_16x16x32_bf16 v[18:21], v[142:145], v[182:185], v[18:21]
	s_setprio 0
	s_setprio 1
	v_mfma_f32_16x16x32_bf16 v[10:13], v[138:141], v[170:173], v[10:13]
	v_mfma_f32_16x16x32_bf16 v[10:13], v[142:145], v[174:177], v[10:13]
	s_setprio 2
	s_barrier
	v_mfma_f32_16x16x32_bf16 v[2:5], v[138:141], v[162:165], v[2:5]
	v_mfma_f32_16x16x32_bf16 v[2:5], v[142:145], v[166:169], v[2:5]
	s_setprio 0
	s_nop 0
	v_add_u32_e32 v142, 0x18000, v214
	v_add_u32_e32 v158, 0x1c000, v214
	ds_read_b128 v[130:133], v142
	ds_read_b128 v[134:137], v142 offset:1024
	ds_read_b128 v[138:141], v142 offset:2048
	ds_read_b128 v[142:145], v142 offset:3072
	ds_read_b128 v[146:149], v158
	ds_read_b128 v[150:153], v158 offset:1024
	ds_read_b128 v[154:157], v158 offset:2048
	ds_read_b128 v[158:161], v158 offset:3072
	ds_read_b128 v[162:165], v215 offset:32768
	ds_read_b128 v[166:169], v215 offset:33792
	ds_read_b128 v[170:173], v215 offset:34816
	ds_read_b128 v[174:177], v215 offset:35840
	ds_read_b128 v[178:181], v215 offset:36864
	ds_read_b128 v[182:185], v215 offset:37888
	ds_read_b128 v[186:189], v215 offset:38912
	ds_read_b128 v[190:193], v215 offset:39936
	s_add_u32 s38, s38, 0x4000
	s_addc_u32 s39, s39, 0
	s_mov_b32 m0, s59
	s_nop 0
	global_load_lds_dwordx4 v195, s[38:39]
	s_add_u32 m0, s59, 0x2000
	s_nop 0
	global_load_lds_dwordx4 v208, s[38:39]
	s_waitcnt vmcnt(8)
	s_waitcnt lgkmcnt(0)
	s_setprio 1
	s_barrier
	v_mfma_f32_16x16x32_bf16 v[126:129], v[130:133], v[162:165], v[126:129]
	v_mfma_f32_16x16x32_bf16 v[126:129], v[134:137], v[166:169], v[126:129]
	s_waitcnt lgkmcnt(5)
	v_mfma_f32_16x16x32_bf16 v[118:121], v[130:133], v[170:173], v[118:121]
	v_mfma_f32_16x16x32_bf16 v[118:121], v[134:137], v[174:177], v[118:121]
	s_waitcnt lgkmcnt(3)
	s_setprio 0
	s_setprio 1
	v_mfma_f32_16x16x32_bf16 v[110:113], v[130:133], v[178:181], v[110:113]
	v_mfma_f32_16x16x32_bf16 v[110:113], v[134:137], v[182:185], v[110:113]
	s_waitcnt lgkmcnt(1)
	v_mfma_f32_16x16x32_bf16 v[102:105], v[130:133], v[186:189], v[102:105]
	v_mfma_f32_16x16x32_bf16 v[102:105], v[134:137], v[190:193], v[102:105]
	s_setprio 0
	s_setprio 1
	v_mfma_f32_16x16x32_bf16 v[122:125], v[138:141], v[162:165], v[122:125]
	v_mfma_f32_16x16x32_bf16 v[122:125], v[142:145], v[166:169], v[122:125]
	v_mfma_f32_16x16x32_bf16 v[114:117], v[138:141], v[170:173], v[114:117]
	v_mfma_f32_16x16x32_bf16 v[114:117], v[142:145], v[174:177], v[114:117]
	s_setprio 0
	s_setprio 1
	v_mfma_f32_16x16x32_bf16 v[106:109], v[138:141], v[178:181], v[106:109]
	v_mfma_f32_16x16x32_bf16 v[106:109], v[142:145], v[182:185], v[106:109]
	s_waitcnt lgkmcnt(0)
	v_mfma_f32_16x16x32_bf16 v[98:101], v[138:141], v[186:189], v[98:101]
	v_mfma_f32_16x16x32_bf16 v[98:101], v[142:145], v[190:193], v[98:101]
	s_setprio 0
	s_setprio 1
	v_mfma_f32_16x16x32_bf16 v[94:97], v[146:149], v[162:165], v[94:97]
	v_mfma_f32_16x16x32_bf16 v[94:97], v[150:153], v[166:169], v[94:97]
	v_mfma_f32_16x16x32_bf16 v[86:89], v[146:149], v[170:173], v[86:89]
	v_mfma_f32_16x16x32_bf16 v[86:89], v[150:153], v[174:177], v[86:89]
	s_setprio 0
	s_setprio 1
	v_mfma_f32_16x16x32_bf16 v[78:81], v[146:149], v[178:181], v[78:81]
	v_mfma_f32_16x16x32_bf16 v[78:81], v[150:153], v[182:185], v[78:81]
	v_mfma_f32_16x16x32_bf16 v[70:73], v[146:149], v[186:189], v[70:73]
	v_mfma_f32_16x16x32_bf16 v[70:73], v[150:153], v[190:193], v[70:73]
	s_setprio 0
	s_setprio 1
	v_mfma_f32_16x16x32_bf16 v[90:93], v[154:157], v[162:165], v[90:93]
	v_mfma_f32_16x16x32_bf16 v[90:93], v[158:161], v[166:169], v[90:93]
	v_mfma_f32_16x16x32_bf16 v[82:85], v[154:157], v[170:173], v[82:85]
	v_mfma_f32_16x16x32_bf16 v[82:85], v[158:161], v[174:177], v[82:85]
	s_setprio 0
	s_setprio 1
	v_mfma_f32_16x16x32_bf16 v[74:77], v[154:157], v[178:181], v[74:77]
	v_mfma_f32_16x16x32_bf16 v[74:77], v[158:161], v[182:185], v[74:77]
	s_setprio 2
	s_barrier
	v_mfma_f32_16x16x32_bf16 v[66:69], v[154:157], v[186:189], v[66:69]
	v_mfma_f32_16x16x32_bf16 v[66:69], v[158:161], v[190:193], v[66:69]
	s_setprio 0
	s_nop 0
	ds_read_b128 v[162:165], v215 offset:49152
	ds_read_b128 v[166:169], v215 offset:50176
	ds_read_b128 v[170:173], v215 offset:51200
	ds_read_b128 v[174:177], v215 offset:52224
	ds_read_b128 v[178:181], v215 offset:53248
	ds_read_b128 v[182:185], v215 offset:54272
	ds_read_b128 v[186:189], v215 offset:55296
	ds_read_b128 v[190:193], v215 offset:56320
	s_mov_b32 m0, s63
	s_nop 0
	global_load_lds_dwordx4 v195, s[42:43]
	s_add_u32 m0, s63, 0x2000
	s_nop 0
	global_load_lds_dwordx4 v208, s[42:43]
	s_add_u32 s14, s14, 0xc000
	s_addc_u32 s15, s15, 0
	s_mov_b32 m0, s65
	s_nop 0
	global_load_lds_dwordx4 v195, s[14:15]
	s_add_u32 m0, s65, 0x2000
	s_nop 0
	global_load_lds_dwordx4 v208, s[14:15]
	s_nop 0
	s_mov_b32 m0, s64
	s_nop 0
	global_load_lds_dwordx4 v195, s[40:41]
	s_add_u32 m0, s64, 0x2000
	s_nop 0
	global_load_lds_dwordx4 v208, s[40:41]
	s_waitcnt vmcnt(8)
	s_waitcnt lgkmcnt(0)
	s_setprio 1
	s_barrier
	v_mfma_f32_16x16x32_bf16 v[62:65], v[130:133], v[162:165], v[62:65]
	v_mfma_f32_16x16x32_bf16 v[62:65], v[134:137], v[166:169], v[62:65]
	s_waitcnt lgkmcnt(5)
	v_mfma_f32_16x16x32_bf16 v[54:57], v[130:133], v[170:173], v[54:57]
	v_mfma_f32_16x16x32_bf16 v[54:57], v[134:137], v[174:177], v[54:57]
	s_waitcnt lgkmcnt(3)
	s_setprio 0
	s_setprio 1
	v_mfma_f32_16x16x32_bf16 v[46:49], v[130:133], v[178:181], v[46:49]
	v_mfma_f32_16x16x32_bf16 v[46:49], v[134:137], v[182:185], v[46:49]
	s_waitcnt lgkmcnt(1)
	v_mfma_f32_16x16x32_bf16 v[38:41], v[130:133], v[186:189], v[38:41]
	v_mfma_f32_16x16x32_bf16 v[38:41], v[134:137], v[190:193], v[38:41]
	s_setprio 0
	s_setprio 1
	v_mfma_f32_16x16x32_bf16 v[58:61], v[138:141], v[162:165], v[58:61]
	v_mfma_f32_16x16x32_bf16 v[58:61], v[142:145], v[166:169], v[58:61]
	v_mfma_f32_16x16x32_bf16 v[50:53], v[138:141], v[170:173], v[50:53]
	v_mfma_f32_16x16x32_bf16 v[50:53], v[142:145], v[174:177], v[50:53]
	s_setprio 0
	s_setprio 1
	v_mfma_f32_16x16x32_bf16 v[42:45], v[138:141], v[178:181], v[42:45]
	v_mfma_f32_16x16x32_bf16 v[42:45], v[142:145], v[182:185], v[42:45]
	s_waitcnt lgkmcnt(0)
	v_mfma_f32_16x16x32_bf16 v[34:37], v[138:141], v[186:189], v[34:37]
	v_mfma_f32_16x16x32_bf16 v[34:37], v[142:145], v[190:193], v[34:37]
	s_setprio 0
	s_setprio 1
	v_mfma_f32_16x16x32_bf16 v[30:33], v[146:149], v[162:165], v[30:33]
	v_mfma_f32_16x16x32_bf16 v[30:33], v[150:153], v[166:169], v[30:33]
	v_mfma_f32_16x16x32_bf16 v[22:25], v[146:149], v[170:173], v[22:25]
	v_mfma_f32_16x16x32_bf16 v[22:25], v[150:153], v[174:177], v[22:25]
	s_setprio 0
	s_setprio 1
	v_mfma_f32_16x16x32_bf16 v[14:17], v[146:149], v[178:181], v[14:17]
	v_mfma_f32_16x16x32_bf16 v[14:17], v[150:153], v[182:185], v[14:17]
	v_mfma_f32_16x16x32_bf16 v[6:9], v[146:149], v[186:189], v[6:9]
	v_mfma_f32_16x16x32_bf16 v[6:9], v[150:153], v[190:193], v[6:9]
	s_setprio 0
	s_setprio 1
	v_mfma_f32_16x16x32_bf16 v[26:29], v[154:157], v[162:165], v[26:29]
	v_mfma_f32_16x16x32_bf16 v[26:29], v[158:161], v[166:169], v[26:29]
	v_mfma_f32_16x16x32_bf16 v[18:21], v[154:157], v[170:173], v[18:21]
	v_mfma_f32_16x16x32_bf16 v[18:21], v[158:161], v[174:177], v[18:21]
	s_setprio 0
	s_setprio 1
	v_mfma_f32_16x16x32_bf16 v[10:13], v[154:157], v[178:181], v[10:13]
	v_mfma_f32_16x16x32_bf16 v[10:13], v[158:161], v[182:185], v[10:13]
	s_setprio 2
	s_barrier
	v_mfma_f32_16x16x32_bf16 v[2:5], v[154:157], v[186:189], v[2:5]
	v_mfma_f32_16x16x32_bf16 v[2:5], v[158:161], v[190:193], v[2:5]
	s_setprio 0
	s_nop 0
	s_cmp_gt_u32 s46, 41
	s_cbranch_scc1 .LBB0_2233
	v_mov_b32_e32 v130, v196
	s_mov_b32 s46, s22
	s_branch .LBB0_2208
